# prefetch earlier: LDS-DMA load groups hoisted above the ds_read fragment reads in every GEMM load segment (on top of astat order + unscaled MFMA + handoff edits)
# baseline (speedup 1.0000x reference)
.LBB0_197:
	s_ashr_i32 s47, s46, 31
	s_lshl_b64 s[8:9], s[46:47], 20
	s_add_u32 s48, s22, s8
	s_addc_u32 s49, s23, s9
	s_and_b64 s[8:9], s[2:3], exec
	s_cselect_b32 s47, s49, s73
	s_cselect_b32 s70, s48, s72
	s_ashr_i32 s45, s44, 31
	s_lshl_b64 s[8:9], s[44:45], 20
	s_add_u32 s50, s27, s8
	s_addc_u32 s51, s68, s9
	s_and_b64 s[8:9], s[2:3], exec
	s_cselect_b32 s45, s51, s55
	s_cselect_b32 s71, s50, s54
	s_add_u32 s8, s72, 0x80080
	s_addc_u32 s9, s73, 0
	s_mov_b32 m0, s92
	v_lshl_add_u64 v[216:217], s[8:9], 0, v[164:165]
	global_load_lds_dwordx4 v[216:217], off
	v_lshl_add_u64 v[216:217], s[8:9], 0, v[168:169]
	s_mov_b32 m0, s93
	s_nop 0
	global_load_lds_dwordx4 v[216:217], off
	ds_read_b128 v[18:21], v190
	ds_read_b128 v[22:25], v190 offset:1024
	ds_read_b128 v[26:29], v190 offset:2048
	ds_read_b128 v[30:33], v190 offset:3072
	ds_read_b128 v[2:5], v190 offset:16384
	ds_read_b128 v[6:9], v190 offset:17408
	ds_read_b128 v[10:13], v190 offset:18432
	ds_read_b128 v[14:17], v190 offset:19456
	ds_read_b128 v[180:183], v191
	ds_read_b128 v[184:187], v191 offset:1024
	ds_read_b128 v[192:195], v191 offset:2048
	ds_read_b128 v[196:199], v191 offset:3072
	ds_read_b128 v[200:203], v191 offset:4096
	ds_read_b128 v[204:207], v191 offset:5120
	ds_read_b128 v[208:211], v191 offset:6144
	ds_read_b128 v[212:215], v191 offset:7168
	s_waitcnt vmcnt(8)
	s_waitcnt lgkmcnt(0)
	s_setprio 1
	s_barrier
	v_mfma_f32_16x16x128_f8f6f4 v[158:161], v[18:25], v[180:187], 0
	v_mfma_f32_16x16x128_f8f6f4 v[154:157], v[26:33], v[180:187], 0
	v_mfma_f32_16x16x128_f8f6f4 v[122:125], v[10:17], v[180:187], 0
	v_mfma_f32_16x16x128_f8f6f4 v[126:129], v[2:9], v[180:187], 0
	v_mfma_f32_16x16x128_f8f6f4 v[118:121], v[2:9], v[192:199], 0
	v_mfma_f32_16x16x128_f8f6f4 v[114:117], v[10:17], v[192:199], 0
	v_mfma_f32_16x16x128_f8f6f4 v[146:149], v[26:33], v[192:199], 0
	v_mfma_f32_16x16x128_f8f6f4 v[150:153], v[18:25], v[192:199], 0
	s_setprio 0
	s_setprio 1
	v_mfma_f32_16x16x128_f8f6f4 v[142:145], v[18:25], v[200:207], 0
	v_mfma_f32_16x16x128_f8f6f4 v[138:141], v[26:33], v[200:207], 0
	v_mfma_f32_16x16x128_f8f6f4 v[106:109], v[10:17], v[200:207], 0
	v_mfma_f32_16x16x128_f8f6f4 v[110:113], v[2:9], v[200:207], 0
	v_mfma_f32_16x16x128_f8f6f4 v[102:105], v[2:9], v[208:215], 0
	v_mfma_f32_16x16x128_f8f6f4 v[98:101], v[10:17], v[208:215], 0
	v_mfma_f32_16x16x128_f8f6f4 v[130:133], v[26:33], v[208:215], 0
	v_mfma_f32_16x16x128_f8f6f4 v[134:137], v[18:25], v[208:215], 0
	s_barrier
	s_setprio 0
	v_lshl_add_u64 v[180:181], s[54:55], 0, v[166:167]
	s_mov_b32 m0, s77
	v_lshl_add_u64 v[182:183], v[180:181], 0, s[16:17]
	global_load_lds_dwordx4 v[182:183], off
	v_lshl_add_u64 v[182:183], s[54:55], 0, v[170:171]
	s_add_u32 s8, s54, 0x80100
	v_lshl_add_u64 v[184:185], v[182:183], 0, s[16:17]
	s_mov_b32 m0, s78
	s_addc_u32 s9, s55, 0
	global_load_lds_dwordx4 v[184:185], off
	v_lshl_add_u64 v[184:185], s[8:9], 0, v[166:167]
	s_mov_b32 m0, s79
	s_nop 0
	global_load_lds_dwordx4 v[184:185], off
	v_lshl_add_u64 v[184:185], s[8:9], 0, v[170:171]
	s_mov_b32 m0, s80
	s_nop 0
	global_load_lds_dwordx4 v[184:185], off
	v_lshl_add_u64 v[184:185], s[72:73], 0, v[164:165]
	v_lshl_add_u64 v[186:187], v[184:185], 0, s[16:17]
	s_mov_b32 m0, s53
	s_nop 0
	global_load_lds_dwordx4 v[186:187], off
	v_lshl_add_u64 v[186:187], s[72:73], 0, v[168:169]
	v_lshl_add_u64 v[224:225], v[186:187], 0, s[16:17]
	s_mov_b32 m0, s81
	s_nop 0
	global_load_lds_dwordx4 v[224:225], off
	ds_read_b128 v[192:195], v191 offset:16384
	ds_read_b128 v[196:199], v191 offset:17408
	ds_read_b128 v[200:203], v191 offset:18432
	ds_read_b128 v[204:207], v191 offset:19456
	ds_read_b128 v[208:211], v191 offset:20480
	ds_read_b128 v[212:215], v191 offset:21504
	ds_read_b128 v[216:219], v191 offset:22528
	ds_read_b128 v[220:223], v191 offset:23552
	s_waitcnt vmcnt(8)
	s_waitcnt lgkmcnt(0)
	s_setprio 1
	s_barrier
	v_mfma_f32_16x16x128_f8f6f4 v[94:97], v[18:25], v[192:199], 0
	v_mfma_f32_16x16x128_f8f6f4 v[90:93], v[26:33], v[192:199], 0
	v_mfma_f32_16x16x128_f8f6f4 v[58:61], v[10:17], v[192:199], 0
	v_mfma_f32_16x16x128_f8f6f4 v[62:65], v[2:9], v[192:199], 0
	v_mfma_f32_16x16x128_f8f6f4 v[54:57], v[2:9], v[200:207], 0
	v_mfma_f32_16x16x128_f8f6f4 v[50:53], v[10:17], v[200:207], 0
	v_mfma_f32_16x16x128_f8f6f4 v[82:85], v[26:33], v[200:207], 0
	v_mfma_f32_16x16x128_f8f6f4 v[86:89], v[18:25], v[200:207], 0
	s_setprio 0
	s_setprio 1
	v_mfma_f32_16x16x128_f8f6f4 v[78:81], v[18:25], v[208:215], 0
	v_mfma_f32_16x16x128_f8f6f4 v[74:77], v[26:33], v[208:215], 0
	v_mfma_f32_16x16x128_f8f6f4 v[42:45], v[10:17], v[208:215], 0
	v_mfma_f32_16x16x128_f8f6f4 v[46:49], v[2:9], v[208:215], 0
	v_mfma_f32_16x16x128_f8f6f4 v[38:41], v[2:9], v[216:223], 0
	v_mfma_f32_16x16x128_f8f6f4 v[34:37], v[10:17], v[216:223], 0
	v_mfma_f32_16x16x128_f8f6f4 v[66:69], v[26:33], v[216:223], 0
	v_mfma_f32_16x16x128_f8f6f4 v[70:73], v[18:25], v[216:223], 0
	s_barrier
	s_setprio 0
	s_add_u32 s8, s72, 0x80100
	s_addc_u32 s9, s73, 0
	s_mov_b32 m0, s82
	v_lshl_add_u64 v[224:225], s[8:9], 0, v[164:165]
	global_load_lds_dwordx4 v[224:225], off
	v_lshl_add_u64 v[224:225], s[8:9], 0, v[168:169]
	s_mov_b32 m0, s83
	s_nop 0
	global_load_lds_dwordx4 v[224:225], off
	ds_read_b128 v[18:21], v190 offset:32768
	ds_read_b128 v[22:25], v190 offset:33792
	ds_read_b128 v[26:29], v190 offset:34816
	ds_read_b128 v[30:33], v190 offset:35840
	ds_read_b128 v[2:5], v190 offset:49152
	ds_read_b128 v[6:9], v190 offset:50176
	ds_read_b128 v[10:13], v190 offset:51200
	ds_read_b128 v[14:17], v190 offset:52224
	ds_read_b128 v[192:195], v191 offset:32768
	ds_read_b128 v[196:199], v191 offset:33792
	ds_read_b128 v[200:203], v191 offset:34816
	ds_read_b128 v[204:207], v191 offset:35840
	ds_read_b128 v[208:211], v191 offset:36864
	ds_read_b128 v[212:215], v191 offset:37888
	ds_read_b128 v[216:219], v191 offset:38912
	ds_read_b128 v[220:223], v191 offset:39936
	s_waitcnt vmcnt(8)
	s_waitcnt lgkmcnt(0)
	s_setprio 1
	s_barrier
	v_mfma_f32_16x16x128_f8f6f4 v[158:161], v[18:25], v[192:199], v[158:161]
	v_mfma_f32_16x16x128_f8f6f4 v[154:157], v[26:33], v[192:199], v[154:157]
	v_mfma_f32_16x16x128_f8f6f4 v[122:125], v[10:17], v[192:199], v[122:125]
	v_mfma_f32_16x16x128_f8f6f4 v[126:129], v[2:9], v[192:199], v[126:129]
	v_mfma_f32_16x16x128_f8f6f4 v[118:121], v[2:9], v[200:207], v[118:121]
	v_mfma_f32_16x16x128_f8f6f4 v[114:117], v[10:17], v[200:207], v[114:117]
	v_mfma_f32_16x16x128_f8f6f4 v[146:149], v[26:33], v[200:207], v[146:149]
	v_mfma_f32_16x16x128_f8f6f4 v[150:153], v[18:25], v[200:207], v[150:153]
	s_setprio 0
	s_setprio 1
	v_mfma_f32_16x16x128_f8f6f4 v[142:145], v[18:25], v[208:215], v[142:145]
	v_mfma_f32_16x16x128_f8f6f4 v[138:141], v[26:33], v[208:215], v[138:141]
	v_mfma_f32_16x16x128_f8f6f4 v[106:109], v[10:17], v[208:215], v[106:109]
	v_mfma_f32_16x16x128_f8f6f4 v[110:113], v[2:9], v[208:215], v[110:113]
	v_mfma_f32_16x16x128_f8f6f4 v[102:105], v[2:9], v[216:223], v[102:105]
	v_mfma_f32_16x16x128_f8f6f4 v[98:101], v[10:17], v[216:223], v[98:101]
	v_mfma_f32_16x16x128_f8f6f4 v[130:133], v[26:33], v[216:223], v[130:133]
	v_mfma_f32_16x16x128_f8f6f4 v[134:137], v[18:25], v[216:223], v[134:137]
	s_barrier
	s_setprio 0
	s_mov_b32 m0, s86
	v_lshl_add_u64 v[180:181], v[180:181], 0, s[20:21]
	s_add_u32 s8, s54, 0x80180
	global_load_lds_dwordx4 v[180:181], off
	v_lshl_add_u64 v[180:181], v[182:183], 0, s[20:21]
	s_mov_b32 m0, s87
	s_addc_u32 s9, s55, 0
	global_load_lds_dwordx4 v[180:181], off
	v_lshl_add_u64 v[180:181], s[8:9], 0, v[166:167]
	s_mov_b32 m0, s90
	s_nop 0
	global_load_lds_dwordx4 v[180:181], off
	v_lshl_add_u64 v[180:181], s[8:9], 0, v[170:171]
	s_mov_b32 m0, s91
	s_nop 0
	global_load_lds_dwordx4 v[180:181], off
	v_lshl_add_u64 v[180:181], v[184:185], 0, s[20:21]
	s_mov_b32 m0, s88
	s_nop 0
	global_load_lds_dwordx4 v[180:181], off
	v_lshl_add_u64 v[180:181], v[186:187], 0, s[20:21]
	s_mov_b32 m0, s89
	s_nop 0
	global_load_lds_dwordx4 v[180:181], off
	ds_read_b128 v[192:195], v191 offset:49152
	ds_read_b128 v[196:199], v191 offset:50176
	ds_read_b128 v[200:203], v191 offset:51200
	ds_read_b128 v[204:207], v191 offset:52224
	ds_read_b128 v[208:211], v191 offset:53248
	ds_read_b128 v[212:215], v191 offset:54272
	ds_read_b128 v[216:219], v191 offset:55296
	ds_read_b128 v[220:223], v191 offset:56320
	s_waitcnt vmcnt(8)
	s_waitcnt lgkmcnt(0)
	s_setprio 1
	s_barrier
	v_mfma_f32_16x16x128_f8f6f4 v[94:97], v[18:25], v[192:199], v[94:97]
	v_mfma_f32_16x16x128_f8f6f4 v[90:93], v[26:33], v[192:199], v[90:93]
	v_mfma_f32_16x16x128_f8f6f4 v[58:61], v[10:17], v[192:199], v[58:61]
	v_mfma_f32_16x16x128_f8f6f4 v[62:65], v[2:9], v[192:199], v[62:65]
	v_mfma_f32_16x16x128_f8f6f4 v[54:57], v[2:9], v[200:207], v[54:57]
	v_mfma_f32_16x16x128_f8f6f4 v[50:53], v[10:17], v[200:207], v[50:53]
	v_mfma_f32_16x16x128_f8f6f4 v[82:85], v[26:33], v[200:207], v[82:85]
	v_mfma_f32_16x16x128_f8f6f4 v[86:89], v[18:25], v[200:207], v[86:89]
	s_setprio 0
	s_setprio 1
	v_mfma_f32_16x16x128_f8f6f4 v[78:81], v[18:25], v[208:215], v[78:81]
	v_mfma_f32_16x16x128_f8f6f4 v[74:77], v[26:33], v[208:215], v[74:77]
	v_mfma_f32_16x16x128_f8f6f4 v[42:45], v[10:17], v[208:215], v[42:45]
	v_mfma_f32_16x16x128_f8f6f4 v[46:49], v[2:9], v[208:215], v[46:49]
	v_mfma_f32_16x16x128_f8f6f4 v[38:41], v[2:9], v[216:223], v[38:41]
	v_mfma_f32_16x16x128_f8f6f4 v[34:37], v[10:17], v[216:223], v[34:37]
	v_mfma_f32_16x16x128_f8f6f4 v[66:69], v[26:33], v[216:223], v[66:69]
	v_mfma_f32_16x16x128_f8f6f4 v[70:73], v[18:25], v[216:223], v[70:73]
	s_barrier
	s_setprio 0
	s_add_u32 s72, s72, 0x80180
	s_addc_u32 s73, s73, 0
	s_add_u32 s8, s54, 0x200
	s_addc_u32 s9, s55, 0
	s_mov_b32 s62, 0
.LBB0_198:
	s_add_u32 s54, s72, 0xfff80080
	s_addc_u32 s55, s73, -1
	s_cmp_eq_u32 s62, 28
	s_cselect_b32 s75, s47, s55
	s_cselect_b32 s74, s70, s54
	s_cselect_b32 s55, s45, s9
	s_cselect_b32 s54, s71, s8
	s_mov_b32 m0, s92
	v_lshl_add_u64 v[216:217], s[72:73], 0, v[172:173]
	global_load_lds_dwordx4 v[216:217], off
	v_lshl_add_u64 v[216:217], s[72:73], 0, v[174:175]
	s_mov_b32 m0, s93
	s_nop 0
	global_load_lds_dwordx4 v[216:217], off
	ds_read_b128 v[2:5], v190
	ds_read_b128 v[6:9], v190 offset:1024
	ds_read_b128 v[18:21], v190 offset:2048
	ds_read_b128 v[22:25], v190 offset:3072
	ds_read_b128 v[26:29], v190 offset:16384
	ds_read_b128 v[30:33], v190 offset:17408
	ds_read_b128 v[180:183], v190 offset:18432
	ds_read_b128 v[184:187], v190 offset:19456
	ds_read_b128 v[10:13], v191
	ds_read_b128 v[14:17], v191 offset:1024
	ds_read_b128 v[192:195], v191 offset:2048
	ds_read_b128 v[196:199], v191 offset:3072
	ds_read_b128 v[200:203], v191 offset:4096
	ds_read_b128 v[204:207], v191 offset:5120
	ds_read_b128 v[208:211], v191 offset:6144
	ds_read_b128 v[212:215], v191 offset:7168
	s_waitcnt vmcnt(8)
	s_waitcnt lgkmcnt(0)
	s_setprio 1
	s_barrier
	v_mfma_f32_16x16x128_f8f6f4 v[158:161], v[2:9], v[10:17], v[158:161]
	v_mfma_f32_16x16x128_f8f6f4 v[154:157], v[18:25], v[10:17], v[154:157]
	v_mfma_f32_16x16x128_f8f6f4 v[122:125], v[180:187], v[10:17], v[122:125]
	v_mfma_f32_16x16x128_f8f6f4 v[126:129], v[26:33], v[10:17], v[126:129]
	v_mfma_f32_16x16x128_f8f6f4 v[118:121], v[26:33], v[192:199], v[118:121]
	v_mfma_f32_16x16x128_f8f6f4 v[114:117], v[180:187], v[192:199], v[114:117]
	v_mfma_f32_16x16x128_f8f6f4 v[146:149], v[18:25], v[192:199], v[146:149]
	v_mfma_f32_16x16x128_f8f6f4 v[150:153], v[2:9], v[192:199], v[150:153]
	s_setprio 0
	s_setprio 1
	v_mfma_f32_16x16x128_f8f6f4 v[142:145], v[2:9], v[200:207], v[142:145]
	v_mfma_f32_16x16x128_f8f6f4 v[138:141], v[18:25], v[200:207], v[138:141]
	v_mfma_f32_16x16x128_f8f6f4 v[106:109], v[180:187], v[200:207], v[106:109]
	v_mfma_f32_16x16x128_f8f6f4 v[110:113], v[26:33], v[200:207], v[110:113]
	v_mfma_f32_16x16x128_f8f6f4 v[102:105], v[26:33], v[208:215], v[102:105]
	v_mfma_f32_16x16x128_f8f6f4 v[98:101], v[180:187], v[208:215], v[98:101]
	v_mfma_f32_16x16x128_f8f6f4 v[130:133], v[18:25], v[208:215], v[130:133]
	v_mfma_f32_16x16x128_f8f6f4 v[134:137], v[2:9], v[208:215], v[134:137]
	s_barrier
	s_setprio 0
	s_mov_b32 m0, s77
	v_lshl_add_u64 v[10:11], s[54:55], 0, v[166:167]
	s_add_u32 vcc_lo, s54, 0x80000
	global_load_lds_dwordx4 v[10:11], off
	v_lshl_add_u64 v[12:13], s[54:55], 0, v[170:171]
	s_mov_b32 m0, s78
	s_addc_u32 vcc_hi, s55, 0
	global_load_lds_dwordx4 v[12:13], off
	v_lshl_add_u64 v[14:15], vcc, 0, v[166:167]
	s_mov_b32 m0, s79
	v_lshl_add_u64 v[16:17], s[74:75], 0, v[168:169]
	global_load_lds_dwordx4 v[14:15], off
	v_lshl_add_u64 v[14:15], vcc, 0, v[170:171]
	s_mov_b32 m0, s80
	s_nop 0
	global_load_lds_dwordx4 v[14:15], off
	v_lshl_add_u64 v[14:15], s[74:75], 0, v[164:165]
	s_mov_b32 m0, s53
	s_nop 0
	global_load_lds_dwordx4 v[14:15], off
	s_mov_b32 m0, s81
	s_nop 0
	global_load_lds_dwordx4 v[16:17], off
	ds_read_b128 v[192:195], v191 offset:16384
	ds_read_b128 v[196:199], v191 offset:17408
	ds_read_b128 v[200:203], v191 offset:18432
	ds_read_b128 v[204:207], v191 offset:19456
	ds_read_b128 v[208:211], v191 offset:20480
	ds_read_b128 v[212:215], v191 offset:21504
	ds_read_b128 v[216:219], v191 offset:22528
	ds_read_b128 v[220:223], v191 offset:23552
	s_waitcnt vmcnt(8)
	s_waitcnt lgkmcnt(0)
	s_setprio 1
	s_barrier
	v_mfma_f32_16x16x128_f8f6f4 v[94:97], v[2:9], v[192:199], v[94:97]
	v_mfma_f32_16x16x128_f8f6f4 v[90:93], v[18:25], v[192:199], v[90:93]
	v_mfma_f32_16x16x128_f8f6f4 v[58:61], v[180:187], v[192:199], v[58:61]
	v_mfma_f32_16x16x128_f8f6f4 v[62:65], v[26:33], v[192:199], v[62:65]
	v_mfma_f32_16x16x128_f8f6f4 v[54:57], v[26:33], v[200:207], v[54:57]
	v_mfma_f32_16x16x128_f8f6f4 v[50:53], v[180:187], v[200:207], v[50:53]
	v_mfma_f32_16x16x128_f8f6f4 v[82:85], v[18:25], v[200:207], v[82:85]
	v_mfma_f32_16x16x128_f8f6f4 v[86:89], v[2:9], v[200:207], v[86:89]
	s_setprio 0
	s_setprio 1
	v_mfma_f32_16x16x128_f8f6f4 v[78:81], v[2:9], v[208:215], v[78:81]
	v_mfma_f32_16x16x128_f8f6f4 v[74:77], v[18:25], v[208:215], v[74:77]
	v_mfma_f32_16x16x128_f8f6f4 v[42:45], v[180:187], v[208:215], v[42:45]
	v_mfma_f32_16x16x128_f8f6f4 v[46:49], v[26:33], v[208:215], v[46:49]
	v_mfma_f32_16x16x128_f8f6f4 v[38:41], v[26:33], v[216:223], v[38:41]
	v_mfma_f32_16x16x128_f8f6f4 v[34:37], v[180:187], v[216:223], v[34:37]
	v_mfma_f32_16x16x128_f8f6f4 v[66:69], v[18:25], v[216:223], v[66:69]
	v_mfma_f32_16x16x128_f8f6f4 v[70:73], v[2:9], v[216:223], v[70:73]
	s_barrier
	s_setprio 0
	s_add_u32 s74, s74, 0x80000
	s_addc_u32 s75, s75, 0
	s_mov_b32 m0, s82
	v_lshl_add_u64 v[224:225], s[74:75], 0, v[164:165]
	global_load_lds_dwordx4 v[224:225], off
	v_lshl_add_u64 v[224:225], s[74:75], 0, v[168:169]
	s_mov_b32 m0, s83
	s_nop 0
	global_load_lds_dwordx4 v[224:225], off
	ds_read_b128 v[18:21], v190 offset:32768
	ds_read_b128 v[22:25], v190 offset:33792
	ds_read_b128 v[26:29], v190 offset:34816
	ds_read_b128 v[30:33], v190 offset:35840
	ds_read_b128 v[2:5], v190 offset:49152
	ds_read_b128 v[6:9], v190 offset:50176
	ds_read_b128 v[180:183], v190 offset:51200
	ds_read_b128 v[184:187], v190 offset:52224
	ds_read_b128 v[192:195], v191 offset:32768
	ds_read_b128 v[196:199], v191 offset:33792
	ds_read_b128 v[200:203], v191 offset:34816
	ds_read_b128 v[204:207], v191 offset:35840
	ds_read_b128 v[208:211], v191 offset:36864
	ds_read_b128 v[212:215], v191 offset:37888
	ds_read_b128 v[216:219], v191 offset:38912
	ds_read_b128 v[220:223], v191 offset:39936
	s_waitcnt vmcnt(8)
	s_waitcnt lgkmcnt(0)
	s_setprio 1
	s_barrier
	v_mfma_f32_16x16x128_f8f6f4 v[158:161], v[18:25], v[192:199], v[158:161]
	v_mfma_f32_16x16x128_f8f6f4 v[154:157], v[26:33], v[192:199], v[154:157]
	v_mfma_f32_16x16x128_f8f6f4 v[122:125], v[180:187], v[192:199], v[122:125]
	v_mfma_f32_16x16x128_f8f6f4 v[126:129], v[2:9], v[192:199], v[126:129]
	v_mfma_f32_16x16x128_f8f6f4 v[118:121], v[2:9], v[200:207], v[118:121]
	v_mfma_f32_16x16x128_f8f6f4 v[114:117], v[180:187], v[200:207], v[114:117]
	v_mfma_f32_16x16x128_f8f6f4 v[146:149], v[26:33], v[200:207], v[146:149]
	v_mfma_f32_16x16x128_f8f6f4 v[150:153], v[18:25], v[200:207], v[150:153]
	s_setprio 0
	s_setprio 1
	v_mfma_f32_16x16x128_f8f6f4 v[142:145], v[18:25], v[208:215], v[142:145]
	v_mfma_f32_16x16x128_f8f6f4 v[138:141], v[26:33], v[208:215], v[138:141]
	v_mfma_f32_16x16x128_f8f6f4 v[106:109], v[180:187], v[208:215], v[106:109]
	v_mfma_f32_16x16x128_f8f6f4 v[110:113], v[2:9], v[208:215], v[110:113]
	v_mfma_f32_16x16x128_f8f6f4 v[102:105], v[2:9], v[216:223], v[102:105]
	v_mfma_f32_16x16x128_f8f6f4 v[98:101], v[180:187], v[216:223], v[98:101]
	v_mfma_f32_16x16x128_f8f6f4 v[130:133], v[26:33], v[216:223], v[130:133]
	v_mfma_f32_16x16x128_f8f6f4 v[134:137], v[18:25], v[216:223], v[134:137]
	s_barrier
	s_setprio 0
	s_mov_b32 m0, s86
	v_lshl_add_u64 v[10:11], v[10:11], 0, s[4:5]
	s_add_u32 s54, s54, 0x80080
	global_load_lds_dwordx4 v[10:11], off
	v_lshl_add_u64 v[10:11], v[12:13], 0, s[4:5]
	s_mov_b32 m0, s87
	s_addc_u32 s55, s55, 0
	global_load_lds_dwordx4 v[10:11], off
	v_lshl_add_u64 v[10:11], s[54:55], 0, v[166:167]
	s_mov_b32 m0, s90
	s_nop 0
	global_load_lds_dwordx4 v[10:11], off
	v_lshl_add_u64 v[10:11], s[54:55], 0, v[170:171]
	s_mov_b32 m0, s91
	s_nop 0
	global_load_lds_dwordx4 v[10:11], off
	v_lshl_add_u64 v[10:11], v[14:15], 0, s[4:5]
	s_mov_b32 m0, s88
	s_nop 0
	global_load_lds_dwordx4 v[10:11], off
	v_lshl_add_u64 v[10:11], v[16:17], 0, s[4:5]
	s_mov_b32 m0, s89
	s_nop 0
	global_load_lds_dwordx4 v[10:11], off
	ds_read_b128 v[192:195], v191 offset:49152
	ds_read_b128 v[196:199], v191 offset:50176
	ds_read_b128 v[200:203], v191 offset:51200
	ds_read_b128 v[204:207], v191 offset:52224
	ds_read_b128 v[208:211], v191 offset:53248
	ds_read_b128 v[212:215], v191 offset:54272
	ds_read_b128 v[216:219], v191 offset:55296
	ds_read_b128 v[220:223], v191 offset:56320
	s_waitcnt vmcnt(8)
	s_waitcnt lgkmcnt(0)
	s_setprio 1
	s_barrier
	v_mfma_f32_16x16x128_f8f6f4 v[94:97], v[18:25], v[192:199], v[94:97]
	v_mfma_f32_16x16x128_f8f6f4 v[90:93], v[26:33], v[192:199], v[90:93]
	v_mfma_f32_16x16x128_f8f6f4 v[58:61], v[180:187], v[192:199], v[58:61]
	v_mfma_f32_16x16x128_f8f6f4 v[62:65], v[2:9], v[192:199], v[62:65]
	v_mfma_f32_16x16x128_f8f6f4 v[54:57], v[2:9], v[200:207], v[54:57]
	v_mfma_f32_16x16x128_f8f6f4 v[50:53], v[180:187], v[200:207], v[50:53]
	v_mfma_f32_16x16x128_f8f6f4 v[82:85], v[26:33], v[200:207], v[82:85]
	v_mfma_f32_16x16x128_f8f6f4 v[86:89], v[18:25], v[200:207], v[86:89]
	s_setprio 0
	s_setprio 1
	v_mfma_f32_16x16x128_f8f6f4 v[78:81], v[18:25], v[208:215], v[78:81]
	v_mfma_f32_16x16x128_f8f6f4 v[74:77], v[26:33], v[208:215], v[74:77]
	v_mfma_f32_16x16x128_f8f6f4 v[42:45], v[180:187], v[208:215], v[42:45]
	v_mfma_f32_16x16x128_f8f6f4 v[46:49], v[2:9], v[208:215], v[46:49]
	v_mfma_f32_16x16x128_f8f6f4 v[38:41], v[2:9], v[216:223], v[38:41]
	v_mfma_f32_16x16x128_f8f6f4 v[34:37], v[180:187], v[216:223], v[34:37]
	v_mfma_f32_16x16x128_f8f6f4 v[66:69], v[26:33], v[216:223], v[66:69]
	v_mfma_f32_16x16x128_f8f6f4 v[70:73], v[18:25], v[216:223], v[70:73]
	s_barrier
	s_setprio 0
	s_add_i32 s62, s62, 2
	s_add_u32 s72, s72, 0x100
	s_addc_u32 s73, s73, 0
	s_add_u32 s8, s8, 0x100
	s_addc_u32 s9, s9, 0
	s_cmp_gt_u32 s62, 29
	s_cbranch_scc0 .LBB0_198
	s_and_b64 vcc, exec, s[6:7]
	s_cbranch_vccz .LBB0_201
	s_barrier

.LBB0_282:
	s_add_u32 s49, s52, 0x100
	s_addc_u32 s71, s53, 0
	s_and_b64 s[62:63], s[54:55], exec
	s_cselect_b32 s73, s1, s71
	s_cselect_b32 s72, s0, s49
	s_add_u32 s49, s50, 0x100
	s_addc_u32 s62, s51, 0
	s_and_b64 s[54:55], s[54:55], exec
	s_cselect_b32 s55, s5, s62
	s_cselect_b32 s54, s4, s49
	s_add_u32 s62, s52, 0x158080
	s_addc_u32 s63, s53, 0
	s_add_i32 s49, s33, 0xc000
	v_lshl_add_u64 v[182:183], s[62:63], 0, v[154:155]
	s_mov_b32 m0, s49
	s_add_i32 s71, s33, 0xe000
	global_load_lds_dwordx4 v[182:183], off
	v_lshl_add_u64 v[182:183], s[62:63], 0, v[158:159]
	s_mov_b32 m0, s71
	s_nop 0
	global_load_lds_dwordx4 v[182:183], off
	ds_read_b128 v[2:5], v187
	ds_read_b128 v[6:9], v187 offset:1024
	ds_read_b128 v[174:177], v187 offset:2048
	ds_read_b128 v[178:181], v187 offset:3072
	ds_read_b128 v[190:193], v187 offset:16384
	ds_read_b128 v[194:197], v187 offset:17408
	ds_read_b128 v[198:201], v187 offset:18432
	ds_read_b128 v[202:205], v187 offset:19456
	ds_read_b128 v[206:209], v188
	ds_read_b128 v[210:213], v188 offset:1024
	ds_read_b128 v[214:217], v188 offset:2048
	ds_read_b128 v[218:221], v188 offset:3072
	ds_read_b128 v[222:225], v188 offset:4096
	ds_read_b128 v[226:229], v188 offset:5120
	ds_read_b128 v[230:233], v188 offset:6144
	ds_read_b128 v[234:237], v188 offset:7168
	s_waitcnt vmcnt(8)
	s_waitcnt lgkmcnt(0)
	s_setprio 1
	s_barrier
	v_mfma_f32_16x16x128_f8f6f4 v[134:137], v[2:9], v[206:213], 0
	v_mfma_f32_16x16x128_f8f6f4 v[130:133], v[174:181], v[206:213], 0
	v_mfma_f32_16x16x128_f8f6f4 v[98:101], v[198:205], v[206:213], 0
	v_mfma_f32_16x16x128_f8f6f4 v[102:105], v[190:197], v[206:213], 0
	v_mfma_f32_16x16x128_f8f6f4 v[94:97], v[190:197], v[214:221], 0
	v_mfma_f32_16x16x128_f8f6f4 v[90:93], v[198:205], v[214:221], 0
	v_mfma_f32_16x16x128_f8f6f4 v[122:125], v[174:181], v[214:221], 0
	v_mfma_f32_16x16x128_f8f6f4 v[126:129], v[2:9], v[214:221], 0
	s_setprio 0
	s_setprio 1
	v_mfma_f32_16x16x128_f8f6f4 v[118:121], v[2:9], v[222:229], 0
	v_mfma_f32_16x16x128_f8f6f4 v[114:117], v[174:181], v[222:229], 0
	v_mfma_f32_16x16x128_f8f6f4 v[82:85], v[198:205], v[222:229], 0
	v_mfma_f32_16x16x128_f8f6f4 v[86:89], v[190:197], v[222:229], 0
	v_mfma_f32_16x16x128_f8f6f4 v[78:81], v[190:197], v[230:237], 0
	v_mfma_f32_16x16x128_f8f6f4 v[74:77], v[198:205], v[230:237], 0
	v_mfma_f32_16x16x128_f8f6f4 v[106:109], v[174:181], v[230:237], 0
	v_mfma_f32_16x16x128_f8f6f4 v[110:113], v[2:9], v[230:237], 0
	s_barrier
	s_setprio 0
	s_mov_b32 m0, s47
	v_lshl_add_u64 v[182:183], s[54:55], 0, v[156:157]
	s_add_u32 s62, s54, 0x158000
	global_load_lds_dwordx4 v[182:183], off
	v_lshl_add_u64 v[238:239], s[54:55], 0, v[160:161]
	s_mov_b32 m0, s68
	s_addc_u32 s63, s55, 0
	global_load_lds_dwordx4 v[238:239], off
	v_lshl_add_u64 v[242:243], s[62:63], 0, v[156:157]
	s_mov_b32 m0, s69
	v_lshl_add_u64 v[244:245], s[72:73], 0, v[158:159]
	global_load_lds_dwordx4 v[242:243], off
	v_lshl_add_u64 v[242:243], s[62:63], 0, v[160:161]
	s_mov_b32 m0, s74
	s_nop 0
	global_load_lds_dwordx4 v[242:243], off
	v_lshl_add_u64 v[242:243], s[72:73], 0, v[154:155]
	s_mov_b32 m0, s33
	s_nop 0
	global_load_lds_dwordx4 v[242:243], off
	s_mov_b32 m0, s75
	s_nop 0
	global_load_lds_dwordx4 v[244:245], off
	ds_read_b128 v[206:209], v188 offset:16384
	ds_read_b128 v[210:213], v188 offset:17408
	ds_read_b128 v[214:217], v188 offset:18432
	ds_read_b128 v[218:221], v188 offset:19456
	ds_read_b128 v[222:225], v188 offset:20480
	ds_read_b128 v[226:229], v188 offset:21504
	ds_read_b128 v[230:233], v188 offset:22528
	ds_read_b128 v[234:237], v188 offset:23552
	s_waitcnt vmcnt(8)
	s_waitcnt lgkmcnt(0)
	s_setprio 1
	s_barrier
	v_mfma_f32_16x16x128_f8f6f4 v[70:73], v[2:9], v[206:213], 0
	v_mfma_f32_16x16x128_f8f6f4 v[66:69], v[174:181], v[206:213], 0
	v_mfma_f32_16x16x128_f8f6f4 v[34:37], v[198:205], v[206:213], 0
	v_mfma_f32_16x16x128_f8f6f4 v[38:41], v[190:197], v[206:213], 0
	v_mfma_f32_16x16x128_f8f6f4 v[30:33], v[190:197], v[214:221], 0
	v_mfma_f32_16x16x128_f8f6f4 v[26:29], v[198:205], v[214:221], 0
	v_mfma_f32_16x16x128_f8f6f4 v[58:61], v[174:181], v[214:221], 0
	v_mfma_f32_16x16x128_f8f6f4 v[62:65], v[2:9], v[214:221], 0
	s_setprio 0
	s_setprio 1
	v_mfma_f32_16x16x128_f8f6f4 v[54:57], v[2:9], v[222:229], 0
	v_mfma_f32_16x16x128_f8f6f4 v[50:53], v[174:181], v[222:229], 0
	v_mfma_f32_16x16x128_f8f6f4 v[18:21], v[198:205], v[222:229], 0
	v_mfma_f32_16x16x128_f8f6f4 v[22:25], v[190:197], v[222:229], 0
	v_mfma_f32_16x16x128_f8f6f4 v[14:17], v[190:197], v[230:237], 0
	v_mfma_f32_16x16x128_f8f6f4 v[10:13], v[198:205], v[230:237], 0
	v_mfma_f32_16x16x128_f8f6f4 v[42:45], v[174:181], v[230:237], 0
	v_mfma_f32_16x16x128_f8f6f4 v[46:49], v[2:9], v[230:237], 0
	s_barrier
	s_setprio 0
	s_add_u32 s62, s72, 0x158000
	s_addc_u32 s63, s73, 0
	s_mov_b32 m0, s76
	v_lshl_add_u64 v[246:247], s[62:63], 0, v[154:155]
	global_load_lds_dwordx4 v[246:247], off
	v_lshl_add_u64 v[246:247], s[62:63], 0, v[158:159]
	s_mov_b32 m0, s77
	s_nop 0
	global_load_lds_dwordx4 v[246:247], off
	ds_read_b128 v[2:5], v187 offset:32768
	ds_read_b128 v[6:9], v187 offset:33792
	ds_read_b128 v[174:177], v187 offset:34816
	ds_read_b128 v[178:181], v187 offset:35840
	ds_read_b128 v[190:193], v187 offset:49152
	ds_read_b128 v[194:197], v187 offset:50176
	ds_read_b128 v[198:201], v187 offset:51200
	ds_read_b128 v[202:205], v187 offset:52224
	ds_read_b128 v[206:209], v188 offset:32768
	ds_read_b128 v[210:213], v188 offset:33792
	ds_read_b128 v[214:217], v188 offset:34816
	ds_read_b128 v[218:221], v188 offset:35840
	ds_read_b128 v[222:225], v188 offset:36864
	ds_read_b128 v[226:229], v188 offset:37888
	ds_read_b128 v[230:233], v188 offset:38912
	ds_read_b128 v[234:237], v188 offset:39936
	s_waitcnt vmcnt(8)
	s_waitcnt lgkmcnt(0)
	s_setprio 1
	s_barrier
	v_mfma_f32_16x16x128_f8f6f4 v[134:137], v[2:9], v[206:213], v[134:137]
	v_mfma_f32_16x16x128_f8f6f4 v[130:133], v[174:181], v[206:213], v[130:133]
	v_mfma_f32_16x16x128_f8f6f4 v[98:101], v[198:205], v[206:213], v[98:101]
	v_mfma_f32_16x16x128_f8f6f4 v[102:105], v[190:197], v[206:213], v[102:105]
	v_mfma_f32_16x16x128_f8f6f4 v[94:97], v[190:197], v[214:221], v[94:97]
	v_mfma_f32_16x16x128_f8f6f4 v[90:93], v[198:205], v[214:221], v[90:93]
	v_mfma_f32_16x16x128_f8f6f4 v[122:125], v[174:181], v[214:221], v[122:125]
	v_mfma_f32_16x16x128_f8f6f4 v[126:129], v[2:9], v[214:221], v[126:129]
	s_setprio 0
	s_setprio 1
	v_mfma_f32_16x16x128_f8f6f4 v[118:121], v[2:9], v[222:229], v[118:121]
	v_mfma_f32_16x16x128_f8f6f4 v[114:117], v[174:181], v[222:229], v[114:117]
	v_mfma_f32_16x16x128_f8f6f4 v[82:85], v[198:205], v[222:229], v[82:85]
	v_mfma_f32_16x16x128_f8f6f4 v[86:89], v[190:197], v[222:229], v[86:89]
	v_mfma_f32_16x16x128_f8f6f4 v[78:81], v[190:197], v[230:237], v[78:81]
	v_mfma_f32_16x16x128_f8f6f4 v[74:77], v[198:205], v[230:237], v[74:77]
	v_mfma_f32_16x16x128_f8f6f4 v[106:109], v[174:181], v[230:237], v[106:109]
	v_mfma_f32_16x16x128_f8f6f4 v[110:113], v[2:9], v[230:237], v[110:113]
	s_barrier
	s_setprio 0
	s_mov_b32 m0, s83
	v_lshl_add_u64 v[182:183], v[182:183], 0, s[26:27]
	s_add_u32 s54, s54, 0x158080
	global_load_lds_dwordx4 v[182:183], off
	v_lshl_add_u64 v[182:183], v[238:239], 0, s[26:27]
	s_mov_b32 m0, s84
	s_addc_u32 s55, s55, 0
	global_load_lds_dwordx4 v[182:183], off
	v_lshl_add_u64 v[182:183], s[54:55], 0, v[156:157]
	s_mov_b32 m0, s87
	s_nop 0
	global_load_lds_dwordx4 v[182:183], off
	v_lshl_add_u64 v[182:183], s[54:55], 0, v[160:161]
	s_mov_b32 m0, s88
	s_nop 0
	global_load_lds_dwordx4 v[182:183], off
	v_lshl_add_u64 v[182:183], v[242:243], 0, s[26:27]
	s_mov_b32 m0, s85
	s_nop 0
	global_load_lds_dwordx4 v[182:183], off
	v_lshl_add_u64 v[182:183], v[244:245], 0, s[26:27]
	s_mov_b32 m0, s86
	s_nop 0
	global_load_lds_dwordx4 v[182:183], off
	ds_read_b128 v[206:209], v188 offset:49152
	ds_read_b128 v[210:213], v188 offset:50176
	ds_read_b128 v[214:217], v188 offset:51200
	ds_read_b128 v[218:221], v188 offset:52224
	ds_read_b128 v[222:225], v188 offset:53248
	ds_read_b128 v[226:229], v188 offset:54272
	ds_read_b128 v[230:233], v188 offset:55296
	ds_read_b128 v[234:237], v188 offset:56320
	s_waitcnt vmcnt(8)
	s_waitcnt lgkmcnt(0)
	s_setprio 1
	s_barrier
	v_mfma_f32_16x16x128_f8f6f4 v[70:73], v[2:9], v[206:213], v[70:73]
	v_mfma_f32_16x16x128_f8f6f4 v[66:69], v[174:181], v[206:213], v[66:69]
	v_mfma_f32_16x16x128_f8f6f4 v[34:37], v[198:205], v[206:213], v[34:37]
	v_mfma_f32_16x16x128_f8f6f4 v[38:41], v[190:197], v[206:213], v[38:41]
	v_mfma_f32_16x16x128_f8f6f4 v[30:33], v[190:197], v[214:221], v[30:33]
	v_mfma_f32_16x16x128_f8f6f4 v[26:29], v[198:205], v[214:221], v[26:29]
	v_mfma_f32_16x16x128_f8f6f4 v[58:61], v[174:181], v[214:221], v[58:61]
	v_mfma_f32_16x16x128_f8f6f4 v[62:65], v[2:9], v[214:221], v[62:65]
	s_setprio 0
	s_setprio 1
	v_mfma_f32_16x16x128_f8f6f4 v[54:57], v[2:9], v[222:229], v[54:57]
	v_mfma_f32_16x16x128_f8f6f4 v[50:53], v[174:181], v[222:229], v[50:53]
	v_mfma_f32_16x16x128_f8f6f4 v[18:21], v[198:205], v[222:229], v[18:21]
	v_mfma_f32_16x16x128_f8f6f4 v[22:25], v[190:197], v[222:229], v[22:25]
	v_mfma_f32_16x16x128_f8f6f4 v[14:17], v[190:197], v[230:237], v[14:17]
	v_mfma_f32_16x16x128_f8f6f4 v[10:13], v[198:205], v[230:237], v[10:13]
	v_mfma_f32_16x16x128_f8f6f4 v[42:45], v[174:181], v[230:237], v[42:45]
	v_mfma_f32_16x16x128_f8f6f4 v[46:49], v[2:9], v[230:237], v[46:49]
	s_barrier
	s_setprio 0
	s_cmp_lt_u32 s95, 3
	s_cbranch_scc1 .LBB0_287
	s_add_u32 s54, s79, s9
	s_addc_u32 s55, s80, s8
	s_add_u32 s52, s52, 0x158180
	s_addc_u32 s53, s53, 0
	s_add_u32 s8, s50, 0x200
	v_lshl_add_u64 v[174:175], v[172:173], 2, s[54:55]
	s_addc_u32 s9, s51, 0
	s_mov_b32 s72, 4
	s_cmp_eq_u32 s95, s72
	s_cselect_b64 s[50:51], -1, 0
	s_cmp_lg_u32 s95, s72
	s_cbranch_scc1 .LBB0_285

.LBB0_285:
	s_add_u32 s54, s52, 0xffea8080
	s_addc_u32 s55, s53, -1
	s_and_b64 s[50:51], s[50:51], exec
	s_cselect_b32 s50, s4, s8
	s_cselect_b32 s55, s1, s55
	s_cselect_b32 s54, s0, s54
	s_cselect_b32 s51, s5, s9
	s_mov_b32 m0, s49
	v_lshl_add_u64 v[238:239], s[52:53], 0, v[162:163]
	global_load_lds_dwordx4 v[238:239], off
	v_lshl_add_u64 v[238:239], s[52:53], 0, v[164:165]
	s_mov_b32 m0, s71
	s_nop 0
	global_load_lds_dwordx4 v[238:239], off
	ds_read_b128 v[2:5], v187
	ds_read_b128 v[6:9], v187 offset:1024
	ds_read_b128 v[190:193], v187 offset:2048
	ds_read_b128 v[194:197], v187 offset:3072
	ds_read_b128 v[198:201], v187 offset:16384
	ds_read_b128 v[202:205], v187 offset:17408
	ds_read_b128 v[206:209], v187 offset:18432
	ds_read_b128 v[210:213], v187 offset:19456
	ds_read_b128 v[176:179], v188
	ds_read_b128 v[180:183], v188 offset:1024
	ds_read_b128 v[214:217], v188 offset:2048
	ds_read_b128 v[218:221], v188 offset:3072
	ds_read_b128 v[222:225], v188 offset:4096
	ds_read_b128 v[226:229], v188 offset:5120
	ds_read_b128 v[230:233], v188 offset:6144
	ds_read_b128 v[234:237], v188 offset:7168
	s_waitcnt vmcnt(8)
	s_waitcnt lgkmcnt(0)
	s_setprio 1
	s_barrier
	v_mfma_f32_16x16x128_f8f6f4 v[134:137], v[2:9], v[176:183], v[134:137]
	v_mfma_f32_16x16x128_f8f6f4 v[130:133], v[190:197], v[176:183], v[130:133]
	v_mfma_f32_16x16x128_f8f6f4 v[98:101], v[206:213], v[176:183], v[98:101]
	v_mfma_f32_16x16x128_f8f6f4 v[102:105], v[198:205], v[176:183], v[102:105]
	v_mfma_f32_16x16x128_f8f6f4 v[94:97], v[198:205], v[214:221], v[94:97]
	v_mfma_f32_16x16x128_f8f6f4 v[90:93], v[206:213], v[214:221], v[90:93]
	v_mfma_f32_16x16x128_f8f6f4 v[122:125], v[190:197], v[214:221], v[122:125]
	v_mfma_f32_16x16x128_f8f6f4 v[126:129], v[2:9], v[214:221], v[126:129]
	s_setprio 0
	s_setprio 1
	v_mfma_f32_16x16x128_f8f6f4 v[118:121], v[2:9], v[222:229], v[118:121]
	v_mfma_f32_16x16x128_f8f6f4 v[114:117], v[190:197], v[222:229], v[114:117]
	v_mfma_f32_16x16x128_f8f6f4 v[82:85], v[206:213], v[222:229], v[82:85]
	v_mfma_f32_16x16x128_f8f6f4 v[86:89], v[198:205], v[222:229], v[86:89]
	v_mfma_f32_16x16x128_f8f6f4 v[78:81], v[198:205], v[230:237], v[78:81]
	v_mfma_f32_16x16x128_f8f6f4 v[74:77], v[206:213], v[230:237], v[74:77]
	v_mfma_f32_16x16x128_f8f6f4 v[106:109], v[190:197], v[230:237], v[106:109]
	v_mfma_f32_16x16x128_f8f6f4 v[110:113], v[2:9], v[230:237], v[110:113]
	s_barrier
	s_setprio 0
	s_mov_b32 m0, s47
	v_lshl_add_u64 v[176:177], s[50:51], 0, v[156:157]
	s_add_u32 s62, s50, 0x158000
	global_load_lds_dwordx4 v[176:177], off
	v_lshl_add_u64 v[178:179], s[50:51], 0, v[160:161]
	s_mov_b32 m0, s68
	s_addc_u32 s63, s51, 0
	global_load_lds_dwordx4 v[178:179], off
	v_lshl_add_u64 v[180:181], s[62:63], 0, v[156:157]
	s_mov_b32 m0, s69
	v_lshl_add_u64 v[182:183], s[54:55], 0, v[158:159]
	global_load_lds_dwordx4 v[180:181], off
	v_lshl_add_u64 v[180:181], s[62:63], 0, v[160:161]
	s_mov_b32 m0, s74
	s_nop 0
	global_load_lds_dwordx4 v[180:181], off
	v_lshl_add_u64 v[180:181], s[54:55], 0, v[154:155]
	s_mov_b32 m0, s33
	s_nop 0
	global_load_lds_dwordx4 v[180:181], off
	s_mov_b32 m0, s75
	s_nop 0
	global_load_lds_dwordx4 v[182:183], off
	ds_read_b128 v[214:217], v188 offset:16384
	ds_read_b128 v[218:221], v188 offset:17408
	ds_read_b128 v[222:225], v188 offset:18432
	ds_read_b128 v[226:229], v188 offset:19456
	ds_read_b128 v[230:233], v188 offset:20480
	ds_read_b128 v[234:237], v188 offset:21504
	ds_read_b128 v[242:245], v188 offset:22528
	ds_read_b128 v[246:249], v188 offset:23552
	s_waitcnt vmcnt(8)
	s_waitcnt lgkmcnt(0)
	s_setprio 1
	s_barrier
	v_mfma_f32_16x16x128_f8f6f4 v[70:73], v[2:9], v[214:221], v[70:73]
	v_mfma_f32_16x16x128_f8f6f4 v[66:69], v[190:197], v[214:221], v[66:69]
	v_mfma_f32_16x16x128_f8f6f4 v[34:37], v[206:213], v[214:221], v[34:37]
	v_mfma_f32_16x16x128_f8f6f4 v[38:41], v[198:205], v[214:221], v[38:41]
	v_mfma_f32_16x16x128_f8f6f4 v[30:33], v[198:205], v[222:229], v[30:33]
	v_mfma_f32_16x16x128_f8f6f4 v[26:29], v[206:213], v[222:229], v[26:29]
	v_mfma_f32_16x16x128_f8f6f4 v[58:61], v[190:197], v[222:229], v[58:61]
	v_mfma_f32_16x16x128_f8f6f4 v[62:65], v[2:9], v[222:229], v[62:65]
	s_setprio 0
	s_setprio 1
	v_mfma_f32_16x16x128_f8f6f4 v[54:57], v[2:9], v[230:237], v[54:57]
	v_mfma_f32_16x16x128_f8f6f4 v[50:53], v[190:197], v[230:237], v[50:53]
	v_mfma_f32_16x16x128_f8f6f4 v[18:21], v[206:213], v[230:237], v[18:21]
	v_mfma_f32_16x16x128_f8f6f4 v[22:25], v[198:205], v[230:237], v[22:25]
	v_mfma_f32_16x16x128_f8f6f4 v[14:17], v[198:205], v[242:249], v[14:17]
	v_mfma_f32_16x16x128_f8f6f4 v[10:13], v[206:213], v[242:249], v[10:13]
	v_mfma_f32_16x16x128_f8f6f4 v[42:45], v[190:197], v[242:249], v[42:45]
	v_mfma_f32_16x16x128_f8f6f4 v[46:49], v[2:9], v[242:249], v[46:49]
	s_barrier
	s_setprio 0
	s_add_u32 s54, s54, 0x158000
	s_addc_u32 s55, s55, 0
	s_mov_b32 m0, s76
	v_lshl_add_u64 v[238:239], s[54:55], 0, v[154:155]
	global_load_lds_dwordx4 v[238:239], off
	v_lshl_add_u64 v[238:239], s[54:55], 0, v[158:159]
	s_mov_b32 m0, s77
	s_nop 0
	global_load_lds_dwordx4 v[238:239], off
	ds_read_b128 v[190:193], v187 offset:32768
	ds_read_b128 v[194:197], v187 offset:33792
	ds_read_b128 v[198:201], v187 offset:34816
	ds_read_b128 v[202:205], v187 offset:35840
	ds_read_b128 v[2:5], v187 offset:49152
	ds_read_b128 v[6:9], v187 offset:50176
	ds_read_b128 v[206:209], v187 offset:51200
	ds_read_b128 v[210:213], v187 offset:52224
	ds_read_b128 v[214:217], v188 offset:32768
	ds_read_b128 v[218:221], v188 offset:33792
	ds_read_b128 v[222:225], v188 offset:34816
	ds_read_b128 v[226:229], v188 offset:35840
	ds_read_b128 v[230:233], v188 offset:36864
	ds_read_b128 v[234:237], v188 offset:37888
	ds_read_b128 v[242:245], v188 offset:38912
	ds_read_b128 v[246:249], v188 offset:39936
	s_waitcnt vmcnt(8)
	s_waitcnt lgkmcnt(0)
	s_setprio 1
	s_barrier
	v_mfma_f32_16x16x128_f8f6f4 v[134:137], v[190:197], v[214:221], v[134:137]
	v_mfma_f32_16x16x128_f8f6f4 v[130:133], v[198:205], v[214:221], v[130:133]
	v_mfma_f32_16x16x128_f8f6f4 v[98:101], v[206:213], v[214:221], v[98:101]
	v_mfma_f32_16x16x128_f8f6f4 v[102:105], v[2:9], v[214:221], v[102:105]
	v_mfma_f32_16x16x128_f8f6f4 v[94:97], v[2:9], v[222:229], v[94:97]
	v_mfma_f32_16x16x128_f8f6f4 v[90:93], v[206:213], v[222:229], v[90:93]
	v_mfma_f32_16x16x128_f8f6f4 v[122:125], v[198:205], v[222:229], v[122:125]
	v_mfma_f32_16x16x128_f8f6f4 v[126:129], v[190:197], v[222:229], v[126:129]
	s_setprio 0
	s_setprio 1
	v_mfma_f32_16x16x128_f8f6f4 v[118:121], v[190:197], v[230:237], v[118:121]
	v_mfma_f32_16x16x128_f8f6f4 v[114:117], v[198:205], v[230:237], v[114:117]
	v_mfma_f32_16x16x128_f8f6f4 v[82:85], v[206:213], v[230:237], v[82:85]
	v_mfma_f32_16x16x128_f8f6f4 v[86:89], v[2:9], v[230:237], v[86:89]
	v_mfma_f32_16x16x128_f8f6f4 v[78:81], v[2:9], v[242:249], v[78:81]
	v_mfma_f32_16x16x128_f8f6f4 v[74:77], v[206:213], v[242:249], v[74:77]
	v_mfma_f32_16x16x128_f8f6f4 v[106:109], v[198:205], v[242:249], v[106:109]
	v_mfma_f32_16x16x128_f8f6f4 v[110:113], v[190:197], v[242:249], v[110:113]
	s_barrier
	s_setprio 0
	s_mov_b32 m0, s83
	v_lshl_add_u64 v[176:177], v[176:177], 0, s[26:27]
	s_add_u32 s50, s50, 0x158080
	global_load_lds_dwordx4 v[176:177], off
	v_lshl_add_u64 v[176:177], v[178:179], 0, s[26:27]
	s_mov_b32 m0, s84
	s_addc_u32 s51, s51, 0
	global_load_lds_dwordx4 v[176:177], off
	v_lshl_add_u64 v[176:177], s[50:51], 0, v[156:157]
	s_mov_b32 m0, s87
	s_nop 0
	global_load_lds_dwordx4 v[176:177], off
	v_lshl_add_u64 v[176:177], s[50:51], 0, v[160:161]
	s_mov_b32 m0, s88
	s_nop 0
	global_load_lds_dwordx4 v[176:177], off
	v_lshl_add_u64 v[176:177], v[180:181], 0, s[26:27]
	s_mov_b32 m0, s85
	s_nop 0
	global_load_lds_dwordx4 v[176:177], off
	v_lshl_add_u64 v[176:177], v[182:183], 0, s[26:27]
	s_mov_b32 m0, s86
	s_nop 0
	global_load_lds_dwordx4 v[176:177], off
	ds_read_b128 v[214:217], v188 offset:49152
	ds_read_b128 v[218:221], v188 offset:50176
	ds_read_b128 v[222:225], v188 offset:51200
	ds_read_b128 v[226:229], v188 offset:52224
	ds_read_b128 v[230:233], v188 offset:53248
	ds_read_b128 v[234:237], v188 offset:54272
	ds_read_b128 v[242:245], v188 offset:55296
	ds_read_b128 v[246:249], v188 offset:56320
	s_waitcnt vmcnt(8)
	s_waitcnt lgkmcnt(0)
	s_setprio 1
	s_barrier
	v_mfma_f32_16x16x128_f8f6f4 v[70:73], v[190:197], v[214:221], v[70:73]
	v_mfma_f32_16x16x128_f8f6f4 v[66:69], v[198:205], v[214:221], v[66:69]
	v_mfma_f32_16x16x128_f8f6f4 v[34:37], v[206:213], v[214:221], v[34:37]
	v_mfma_f32_16x16x128_f8f6f4 v[38:41], v[2:9], v[214:221], v[38:41]
	v_mfma_f32_16x16x128_f8f6f4 v[30:33], v[2:9], v[222:229], v[30:33]
	v_mfma_f32_16x16x128_f8f6f4 v[26:29], v[206:213], v[222:229], v[26:29]
	v_mfma_f32_16x16x128_f8f6f4 v[58:61], v[198:205], v[222:229], v[58:61]
	v_mfma_f32_16x16x128_f8f6f4 v[62:65], v[190:197], v[222:229], v[62:65]
	s_setprio 0
	s_setprio 1
	v_mfma_f32_16x16x128_f8f6f4 v[54:57], v[190:197], v[230:237], v[54:57]
	v_mfma_f32_16x16x128_f8f6f4 v[50:53], v[198:205], v[230:237], v[50:53]
	v_mfma_f32_16x16x128_f8f6f4 v[18:21], v[206:213], v[230:237], v[18:21]
	v_mfma_f32_16x16x128_f8f6f4 v[22:25], v[2:9], v[230:237], v[22:25]
	v_mfma_f32_16x16x128_f8f6f4 v[14:17], v[2:9], v[242:249], v[14:17]
	v_mfma_f32_16x16x128_f8f6f4 v[10:13], v[206:213], v[242:249], v[10:13]
	v_mfma_f32_16x16x128_f8f6f4 v[42:45], v[198:205], v[242:249], v[42:45]
	v_mfma_f32_16x16x128_f8f6f4 v[46:49], v[190:197], v[242:249], v[46:49]
	s_barrier
	s_setprio 0
	s_add_i32 s50, s72, 2
	s_add_u32 s52, s52, 0x100
	s_addc_u32 s53, s53, 0
	s_add_u32 s8, s8, 0x100
	s_addc_u32 s9, s9, 0
	s_cmp_ge_i32 s72, s95
	s_cbranch_scc1 .LBB0_287
	s_mov_b32 s72, s50
	s_cmp_eq_u32 s95, s72
	s_cselect_b64 s[50:51], -1, 0
	s_cmp_lg_u32 s95, s72
	s_cbranch_scc0 .LBB0_284
	s_branch .LBB0_285

.LBB0_437:
	s_ashr_i32 s47, s46, 31
	s_lshl_b64 s[8:9], s[46:47], 20
	s_add_u32 s48, s12, s8
	s_addc_u32 s49, s13, s9
	s_and_b64 s[8:9], s[2:3], exec
	s_cselect_b32 s47, s49, s73
	s_cselect_b32 s71, s48, s72
	s_ashr_i32 s45, s44, 31
	s_lshl_b64 s[8:9], s[44:45], 20
	s_add_u32 s50, s39, s8
	s_addc_u32 s51, s76, s9
	s_and_b64 s[8:9], s[2:3], exec
	s_cselect_b32 s45, s51, s55
	s_cselect_b32 s94, s50, s54
	s_add_u32 s8, s72, 0x80080
	s_addc_u32 s9, s73, 0
	s_mov_b32 m0, s33
	v_lshl_add_u64 v[226:227], s[8:9], 0, v[162:163]
	global_load_lds_dwordx4 v[226:227], off
	v_lshl_add_u64 v[226:227], s[8:9], 0, v[166:167]
	s_mov_b32 m0, s93
	s_nop 0
	global_load_lds_dwordx4 v[226:227], off
	ds_read_b128 v[18:21], v200
	ds_read_b128 v[22:25], v200 offset:1024
	ds_read_b128 v[26:29], v200 offset:2048
	ds_read_b128 v[30:33], v200 offset:3072
	ds_read_b128 v[2:5], v200 offset:16384
	ds_read_b128 v[6:9], v200 offset:17408
	ds_read_b128 v[10:13], v200 offset:18432
	ds_read_b128 v[14:17], v200 offset:19456
	ds_read_b128 v[180:183], v201
	ds_read_b128 v[184:187], v201 offset:1024
	ds_read_b128 v[202:205], v201 offset:2048
	ds_read_b128 v[206:209], v201 offset:3072
	ds_read_b128 v[210:213], v201 offset:4096
	ds_read_b128 v[214:217], v201 offset:5120
	ds_read_b128 v[218:221], v201 offset:6144
	ds_read_b128 v[222:225], v201 offset:7168
	s_waitcnt vmcnt(8)
	s_waitcnt lgkmcnt(0)
	s_setprio 1
	s_barrier
	v_mfma_f32_16x16x128_f8f6f4 v[158:161], v[18:25], v[180:187], 0
	v_mfma_f32_16x16x128_f8f6f4 v[154:157], v[26:33], v[180:187], 0
	v_mfma_f32_16x16x128_f8f6f4 v[122:125], v[10:17], v[180:187], 0
	v_mfma_f32_16x16x128_f8f6f4 v[126:129], v[2:9], v[180:187], 0
	v_mfma_f32_16x16x128_f8f6f4 v[118:121], v[2:9], v[202:209], 0
	v_mfma_f32_16x16x128_f8f6f4 v[114:117], v[10:17], v[202:209], 0
	v_mfma_f32_16x16x128_f8f6f4 v[146:149], v[26:33], v[202:209], 0
	v_mfma_f32_16x16x128_f8f6f4 v[150:153], v[18:25], v[202:209], 0
	s_setprio 0
	s_setprio 1
	v_mfma_f32_16x16x128_f8f6f4 v[142:145], v[18:25], v[210:217], 0
	v_mfma_f32_16x16x128_f8f6f4 v[138:141], v[26:33], v[210:217], 0
	v_mfma_f32_16x16x128_f8f6f4 v[106:109], v[10:17], v[210:217], 0
	v_mfma_f32_16x16x128_f8f6f4 v[110:113], v[2:9], v[210:217], 0
	v_mfma_f32_16x16x128_f8f6f4 v[102:105], v[2:9], v[218:225], 0
	v_mfma_f32_16x16x128_f8f6f4 v[98:101], v[10:17], v[218:225], 0
	v_mfma_f32_16x16x128_f8f6f4 v[130:133], v[26:33], v[218:225], 0
	v_mfma_f32_16x16x128_f8f6f4 v[134:137], v[18:25], v[218:225], 0
	s_barrier
	s_setprio 0
	v_lshl_add_u64 v[180:181], s[54:55], 0, v[164:165]
	s_mov_b32 m0, s78
	v_lshl_add_u64 v[182:183], v[180:181], 0, s[26:27]
	global_load_lds_dwordx4 v[182:183], off
	v_lshl_add_u64 v[182:183], s[54:55], 0, v[168:169]
	s_add_u32 s8, s54, 0x80100
	v_lshl_add_u64 v[184:185], v[182:183], 0, s[26:27]
	s_mov_b32 m0, s79
	s_addc_u32 s9, s55, 0
	global_load_lds_dwordx4 v[184:185], off
	v_lshl_add_u64 v[184:185], s[8:9], 0, v[164:165]
	s_mov_b32 m0, s80
	s_nop 0
	global_load_lds_dwordx4 v[184:185], off
	v_lshl_add_u64 v[184:185], s[8:9], 0, v[168:169]
	s_mov_b32 m0, s81
	s_nop 0
	global_load_lds_dwordx4 v[184:185], off
	v_lshl_add_u64 v[184:185], s[72:73], 0, v[162:163]
	v_lshl_add_u64 v[186:187], v[184:185], 0, s[26:27]
	s_mov_b32 m0, s53
	s_nop 0
	global_load_lds_dwordx4 v[186:187], off
	v_lshl_add_u64 v[186:187], s[72:73], 0, v[166:167]
	v_lshl_add_u64 v[234:235], v[186:187], 0, s[26:27]
	s_mov_b32 m0, s82
	s_nop 0
	global_load_lds_dwordx4 v[234:235], off
	ds_read_b128 v[202:205], v201 offset:16384
	ds_read_b128 v[206:209], v201 offset:17408
	ds_read_b128 v[210:213], v201 offset:18432
	ds_read_b128 v[214:217], v201 offset:19456
	ds_read_b128 v[218:221], v201 offset:20480
	ds_read_b128 v[222:225], v201 offset:21504
	ds_read_b128 v[226:229], v201 offset:22528
	ds_read_b128 v[230:233], v201 offset:23552
	s_waitcnt vmcnt(8)
	s_waitcnt lgkmcnt(0)
	s_setprio 1
	s_barrier
	v_mfma_f32_16x16x128_f8f6f4 v[94:97], v[18:25], v[202:209], 0
	v_mfma_f32_16x16x128_f8f6f4 v[90:93], v[26:33], v[202:209], 0
	v_mfma_f32_16x16x128_f8f6f4 v[58:61], v[10:17], v[202:209], 0
	v_mfma_f32_16x16x128_f8f6f4 v[62:65], v[2:9], v[202:209], 0
	v_mfma_f32_16x16x128_f8f6f4 v[54:57], v[2:9], v[210:217], 0
	v_mfma_f32_16x16x128_f8f6f4 v[50:53], v[10:17], v[210:217], 0
	v_mfma_f32_16x16x128_f8f6f4 v[82:85], v[26:33], v[210:217], 0
	v_mfma_f32_16x16x128_f8f6f4 v[86:89], v[18:25], v[210:217], 0
	s_setprio 0
	s_setprio 1
	v_mfma_f32_16x16x128_f8f6f4 v[78:81], v[18:25], v[218:225], 0
	v_mfma_f32_16x16x128_f8f6f4 v[74:77], v[26:33], v[218:225], 0
	v_mfma_f32_16x16x128_f8f6f4 v[42:45], v[10:17], v[218:225], 0
	v_mfma_f32_16x16x128_f8f6f4 v[46:49], v[2:9], v[218:225], 0
	v_mfma_f32_16x16x128_f8f6f4 v[38:41], v[2:9], v[226:233], 0
	v_mfma_f32_16x16x128_f8f6f4 v[34:37], v[10:17], v[226:233], 0
	v_mfma_f32_16x16x128_f8f6f4 v[66:69], v[26:33], v[226:233], 0
	v_mfma_f32_16x16x128_f8f6f4 v[70:73], v[18:25], v[226:233], 0
	s_barrier
	s_setprio 0
	s_add_u32 s8, s72, 0x80100
	s_addc_u32 s9, s73, 0
	s_mov_b32 m0, s83
	v_lshl_add_u64 v[234:235], s[8:9], 0, v[162:163]
	global_load_lds_dwordx4 v[234:235], off
	v_lshl_add_u64 v[234:235], s[8:9], 0, v[166:167]
	s_mov_b32 m0, s84
	s_nop 0
	global_load_lds_dwordx4 v[234:235], off
	ds_read_b128 v[18:21], v200 offset:32768
	ds_read_b128 v[22:25], v200 offset:33792
	ds_read_b128 v[26:29], v200 offset:34816
	ds_read_b128 v[30:33], v200 offset:35840
	ds_read_b128 v[2:5], v200 offset:49152
	ds_read_b128 v[6:9], v200 offset:50176
	ds_read_b128 v[10:13], v200 offset:51200
	ds_read_b128 v[14:17], v200 offset:52224
	ds_read_b128 v[202:205], v201 offset:32768
	ds_read_b128 v[206:209], v201 offset:33792
	ds_read_b128 v[210:213], v201 offset:34816
	ds_read_b128 v[214:217], v201 offset:35840
	ds_read_b128 v[218:221], v201 offset:36864
	ds_read_b128 v[222:225], v201 offset:37888
	ds_read_b128 v[226:229], v201 offset:38912
	ds_read_b128 v[230:233], v201 offset:39936
	s_waitcnt vmcnt(8)
	s_waitcnt lgkmcnt(0)
	s_setprio 1
	s_barrier
	v_mfma_f32_16x16x128_f8f6f4 v[158:161], v[18:25], v[202:209], v[158:161]
	v_mfma_f32_16x16x128_f8f6f4 v[154:157], v[26:33], v[202:209], v[154:157]
	v_mfma_f32_16x16x128_f8f6f4 v[122:125], v[10:17], v[202:209], v[122:125]
	v_mfma_f32_16x16x128_f8f6f4 v[126:129], v[2:9], v[202:209], v[126:129]
	v_mfma_f32_16x16x128_f8f6f4 v[118:121], v[2:9], v[210:217], v[118:121]
	v_mfma_f32_16x16x128_f8f6f4 v[114:117], v[10:17], v[210:217], v[114:117]
	v_mfma_f32_16x16x128_f8f6f4 v[146:149], v[26:33], v[210:217], v[146:149]
	v_mfma_f32_16x16x128_f8f6f4 v[150:153], v[18:25], v[210:217], v[150:153]
	s_setprio 0
	s_setprio 1
	v_mfma_f32_16x16x128_f8f6f4 v[142:145], v[18:25], v[218:225], v[142:145]
	v_mfma_f32_16x16x128_f8f6f4 v[138:141], v[26:33], v[218:225], v[138:141]
	v_mfma_f32_16x16x128_f8f6f4 v[106:109], v[10:17], v[218:225], v[106:109]
	v_mfma_f32_16x16x128_f8f6f4 v[110:113], v[2:9], v[218:225], v[110:113]
	v_mfma_f32_16x16x128_f8f6f4 v[102:105], v[2:9], v[226:233], v[102:105]
	v_mfma_f32_16x16x128_f8f6f4 v[98:101], v[10:17], v[226:233], v[98:101]
	v_mfma_f32_16x16x128_f8f6f4 v[130:133], v[26:33], v[226:233], v[130:133]
	v_mfma_f32_16x16x128_f8f6f4 v[134:137], v[18:25], v[226:233], v[134:137]
	s_barrier
	s_setprio 0
	s_mov_b32 m0, s87
	v_lshl_add_u64 v[180:181], v[180:181], 0, s[36:37]
	s_add_u32 s8, s54, 0x80180
	global_load_lds_dwordx4 v[180:181], off
	v_lshl_add_u64 v[180:181], v[182:183], 0, s[36:37]
	s_mov_b32 m0, s88
	s_addc_u32 s9, s55, 0
	global_load_lds_dwordx4 v[180:181], off
	v_lshl_add_u64 v[180:181], s[8:9], 0, v[164:165]
	s_mov_b32 m0, s91
	s_nop 0
	global_load_lds_dwordx4 v[180:181], off
	v_lshl_add_u64 v[180:181], s[8:9], 0, v[168:169]
	s_mov_b32 m0, s92
	s_nop 0
	global_load_lds_dwordx4 v[180:181], off
	v_lshl_add_u64 v[180:181], v[184:185], 0, s[36:37]
	s_mov_b32 m0, s89
	s_nop 0
	global_load_lds_dwordx4 v[180:181], off
	v_lshl_add_u64 v[180:181], v[186:187], 0, s[36:37]
	s_mov_b32 m0, s90
	s_nop 0
	global_load_lds_dwordx4 v[180:181], off
	ds_read_b128 v[202:205], v201 offset:49152
	ds_read_b128 v[206:209], v201 offset:50176
	ds_read_b128 v[210:213], v201 offset:51200
	ds_read_b128 v[214:217], v201 offset:52224
	ds_read_b128 v[218:221], v201 offset:53248
	ds_read_b128 v[222:225], v201 offset:54272
	ds_read_b128 v[226:229], v201 offset:55296
	ds_read_b128 v[230:233], v201 offset:56320
	s_waitcnt vmcnt(8)
	s_waitcnt lgkmcnt(0)
	s_setprio 1
	s_barrier
	v_mfma_f32_16x16x128_f8f6f4 v[94:97], v[18:25], v[202:209], v[94:97]
	v_mfma_f32_16x16x128_f8f6f4 v[90:93], v[26:33], v[202:209], v[90:93]
	v_mfma_f32_16x16x128_f8f6f4 v[58:61], v[10:17], v[202:209], v[58:61]
	v_mfma_f32_16x16x128_f8f6f4 v[62:65], v[2:9], v[202:209], v[62:65]
	v_mfma_f32_16x16x128_f8f6f4 v[54:57], v[2:9], v[210:217], v[54:57]
	v_mfma_f32_16x16x128_f8f6f4 v[50:53], v[10:17], v[210:217], v[50:53]
	v_mfma_f32_16x16x128_f8f6f4 v[82:85], v[26:33], v[210:217], v[82:85]
	v_mfma_f32_16x16x128_f8f6f4 v[86:89], v[18:25], v[210:217], v[86:89]
	s_setprio 0
	s_setprio 1
	v_mfma_f32_16x16x128_f8f6f4 v[78:81], v[18:25], v[218:225], v[78:81]
	v_mfma_f32_16x16x128_f8f6f4 v[74:77], v[26:33], v[218:225], v[74:77]
	v_mfma_f32_16x16x128_f8f6f4 v[42:45], v[10:17], v[218:225], v[42:45]
	v_mfma_f32_16x16x128_f8f6f4 v[46:49], v[2:9], v[218:225], v[46:49]
	v_mfma_f32_16x16x128_f8f6f4 v[38:41], v[2:9], v[226:233], v[38:41]
	v_mfma_f32_16x16x128_f8f6f4 v[34:37], v[10:17], v[226:233], v[34:37]
	v_mfma_f32_16x16x128_f8f6f4 v[66:69], v[26:33], v[226:233], v[66:69]
	v_mfma_f32_16x16x128_f8f6f4 v[70:73], v[18:25], v[226:233], v[70:73]
	s_barrier
	s_setprio 0
	s_add_u32 s72, s72, 0x80180
	s_addc_u32 s73, s73, 0
	s_add_u32 s8, s54, 0x200
	s_addc_u32 s9, s55, 0
	s_mov_b32 s62, 0
.LBB0_438:
	s_add_u32 s54, s72, 0xfff80080
	s_addc_u32 s55, s73, -1
	s_cmp_eq_u32 s62, 28
	s_cselect_b32 s75, s47, s55
	s_cselect_b32 s74, s71, s54
	s_cselect_b32 s55, s45, s9
	s_cselect_b32 s54, s94, s8
	s_mov_b32 m0, s33
	v_lshl_add_u64 v[226:227], s[72:73], 0, v[170:171]
	global_load_lds_dwordx4 v[226:227], off
	v_lshl_add_u64 v[226:227], s[72:73], 0, v[172:173]
	s_mov_b32 m0, s93
	s_nop 0
	global_load_lds_dwordx4 v[226:227], off
	ds_read_b128 v[2:5], v200
	ds_read_b128 v[6:9], v200 offset:1024
	ds_read_b128 v[18:21], v200 offset:2048
	ds_read_b128 v[22:25], v200 offset:3072
	ds_read_b128 v[26:29], v200 offset:16384
	ds_read_b128 v[30:33], v200 offset:17408
	ds_read_b128 v[180:183], v200 offset:18432
	ds_read_b128 v[184:187], v200 offset:19456
	ds_read_b128 v[10:13], v201
	ds_read_b128 v[14:17], v201 offset:1024
	ds_read_b128 v[202:205], v201 offset:2048
	ds_read_b128 v[206:209], v201 offset:3072
	ds_read_b128 v[210:213], v201 offset:4096
	ds_read_b128 v[214:217], v201 offset:5120
	ds_read_b128 v[218:221], v201 offset:6144
	ds_read_b128 v[222:225], v201 offset:7168
	s_waitcnt vmcnt(8)
	s_waitcnt lgkmcnt(0)
	s_setprio 1
	s_barrier
	v_mfma_f32_16x16x128_f8f6f4 v[158:161], v[2:9], v[10:17], v[158:161]
	v_mfma_f32_16x16x128_f8f6f4 v[154:157], v[18:25], v[10:17], v[154:157]
	v_mfma_f32_16x16x128_f8f6f4 v[122:125], v[180:187], v[10:17], v[122:125]
	v_mfma_f32_16x16x128_f8f6f4 v[126:129], v[26:33], v[10:17], v[126:129]
	v_mfma_f32_16x16x128_f8f6f4 v[118:121], v[26:33], v[202:209], v[118:121]
	v_mfma_f32_16x16x128_f8f6f4 v[114:117], v[180:187], v[202:209], v[114:117]
	v_mfma_f32_16x16x128_f8f6f4 v[146:149], v[18:25], v[202:209], v[146:149]
	v_mfma_f32_16x16x128_f8f6f4 v[150:153], v[2:9], v[202:209], v[150:153]
	s_setprio 0
	s_setprio 1
	v_mfma_f32_16x16x128_f8f6f4 v[142:145], v[2:9], v[210:217], v[142:145]
	v_mfma_f32_16x16x128_f8f6f4 v[138:141], v[18:25], v[210:217], v[138:141]
	v_mfma_f32_16x16x128_f8f6f4 v[106:109], v[180:187], v[210:217], v[106:109]
	v_mfma_f32_16x16x128_f8f6f4 v[110:113], v[26:33], v[210:217], v[110:113]
	v_mfma_f32_16x16x128_f8f6f4 v[102:105], v[26:33], v[218:225], v[102:105]
	v_mfma_f32_16x16x128_f8f6f4 v[98:101], v[180:187], v[218:225], v[98:101]
	v_mfma_f32_16x16x128_f8f6f4 v[130:133], v[18:25], v[218:225], v[130:133]
	v_mfma_f32_16x16x128_f8f6f4 v[134:137], v[2:9], v[218:225], v[134:137]
	s_barrier
	s_setprio 0
	s_mov_b32 m0, s78
	v_lshl_add_u64 v[10:11], s[54:55], 0, v[164:165]
	s_add_u32 s96, s54, 0x80000
	global_load_lds_dwordx4 v[10:11], off
	v_lshl_add_u64 v[12:13], s[54:55], 0, v[168:169]
	s_mov_b32 m0, s79
	s_addc_u32 s97, s55, 0
	global_load_lds_dwordx4 v[12:13], off
	v_lshl_add_u64 v[14:15], s[96:97], 0, v[164:165]
	s_mov_b32 m0, s80
	v_lshl_add_u64 v[16:17], s[74:75], 0, v[166:167]
	global_load_lds_dwordx4 v[14:15], off
	v_lshl_add_u64 v[14:15], s[96:97], 0, v[168:169]
	s_mov_b32 m0, s81
	s_nop 0
	global_load_lds_dwordx4 v[14:15], off
	v_lshl_add_u64 v[14:15], s[74:75], 0, v[162:163]
	s_mov_b32 m0, s53
	s_nop 0
	global_load_lds_dwordx4 v[14:15], off
	s_mov_b32 m0, s82
	s_nop 0
	global_load_lds_dwordx4 v[16:17], off
	ds_read_b128 v[202:205], v201 offset:16384
	ds_read_b128 v[206:209], v201 offset:17408
	ds_read_b128 v[210:213], v201 offset:18432
	ds_read_b128 v[214:217], v201 offset:19456
	ds_read_b128 v[218:221], v201 offset:20480
	ds_read_b128 v[222:225], v201 offset:21504
	ds_read_b128 v[226:229], v201 offset:22528
	ds_read_b128 v[230:233], v201 offset:23552
	s_waitcnt vmcnt(8)
	s_waitcnt lgkmcnt(0)
	s_setprio 1
	s_barrier
	v_mfma_f32_16x16x128_f8f6f4 v[94:97], v[2:9], v[202:209], v[94:97]
	v_mfma_f32_16x16x128_f8f6f4 v[90:93], v[18:25], v[202:209], v[90:93]
	v_mfma_f32_16x16x128_f8f6f4 v[58:61], v[180:187], v[202:209], v[58:61]
	v_mfma_f32_16x16x128_f8f6f4 v[62:65], v[26:33], v[202:209], v[62:65]
	v_mfma_f32_16x16x128_f8f6f4 v[54:57], v[26:33], v[210:217], v[54:57]
	v_mfma_f32_16x16x128_f8f6f4 v[50:53], v[180:187], v[210:217], v[50:53]
	v_mfma_f32_16x16x128_f8f6f4 v[82:85], v[18:25], v[210:217], v[82:85]
	v_mfma_f32_16x16x128_f8f6f4 v[86:89], v[2:9], v[210:217], v[86:89]
	s_setprio 0
	s_setprio 1
	v_mfma_f32_16x16x128_f8f6f4 v[78:81], v[2:9], v[218:225], v[78:81]
	v_mfma_f32_16x16x128_f8f6f4 v[74:77], v[18:25], v[218:225], v[74:77]
	v_mfma_f32_16x16x128_f8f6f4 v[42:45], v[180:187], v[218:225], v[42:45]
	v_mfma_f32_16x16x128_f8f6f4 v[46:49], v[26:33], v[218:225], v[46:49]
	v_mfma_f32_16x16x128_f8f6f4 v[38:41], v[26:33], v[226:233], v[38:41]
	v_mfma_f32_16x16x128_f8f6f4 v[34:37], v[180:187], v[226:233], v[34:37]
	v_mfma_f32_16x16x128_f8f6f4 v[66:69], v[18:25], v[226:233], v[66:69]
	v_mfma_f32_16x16x128_f8f6f4 v[70:73], v[2:9], v[226:233], v[70:73]
	s_barrier
	s_setprio 0
	s_add_u32 s74, s74, 0x80000
	s_addc_u32 s75, s75, 0
	s_mov_b32 m0, s83
	v_lshl_add_u64 v[234:235], s[74:75], 0, v[162:163]
	global_load_lds_dwordx4 v[234:235], off
	v_lshl_add_u64 v[234:235], s[74:75], 0, v[166:167]
	s_mov_b32 m0, s84
	s_nop 0
	global_load_lds_dwordx4 v[234:235], off
	ds_read_b128 v[18:21], v200 offset:32768
	ds_read_b128 v[22:25], v200 offset:33792
	ds_read_b128 v[26:29], v200 offset:34816
	ds_read_b128 v[30:33], v200 offset:35840
	ds_read_b128 v[2:5], v200 offset:49152
	ds_read_b128 v[6:9], v200 offset:50176
	ds_read_b128 v[180:183], v200 offset:51200
	ds_read_b128 v[184:187], v200 offset:52224
	ds_read_b128 v[202:205], v201 offset:32768
	ds_read_b128 v[206:209], v201 offset:33792
	ds_read_b128 v[210:213], v201 offset:34816
	ds_read_b128 v[214:217], v201 offset:35840
	ds_read_b128 v[218:221], v201 offset:36864
	ds_read_b128 v[222:225], v201 offset:37888
	ds_read_b128 v[226:229], v201 offset:38912
	ds_read_b128 v[230:233], v201 offset:39936
	s_waitcnt vmcnt(8)
	s_waitcnt lgkmcnt(0)
	s_setprio 1
	s_barrier
	v_mfma_f32_16x16x128_f8f6f4 v[158:161], v[18:25], v[202:209], v[158:161]
	v_mfma_f32_16x16x128_f8f6f4 v[154:157], v[26:33], v[202:209], v[154:157]
	v_mfma_f32_16x16x128_f8f6f4 v[122:125], v[180:187], v[202:209], v[122:125]
	v_mfma_f32_16x16x128_f8f6f4 v[126:129], v[2:9], v[202:209], v[126:129]
	v_mfma_f32_16x16x128_f8f6f4 v[118:121], v[2:9], v[210:217], v[118:121]
	v_mfma_f32_16x16x128_f8f6f4 v[114:117], v[180:187], v[210:217], v[114:117]
	v_mfma_f32_16x16x128_f8f6f4 v[146:149], v[26:33], v[210:217], v[146:149]
	v_mfma_f32_16x16x128_f8f6f4 v[150:153], v[18:25], v[210:217], v[150:153]
	s_setprio 0
	s_setprio 1
	v_mfma_f32_16x16x128_f8f6f4 v[142:145], v[18:25], v[218:225], v[142:145]
	v_mfma_f32_16x16x128_f8f6f4 v[138:141], v[26:33], v[218:225], v[138:141]
	v_mfma_f32_16x16x128_f8f6f4 v[106:109], v[180:187], v[218:225], v[106:109]
	v_mfma_f32_16x16x128_f8f6f4 v[110:113], v[2:9], v[218:225], v[110:113]
	v_mfma_f32_16x16x128_f8f6f4 v[102:105], v[2:9], v[226:233], v[102:105]
	v_mfma_f32_16x16x128_f8f6f4 v[98:101], v[180:187], v[226:233], v[98:101]
	v_mfma_f32_16x16x128_f8f6f4 v[130:133], v[26:33], v[226:233], v[130:133]
	v_mfma_f32_16x16x128_f8f6f4 v[134:137], v[18:25], v[226:233], v[134:137]
	s_barrier
	s_setprio 0
	s_mov_b32 m0, s87
	v_lshl_add_u64 v[10:11], v[10:11], 0, s[4:5]
	s_add_u32 s54, s54, 0x80080
	global_load_lds_dwordx4 v[10:11], off
	v_lshl_add_u64 v[10:11], v[12:13], 0, s[4:5]
	s_mov_b32 m0, s88
	s_addc_u32 s55, s55, 0
	global_load_lds_dwordx4 v[10:11], off
	v_lshl_add_u64 v[10:11], s[54:55], 0, v[164:165]
	s_mov_b32 m0, s91
	s_nop 0
	global_load_lds_dwordx4 v[10:11], off
	v_lshl_add_u64 v[10:11], s[54:55], 0, v[168:169]
	s_mov_b32 m0, s92
	s_nop 0
	global_load_lds_dwordx4 v[10:11], off
	v_lshl_add_u64 v[10:11], v[14:15], 0, s[4:5]
	s_mov_b32 m0, s89
	s_nop 0
	global_load_lds_dwordx4 v[10:11], off
	v_lshl_add_u64 v[10:11], v[16:17], 0, s[4:5]
	s_mov_b32 m0, s90
	s_nop 0
	global_load_lds_dwordx4 v[10:11], off
	ds_read_b128 v[202:205], v201 offset:49152
	ds_read_b128 v[206:209], v201 offset:50176
	ds_read_b128 v[210:213], v201 offset:51200
	ds_read_b128 v[214:217], v201 offset:52224
	ds_read_b128 v[218:221], v201 offset:53248
	ds_read_b128 v[222:225], v201 offset:54272
	ds_read_b128 v[226:229], v201 offset:55296
	ds_read_b128 v[230:233], v201 offset:56320
	s_waitcnt vmcnt(8)
	s_waitcnt lgkmcnt(0)
	s_setprio 1
	s_barrier
	v_mfma_f32_16x16x128_f8f6f4 v[94:97], v[18:25], v[202:209], v[94:97]
	v_mfma_f32_16x16x128_f8f6f4 v[90:93], v[26:33], v[202:209], v[90:93]
	v_mfma_f32_16x16x128_f8f6f4 v[58:61], v[180:187], v[202:209], v[58:61]
	v_mfma_f32_16x16x128_f8f6f4 v[62:65], v[2:9], v[202:209], v[62:65]
	v_mfma_f32_16x16x128_f8f6f4 v[54:57], v[2:9], v[210:217], v[54:57]
	v_mfma_f32_16x16x128_f8f6f4 v[50:53], v[180:187], v[210:217], v[50:53]
	v_mfma_f32_16x16x128_f8f6f4 v[82:85], v[26:33], v[210:217], v[82:85]
	v_mfma_f32_16x16x128_f8f6f4 v[86:89], v[18:25], v[210:217], v[86:89]
	s_setprio 0
	s_setprio 1
	v_mfma_f32_16x16x128_f8f6f4 v[78:81], v[18:25], v[218:225], v[78:81]
	v_mfma_f32_16x16x128_f8f6f4 v[74:77], v[26:33], v[218:225], v[74:77]
	v_mfma_f32_16x16x128_f8f6f4 v[42:45], v[180:187], v[218:225], v[42:45]
	v_mfma_f32_16x16x128_f8f6f4 v[46:49], v[2:9], v[218:225], v[46:49]
	v_mfma_f32_16x16x128_f8f6f4 v[38:41], v[2:9], v[226:233], v[38:41]
	v_mfma_f32_16x16x128_f8f6f4 v[34:37], v[180:187], v[226:233], v[34:37]
	v_mfma_f32_16x16x128_f8f6f4 v[66:69], v[26:33], v[226:233], v[66:69]
	v_mfma_f32_16x16x128_f8f6f4 v[70:73], v[18:25], v[226:233], v[70:73]
	s_barrier
	s_setprio 0
	s_add_i32 s62, s62, 2
	s_add_u32 s72, s72, 0x100
	s_addc_u32 s73, s73, 0
	s_add_u32 s8, s8, 0x100
	s_addc_u32 s9, s9, 0
	s_cmp_gt_u32 s62, 29
	s_cbranch_scc0 .LBB0_438
	s_and_b64 vcc, exec, s[6:7]
	s_cbranch_vccz .LBB0_441
	s_barrier

.LBB0_452:
	s_add_u32 s8, s52, 0xfff00080
	s_addc_u32 s9, s53, -1
	s_cmp_eq_u32 s91, 28
	s_cselect_b32 s73, s27, s9
	s_cselect_b32 s72, s37, s8
	s_cselect_b32 s55, s39, s90
	s_cselect_b32 s54, s45, s89
	v_lshl_add_u64 v[140:141], s[52:53], 0, v[136:137]
	s_add_i32 m0, s47, 0xc000
	global_load_lds_dwordx4 v[140:141], off
	v_lshl_add_u64 v[140:141], s[52:53], 0, v[138:139]
	s_add_i32 m0, s47, 0xe000
	s_nop 0
	global_load_lds_dwordx4 v[140:141], off
	ds_read_b128 v[146:149], v143
	ds_read_b128 v[150:153], v143 offset:1024
	ds_read_b128 v[154:157], v143 offset:2048
	ds_read_b128 v[158:161], v143 offset:3072
	ds_read_b128 v[162:165], v143 offset:16384
	ds_read_b128 v[166:169], v143 offset:17408
	ds_read_b128 v[170:173], v143 offset:18432
	ds_read_b128 v[174:177], v143 offset:19456
	ds_read_b128 v[180:183], v144
	ds_read_b128 v[184:187], v144 offset:1024
	ds_read_b128 v[188:191], v144 offset:2048
	ds_read_b128 v[192:195], v144 offset:3072
	ds_read_b128 v[196:199], v144 offset:4096
	ds_read_b128 v[200:203], v144 offset:5120
	ds_read_b128 v[204:207], v144 offset:6144
	ds_read_b128 v[208:211], v144 offset:7168
	s_waitcnt vmcnt(8)
	s_waitcnt lgkmcnt(0)
	s_setprio 1
	s_barrier
	v_mfma_f32_16x16x32_bf16 v[126:129], v[146:149], v[180:183], v[126:129]
	v_mfma_f32_16x16x32_bf16 v[122:125], v[154:157], v[180:183], v[122:125]
	v_mfma_f32_16x16x32_bf16 v[118:121], v[146:149], v[188:191], v[118:121]
	v_mfma_f32_16x16x32_bf16 v[114:117], v[154:157], v[188:191], v[114:117]
	v_mfma_f32_16x16x32_bf16 v[110:113], v[146:149], v[196:199], v[110:113]
	v_mfma_f32_16x16x32_bf16 v[106:109], v[154:157], v[196:199], v[106:109]
	v_mfma_f32_16x16x32_bf16 v[102:105], v[146:149], v[204:207], v[102:105]
	v_mfma_f32_16x16x32_bf16 v[98:101], v[154:157], v[204:207], v[98:101]
	v_mfma_f32_16x16x32_bf16 v[126:129], v[150:153], v[184:187], v[126:129]
	v_mfma_f32_16x16x32_bf16 v[122:125], v[158:161], v[184:187], v[122:125]
	v_mfma_f32_16x16x32_bf16 v[118:121], v[150:153], v[192:195], v[118:121]
	v_mfma_f32_16x16x32_bf16 v[114:117], v[158:161], v[192:195], v[114:117]
	v_mfma_f32_16x16x32_bf16 v[110:113], v[150:153], v[200:203], v[110:113]
	v_mfma_f32_16x16x32_bf16 v[106:109], v[158:161], v[200:203], v[106:109]
	v_mfma_f32_16x16x32_bf16 v[102:105], v[150:153], v[208:211], v[102:105]
	v_mfma_f32_16x16x32_bf16 v[98:101], v[158:161], v[208:211], v[98:101]
	s_setprio 0
	s_setprio 1
	v_mfma_f32_16x16x32_bf16 v[90:93], v[162:165], v[180:183], v[90:93]
	v_mfma_f32_16x16x32_bf16 v[82:85], v[170:173], v[180:183], v[82:85]
	v_mfma_f32_16x16x32_bf16 v[74:77], v[162:165], v[188:191], v[74:77]
	v_mfma_f32_16x16x32_bf16 v[66:69], v[170:173], v[188:191], v[66:69]
	v_mfma_f32_16x16x32_bf16 v[58:61], v[162:165], v[196:199], v[58:61]
	v_mfma_f32_16x16x32_bf16 v[50:53], v[170:173], v[196:199], v[50:53]
	v_mfma_f32_16x16x32_bf16 v[42:45], v[162:165], v[204:207], v[42:45]
	v_mfma_f32_16x16x32_bf16 v[34:37], v[170:173], v[204:207], v[34:37]
	v_mfma_f32_16x16x32_bf16 v[90:93], v[166:169], v[184:187], v[90:93]
	v_mfma_f32_16x16x32_bf16 v[82:85], v[174:177], v[184:187], v[82:85]
	v_mfma_f32_16x16x32_bf16 v[74:77], v[166:169], v[192:195], v[74:77]
	v_mfma_f32_16x16x32_bf16 v[66:69], v[174:177], v[192:195], v[66:69]
	v_mfma_f32_16x16x32_bf16 v[58:61], v[166:169], v[200:203], v[58:61]
	v_mfma_f32_16x16x32_bf16 v[50:53], v[174:177], v[200:203], v[50:53]
	v_mfma_f32_16x16x32_bf16 v[42:45], v[166:169], v[208:211], v[42:45]
	v_mfma_f32_16x16x32_bf16 v[34:37], v[174:177], v[208:211], v[34:37]
	s_barrier
	s_setprio 0
	s_mov_b32 m0, s74
	v_lshl_add_u64 v[140:141], s[54:55], 0, v[132:133]
	s_add_u32 s8, s54, 0x100000
	global_load_lds_dwordx4 v[140:141], off
	v_lshl_add_u64 v[212:213], s[54:55], 0, v[130:131]
	s_mov_b32 m0, s75
	s_addc_u32 s9, s55, 0
	global_load_lds_dwordx4 v[212:213], off
	v_lshl_add_u64 v[214:215], s[8:9], 0, v[132:133]
	s_mov_b32 m0, s76
	v_lshl_add_u64 v[216:217], s[72:73], 0, v[130:131]
	global_load_lds_dwordx4 v[214:215], off
	v_lshl_add_u64 v[214:215], s[8:9], 0, v[130:131]
	s_mov_b32 m0, s77
	s_nop 0
	global_load_lds_dwordx4 v[214:215], off
	v_lshl_add_u64 v[214:215], s[72:73], 0, v[132:133]
	s_mov_b32 m0, s47
	s_nop 0
	global_load_lds_dwordx4 v[214:215], off
	s_mov_b32 m0, s78
	s_nop 0
	global_load_lds_dwordx4 v[216:217], off
	ds_read_b128 v[180:183], v144 offset:16384
	ds_read_b128 v[184:187], v144 offset:17408
	ds_read_b128 v[188:191], v144 offset:18432
	ds_read_b128 v[192:195], v144 offset:19456
	ds_read_b128 v[196:199], v144 offset:20480
	ds_read_b128 v[200:203], v144 offset:21504
	ds_read_b128 v[204:207], v144 offset:22528
	ds_read_b128 v[208:211], v144 offset:23552
	s_waitcnt vmcnt(8)
	s_waitcnt lgkmcnt(0)
	s_setprio 1
	s_barrier
	v_mfma_f32_16x16x32_bf16 v[94:97], v[146:149], v[180:183], v[94:97]
	v_mfma_f32_16x16x32_bf16 v[86:89], v[154:157], v[180:183], v[86:89]
	v_mfma_f32_16x16x32_bf16 v[78:81], v[146:149], v[188:191], v[78:81]
	v_mfma_f32_16x16x32_bf16 v[70:73], v[154:157], v[188:191], v[70:73]
	v_mfma_f32_16x16x32_bf16 v[62:65], v[146:149], v[196:199], v[62:65]
	v_mfma_f32_16x16x32_bf16 v[54:57], v[154:157], v[196:199], v[54:57]
	v_mfma_f32_16x16x32_bf16 v[46:49], v[146:149], v[204:207], v[46:49]
	v_mfma_f32_16x16x32_bf16 v[38:41], v[154:157], v[204:207], v[38:41]
	v_mfma_f32_16x16x32_bf16 v[94:97], v[150:153], v[184:187], v[94:97]
	v_mfma_f32_16x16x32_bf16 v[86:89], v[158:161], v[184:187], v[86:89]
	v_mfma_f32_16x16x32_bf16 v[78:81], v[150:153], v[192:195], v[78:81]
	v_mfma_f32_16x16x32_bf16 v[70:73], v[158:161], v[192:195], v[70:73]
	v_mfma_f32_16x16x32_bf16 v[62:65], v[150:153], v[200:203], v[62:65]
	v_mfma_f32_16x16x32_bf16 v[54:57], v[158:161], v[200:203], v[54:57]
	v_mfma_f32_16x16x32_bf16 v[46:49], v[150:153], v[208:211], v[46:49]
	v_mfma_f32_16x16x32_bf16 v[38:41], v[158:161], v[208:211], v[38:41]
	s_setprio 0
	s_setprio 1
	v_mfma_f32_16x16x32_bf16 v[30:33], v[162:165], v[180:183], v[30:33]
	v_mfma_f32_16x16x32_bf16 v[26:29], v[170:173], v[180:183], v[26:29]
	v_mfma_f32_16x16x32_bf16 v[22:25], v[162:165], v[188:191], v[22:25]
	v_mfma_f32_16x16x32_bf16 v[18:21], v[170:173], v[188:191], v[18:21]
	v_mfma_f32_16x16x32_bf16 v[14:17], v[162:165], v[196:199], v[14:17]
	v_mfma_f32_16x16x32_bf16 v[10:13], v[170:173], v[196:199], v[10:13]
	v_mfma_f32_16x16x32_bf16 v[6:9], v[162:165], v[204:207], v[6:9]
	v_mfma_f32_16x16x32_bf16 v[2:5], v[170:173], v[204:207], v[2:5]
	v_mfma_f32_16x16x32_bf16 v[30:33], v[166:169], v[184:187], v[30:33]
	v_mfma_f32_16x16x32_bf16 v[26:29], v[174:177], v[184:187], v[26:29]
	v_mfma_f32_16x16x32_bf16 v[22:25], v[166:169], v[192:195], v[22:25]
	v_mfma_f32_16x16x32_bf16 v[18:21], v[174:177], v[192:195], v[18:21]
	v_mfma_f32_16x16x32_bf16 v[14:17], v[166:169], v[200:203], v[14:17]
	v_mfma_f32_16x16x32_bf16 v[10:13], v[174:177], v[200:203], v[10:13]
	v_mfma_f32_16x16x32_bf16 v[6:9], v[166:169], v[208:211], v[6:9]
	v_mfma_f32_16x16x32_bf16 v[2:5], v[174:177], v[208:211], v[2:5]
	s_barrier
	s_setprio 0
	s_add_u32 s8, s72, 0x100000
	s_addc_u32 s9, s73, 0
	s_mov_b32 m0, s79
	v_lshl_add_u64 v[218:219], s[8:9], 0, v[132:133]
	global_load_lds_dwordx4 v[218:219], off
	v_lshl_add_u64 v[218:219], s[8:9], 0, v[130:131]
	s_mov_b32 m0, s80
	s_nop 0
	global_load_lds_dwordx4 v[218:219], off
	ds_read_b128 v[146:149], v143 offset:32768
	ds_read_b128 v[150:153], v143 offset:33792
	ds_read_b128 v[154:157], v143 offset:34816
	ds_read_b128 v[158:161], v143 offset:35840
	ds_read_b128 v[162:165], v143 offset:49152
	ds_read_b128 v[166:169], v143 offset:50176
	ds_read_b128 v[170:173], v143 offset:51200
	ds_read_b128 v[174:177], v143 offset:52224
	ds_read_b128 v[180:183], v144 offset:32768
	ds_read_b128 v[184:187], v144 offset:33792
	ds_read_b128 v[188:191], v144 offset:34816
	ds_read_b128 v[192:195], v144 offset:35840
	ds_read_b128 v[196:199], v144 offset:36864
	ds_read_b128 v[200:203], v144 offset:37888
	ds_read_b128 v[204:207], v144 offset:38912
	ds_read_b128 v[208:211], v144 offset:39936
	s_waitcnt vmcnt(8)
	s_waitcnt lgkmcnt(0)
	s_setprio 1
	s_barrier
	v_mfma_f32_16x16x32_bf16 v[126:129], v[146:149], v[180:183], v[126:129]
	v_mfma_f32_16x16x32_bf16 v[122:125], v[154:157], v[180:183], v[122:125]
	v_mfma_f32_16x16x32_bf16 v[118:121], v[146:149], v[188:191], v[118:121]
	v_mfma_f32_16x16x32_bf16 v[114:117], v[154:157], v[188:191], v[114:117]
	v_mfma_f32_16x16x32_bf16 v[110:113], v[146:149], v[196:199], v[110:113]
	v_mfma_f32_16x16x32_bf16 v[106:109], v[154:157], v[196:199], v[106:109]
	v_mfma_f32_16x16x32_bf16 v[102:105], v[146:149], v[204:207], v[102:105]
	v_mfma_f32_16x16x32_bf16 v[98:101], v[154:157], v[204:207], v[98:101]
	v_mfma_f32_16x16x32_bf16 v[126:129], v[150:153], v[184:187], v[126:129]
	v_mfma_f32_16x16x32_bf16 v[122:125], v[158:161], v[184:187], v[122:125]
	v_mfma_f32_16x16x32_bf16 v[118:121], v[150:153], v[192:195], v[118:121]
	v_mfma_f32_16x16x32_bf16 v[114:117], v[158:161], v[192:195], v[114:117]
	v_mfma_f32_16x16x32_bf16 v[110:113], v[150:153], v[200:203], v[110:113]
	v_mfma_f32_16x16x32_bf16 v[106:109], v[158:161], v[200:203], v[106:109]
	v_mfma_f32_16x16x32_bf16 v[102:105], v[150:153], v[208:211], v[102:105]
	v_mfma_f32_16x16x32_bf16 v[98:101], v[158:161], v[208:211], v[98:101]
	s_setprio 0
	s_setprio 1
	v_mfma_f32_16x16x32_bf16 v[90:93], v[162:165], v[180:183], v[90:93]
	v_mfma_f32_16x16x32_bf16 v[82:85], v[170:173], v[180:183], v[82:85]
	v_mfma_f32_16x16x32_bf16 v[74:77], v[162:165], v[188:191], v[74:77]
	v_mfma_f32_16x16x32_bf16 v[66:69], v[170:173], v[188:191], v[66:69]
	v_mfma_f32_16x16x32_bf16 v[58:61], v[162:165], v[196:199], v[58:61]
	v_mfma_f32_16x16x32_bf16 v[50:53], v[170:173], v[196:199], v[50:53]
	v_mfma_f32_16x16x32_bf16 v[42:45], v[162:165], v[204:207], v[42:45]
	v_mfma_f32_16x16x32_bf16 v[34:37], v[170:173], v[204:207], v[34:37]
	v_mfma_f32_16x16x32_bf16 v[90:93], v[166:169], v[184:187], v[90:93]
	v_mfma_f32_16x16x32_bf16 v[82:85], v[174:177], v[184:187], v[82:85]
	v_mfma_f32_16x16x32_bf16 v[74:77], v[166:169], v[192:195], v[74:77]
	v_mfma_f32_16x16x32_bf16 v[66:69], v[174:177], v[192:195], v[66:69]
	v_mfma_f32_16x16x32_bf16 v[58:61], v[166:169], v[200:203], v[58:61]
	v_mfma_f32_16x16x32_bf16 v[50:53], v[174:177], v[200:203], v[50:53]
	v_mfma_f32_16x16x32_bf16 v[42:45], v[166:169], v[208:211], v[42:45]
	v_mfma_f32_16x16x32_bf16 v[34:37], v[174:177], v[208:211], v[34:37]
	s_barrier
	s_setprio 0
	s_mov_b32 m0, s81
	v_lshl_add_u64 v[140:141], v[140:141], 0, s[4:5]
	s_add_u32 s8, s54, 0x100080
	global_load_lds_dwordx4 v[140:141], off
	v_lshl_add_u64 v[140:141], v[212:213], 0, s[4:5]
	s_mov_b32 m0, s82
	s_addc_u32 s9, s55, 0
	global_load_lds_dwordx4 v[140:141], off
	v_lshl_add_u64 v[140:141], s[8:9], 0, v[132:133]
	s_mov_b32 m0, s85
	s_nop 0
	global_load_lds_dwordx4 v[140:141], off
	v_lshl_add_u64 v[140:141], s[8:9], 0, v[130:131]
	s_mov_b32 m0, s86
	s_nop 0
	global_load_lds_dwordx4 v[140:141], off
	v_lshl_add_u64 v[140:141], v[214:215], 0, s[4:5]
	s_mov_b32 m0, s83
	s_nop 0
	global_load_lds_dwordx4 v[140:141], off
	v_lshl_add_u64 v[140:141], v[216:217], 0, s[4:5]
	s_mov_b32 m0, s84
	s_nop 0
	global_load_lds_dwordx4 v[140:141], off
	ds_read_b128 v[180:183], v144 offset:49152
	ds_read_b128 v[184:187], v144 offset:50176
	ds_read_b128 v[188:191], v144 offset:51200
	ds_read_b128 v[192:195], v144 offset:52224
	ds_read_b128 v[196:199], v144 offset:53248
	ds_read_b128 v[200:203], v144 offset:54272
	ds_read_b128 v[204:207], v144 offset:55296
	ds_read_b128 v[208:211], v144 offset:56320
	s_waitcnt vmcnt(8)
	s_waitcnt lgkmcnt(0)
	s_setprio 1
	s_barrier
	v_mfma_f32_16x16x32_bf16 v[94:97], v[146:149], v[180:183], v[94:97]
	v_mfma_f32_16x16x32_bf16 v[86:89], v[154:157], v[180:183], v[86:89]
	v_mfma_f32_16x16x32_bf16 v[78:81], v[146:149], v[188:191], v[78:81]
	v_mfma_f32_16x16x32_bf16 v[70:73], v[154:157], v[188:191], v[70:73]
	v_mfma_f32_16x16x32_bf16 v[62:65], v[146:149], v[196:199], v[62:65]
	v_mfma_f32_16x16x32_bf16 v[54:57], v[154:157], v[196:199], v[54:57]
	v_mfma_f32_16x16x32_bf16 v[46:49], v[146:149], v[204:207], v[46:49]
	v_mfma_f32_16x16x32_bf16 v[38:41], v[154:157], v[204:207], v[38:41]
	v_mfma_f32_16x16x32_bf16 v[94:97], v[150:153], v[184:187], v[94:97]
	v_mfma_f32_16x16x32_bf16 v[86:89], v[158:161], v[184:187], v[86:89]
	v_mfma_f32_16x16x32_bf16 v[78:81], v[150:153], v[192:195], v[78:81]
	v_mfma_f32_16x16x32_bf16 v[70:73], v[158:161], v[192:195], v[70:73]
	v_mfma_f32_16x16x32_bf16 v[62:65], v[150:153], v[200:203], v[62:65]
	v_mfma_f32_16x16x32_bf16 v[54:57], v[158:161], v[200:203], v[54:57]
	v_mfma_f32_16x16x32_bf16 v[46:49], v[150:153], v[208:211], v[46:49]
	v_mfma_f32_16x16x32_bf16 v[38:41], v[158:161], v[208:211], v[38:41]
	s_setprio 0
	s_setprio 1
	v_mfma_f32_16x16x32_bf16 v[30:33], v[162:165], v[180:183], v[30:33]
	v_mfma_f32_16x16x32_bf16 v[26:29], v[170:173], v[180:183], v[26:29]
	v_mfma_f32_16x16x32_bf16 v[22:25], v[162:165], v[188:191], v[22:25]
	v_mfma_f32_16x16x32_bf16 v[18:21], v[170:173], v[188:191], v[18:21]
	v_mfma_f32_16x16x32_bf16 v[14:17], v[162:165], v[196:199], v[14:17]
	v_mfma_f32_16x16x32_bf16 v[10:13], v[170:173], v[196:199], v[10:13]
	v_mfma_f32_16x16x32_bf16 v[6:9], v[162:165], v[204:207], v[6:9]
	v_mfma_f32_16x16x32_bf16 v[2:5], v[170:173], v[204:207], v[2:5]
	v_mfma_f32_16x16x32_bf16 v[30:33], v[166:169], v[184:187], v[30:33]
	v_mfma_f32_16x16x32_bf16 v[26:29], v[174:177], v[184:187], v[26:29]
	v_mfma_f32_16x16x32_bf16 v[22:25], v[166:169], v[192:195], v[22:25]
	v_mfma_f32_16x16x32_bf16 v[18:21], v[174:177], v[192:195], v[18:21]
	v_mfma_f32_16x16x32_bf16 v[14:17], v[166:169], v[200:203], v[14:17]
	v_mfma_f32_16x16x32_bf16 v[10:13], v[174:177], v[200:203], v[10:13]
	v_mfma_f32_16x16x32_bf16 v[6:9], v[166:169], v[208:211], v[6:9]
	v_mfma_f32_16x16x32_bf16 v[2:5], v[174:177], v[208:211], v[2:5]
	s_barrier
	s_setprio 0
	s_add_i32 s91, s91, 2
	s_add_u32 s52, s52, 0x100
	s_addc_u32 s53, s53, 0
	s_add_u32 s89, s89, 0x100
	s_addc_u32 s90, s90, 0
	s_cmp_gt_u32 s91, 29
	s_cbranch_scc0 .LBB0_452
	s_and_b64 vcc, exec, s[6:7]
	s_cbranch_vccz .LBB0_455
	s_barrier

.LBB0_600:
	s_ashr_i32 s55, s54, 31
	ds_read_b128 v[18:21], v200
	ds_read_b128 v[22:25], v200 offset:1024
	ds_read_b128 v[26:29], v200 offset:2048
	ds_read_b128 v[30:33], v200 offset:3072
	ds_read_b128 v[2:5], v200 offset:16384
	ds_read_b128 v[6:9], v200 offset:17408
	ds_read_b128 v[10:13], v200 offset:18432
	ds_read_b128 v[14:17], v200 offset:19456
	s_lshl_b64 s[4:5], s[54:55], 18
	s_add_u32 s72, s38, s4
	s_addc_u32 s73, s39, s5
	s_and_b64 s[4:5], s[2:3], exec
	s_cselect_b32 s4, s73, s81
	s_cselect_b32 s5, s72, s80
	s_ashr_i32 s53, s52, 31
	s_lshl_b64 s[8:9], s[52:53], 18
	s_add_u32 s74, s94, s8
	v_readlane_b32 s8, v254, 6
	s_addc_u32 s75, s8, s9
	s_and_b64 s[8:9], s[2:3], exec
	s_cselect_b32 s53, s75, s79
	s_cselect_b32 s55, s74, s78
	s_add_u32 s8, s80, 0x20080
	s_addc_u32 s9, s81, 0
	s_mov_b32 m0, s96
	v_lshl_add_u64 v[226:227], s[8:9], 0, v[162:163]
	ds_read_b128 v[182:185], v201
	ds_read_b128 v[186:189], v201 offset:1024
	ds_read_b128 v[202:205], v201 offset:2048
	ds_read_b128 v[206:209], v201 offset:3072
	ds_read_b128 v[210:213], v201 offset:4096
	ds_read_b128 v[214:217], v201 offset:5120
	ds_read_b128 v[218:221], v201 offset:6144
	ds_read_b128 v[222:225], v201 offset:7168
	global_load_lds_dwordx4 v[226:227], off
	v_lshl_add_u64 v[226:227], s[8:9], 0, v[166:167]
	s_mov_b32 m0, s61
	s_nop 0
	global_load_lds_dwordx4 v[226:227], off
	s_waitcnt vmcnt(8)
	s_waitcnt lgkmcnt(0)
	s_setprio 1
	s_barrier
	v_mfma_f32_16x16x128_f8f6f4 v[158:161], v[18:25], v[182:189], 0
	v_mfma_f32_16x16x128_f8f6f4 v[154:157], v[26:33], v[182:189], 0
	v_mfma_f32_16x16x128_f8f6f4 v[122:125], v[10:17], v[182:189], 0
	v_mfma_f32_16x16x128_f8f6f4 v[126:129], v[2:9], v[182:189], 0
	v_mfma_f32_16x16x128_f8f6f4 v[118:121], v[2:9], v[202:209], 0
	v_mfma_f32_16x16x128_f8f6f4 v[114:117], v[10:17], v[202:209], 0
	v_mfma_f32_16x16x128_f8f6f4 v[146:149], v[26:33], v[202:209], 0
	v_mfma_f32_16x16x128_f8f6f4 v[150:153], v[18:25], v[202:209], 0
	s_setprio 0
	s_setprio 1
	v_mfma_f32_16x16x128_f8f6f4 v[142:145], v[18:25], v[210:217], 0
	v_mfma_f32_16x16x128_f8f6f4 v[138:141], v[26:33], v[210:217], 0
	v_mfma_f32_16x16x128_f8f6f4 v[106:109], v[10:17], v[210:217], 0
	v_mfma_f32_16x16x128_f8f6f4 v[110:113], v[2:9], v[210:217], 0
	v_mfma_f32_16x16x128_f8f6f4 v[102:105], v[2:9], v[218:225], 0
	v_mfma_f32_16x16x128_f8f6f4 v[98:101], v[10:17], v[218:225], 0
	v_mfma_f32_16x16x128_f8f6f4 v[130:133], v[26:33], v[218:225], 0
	v_mfma_f32_16x16x128_f8f6f4 v[134:137], v[18:25], v[218:225], 0
	s_barrier
	s_setprio 0
	v_lshl_add_u64 v[182:183], s[78:79], 0, v[164:165]
	s_mov_b32 m0, s68
	v_lshl_add_u64 v[184:185], v[182:183], 0, s[46:47]
	global_load_lds_dwordx4 v[184:185], off
	v_lshl_add_u64 v[184:185], s[78:79], 0, v[168:169]
	s_add_u32 s8, s78, 0x20100
	v_lshl_add_u64 v[186:187], v[184:185], 0, s[46:47]
	s_mov_b32 m0, s69
	s_addc_u32 s9, s79, 0
	global_load_lds_dwordx4 v[186:187], off
	v_lshl_add_u64 v[186:187], s[8:9], 0, v[164:165]
	s_mov_b32 m0, s77
	s_nop 0
	global_load_lds_dwordx4 v[186:187], off
	v_lshl_add_u64 v[186:187], s[8:9], 0, v[168:169]
	s_mov_b32 m0, s84
	s_nop 0
	global_load_lds_dwordx4 v[186:187], off
	v_lshl_add_u64 v[186:187], s[80:81], 0, v[162:163]
	v_lshl_add_u64 v[188:189], v[186:187], 0, s[46:47]
	s_mov_b32 m0, s33
	s_nop 0
	global_load_lds_dwordx4 v[188:189], off
	v_lshl_add_u64 v[188:189], s[80:81], 0, v[166:167]
	v_lshl_add_u64 v[234:235], v[188:189], 0, s[46:47]
	s_mov_b32 m0, s85
	s_nop 0
	global_load_lds_dwordx4 v[234:235], off
	ds_read_b128 v[202:205], v201 offset:16384
	ds_read_b128 v[206:209], v201 offset:17408
	ds_read_b128 v[210:213], v201 offset:18432
	ds_read_b128 v[214:217], v201 offset:19456
	ds_read_b128 v[218:221], v201 offset:20480
	ds_read_b128 v[222:225], v201 offset:21504
	ds_read_b128 v[226:229], v201 offset:22528
	ds_read_b128 v[230:233], v201 offset:23552
	s_waitcnt vmcnt(8)
	s_waitcnt lgkmcnt(0)
	s_setprio 1
	s_barrier
	v_mfma_f32_16x16x128_f8f6f4 v[94:97], v[18:25], v[202:209], 0
	v_mfma_f32_16x16x128_f8f6f4 v[90:93], v[26:33], v[202:209], 0
	v_mfma_f32_16x16x128_f8f6f4 v[58:61], v[10:17], v[202:209], 0
	v_mfma_f32_16x16x128_f8f6f4 v[62:65], v[2:9], v[202:209], 0
	v_mfma_f32_16x16x128_f8f6f4 v[54:57], v[2:9], v[210:217], 0
	v_mfma_f32_16x16x128_f8f6f4 v[50:53], v[10:17], v[210:217], 0
	v_mfma_f32_16x16x128_f8f6f4 v[82:85], v[26:33], v[210:217], 0
	v_mfma_f32_16x16x128_f8f6f4 v[86:89], v[18:25], v[210:217], 0
	s_setprio 0
	s_setprio 1
	v_mfma_f32_16x16x128_f8f6f4 v[78:81], v[18:25], v[218:225], 0
	v_mfma_f32_16x16x128_f8f6f4 v[74:77], v[26:33], v[218:225], 0
	v_mfma_f32_16x16x128_f8f6f4 v[42:45], v[10:17], v[218:225], 0
	v_mfma_f32_16x16x128_f8f6f4 v[46:49], v[2:9], v[218:225], 0
	v_mfma_f32_16x16x128_f8f6f4 v[38:41], v[2:9], v[226:233], 0
	v_mfma_f32_16x16x128_f8f6f4 v[34:37], v[10:17], v[226:233], 0
	v_mfma_f32_16x16x128_f8f6f4 v[66:69], v[26:33], v[226:233], 0
	v_mfma_f32_16x16x128_f8f6f4 v[70:73], v[18:25], v[226:233], 0
	s_barrier
	s_setprio 0
	s_add_u32 s8, s80, 0x20100
	s_addc_u32 s9, s81, 0
	s_mov_b32 m0, s86
	v_lshl_add_u64 v[234:235], s[8:9], 0, v[162:163]
	global_load_lds_dwordx4 v[234:235], off
	v_lshl_add_u64 v[234:235], s[8:9], 0, v[166:167]
	s_mov_b32 m0, s87
	s_nop 0
	global_load_lds_dwordx4 v[234:235], off
	ds_read_b128 v[18:21], v200 offset:32768
	ds_read_b128 v[22:25], v200 offset:33792
	ds_read_b128 v[26:29], v200 offset:34816
	ds_read_b128 v[30:33], v200 offset:35840
	ds_read_b128 v[2:5], v200 offset:49152
	ds_read_b128 v[6:9], v200 offset:50176
	ds_read_b128 v[10:13], v200 offset:51200
	ds_read_b128 v[14:17], v200 offset:52224
	ds_read_b128 v[202:205], v201 offset:32768
	ds_read_b128 v[206:209], v201 offset:33792
	ds_read_b128 v[210:213], v201 offset:34816
	ds_read_b128 v[214:217], v201 offset:35840
	ds_read_b128 v[218:221], v201 offset:36864
	ds_read_b128 v[222:225], v201 offset:37888
	ds_read_b128 v[226:229], v201 offset:38912
	ds_read_b128 v[230:233], v201 offset:39936
	s_waitcnt vmcnt(8)
	s_waitcnt lgkmcnt(0)
	s_setprio 1
	s_barrier
	v_mfma_f32_16x16x128_f8f6f4 v[158:161], v[18:25], v[202:209], v[158:161]
	v_mfma_f32_16x16x128_f8f6f4 v[154:157], v[26:33], v[202:209], v[154:157]
	v_mfma_f32_16x16x128_f8f6f4 v[122:125], v[10:17], v[202:209], v[122:125]
	v_mfma_f32_16x16x128_f8f6f4 v[126:129], v[2:9], v[202:209], v[126:129]
	v_mfma_f32_16x16x128_f8f6f4 v[118:121], v[2:9], v[210:217], v[118:121]
	v_mfma_f32_16x16x128_f8f6f4 v[114:117], v[10:17], v[210:217], v[114:117]
	v_mfma_f32_16x16x128_f8f6f4 v[146:149], v[26:33], v[210:217], v[146:149]
	v_mfma_f32_16x16x128_f8f6f4 v[150:153], v[18:25], v[210:217], v[150:153]
	s_setprio 0
	s_setprio 1
	v_mfma_f32_16x16x128_f8f6f4 v[142:145], v[18:25], v[218:225], v[142:145]
	v_mfma_f32_16x16x128_f8f6f4 v[138:141], v[26:33], v[218:225], v[138:141]
	v_mfma_f32_16x16x128_f8f6f4 v[106:109], v[10:17], v[218:225], v[106:109]
	v_mfma_f32_16x16x128_f8f6f4 v[110:113], v[2:9], v[218:225], v[110:113]
	v_mfma_f32_16x16x128_f8f6f4 v[102:105], v[2:9], v[226:233], v[102:105]
	v_mfma_f32_16x16x128_f8f6f4 v[98:101], v[10:17], v[226:233], v[98:101]
	v_mfma_f32_16x16x128_f8f6f4 v[130:133], v[26:33], v[226:233], v[130:133]
	v_mfma_f32_16x16x128_f8f6f4 v[134:137], v[18:25], v[226:233], v[134:137]
	s_barrier
	s_setprio 0
	s_mov_b32 m0, s89
	v_lshl_add_u64 v[182:183], v[182:183], 0, s[48:49]
	s_add_u32 s8, s78, 0x20180
	global_load_lds_dwordx4 v[182:183], off
	v_lshl_add_u64 v[182:183], v[184:185], 0, s[48:49]
	s_mov_b32 m0, s90
	s_addc_u32 s9, s79, 0
	global_load_lds_dwordx4 v[182:183], off
	v_lshl_add_u64 v[182:183], s[8:9], 0, v[164:165]
	s_mov_b32 m0, s93
	s_nop 0
	global_load_lds_dwordx4 v[182:183], off
	v_lshl_add_u64 v[182:183], s[8:9], 0, v[168:169]
	s_mov_b32 m0, s95
	s_nop 0
	global_load_lds_dwordx4 v[182:183], off
	v_lshl_add_u64 v[182:183], v[186:187], 0, s[48:49]
	s_mov_b32 m0, s91
	s_nop 0
	global_load_lds_dwordx4 v[182:183], off
	v_lshl_add_u64 v[182:183], v[188:189], 0, s[48:49]
	s_mov_b32 m0, s92
	s_nop 0
	global_load_lds_dwordx4 v[182:183], off
	ds_read_b128 v[202:205], v201 offset:49152
	ds_read_b128 v[206:209], v201 offset:50176
	ds_read_b128 v[210:213], v201 offset:51200
	ds_read_b128 v[214:217], v201 offset:52224
	ds_read_b128 v[218:221], v201 offset:53248
	ds_read_b128 v[222:225], v201 offset:54272
	ds_read_b128 v[226:229], v201 offset:55296
	ds_read_b128 v[230:233], v201 offset:56320
	s_waitcnt vmcnt(8)
	s_waitcnt lgkmcnt(0)
	s_setprio 1
	s_barrier
	v_mfma_f32_16x16x128_f8f6f4 v[94:97], v[18:25], v[202:209], v[94:97]
	v_mfma_f32_16x16x128_f8f6f4 v[90:93], v[26:33], v[202:209], v[90:93]
	v_mfma_f32_16x16x128_f8f6f4 v[58:61], v[10:17], v[202:209], v[58:61]
	v_mfma_f32_16x16x128_f8f6f4 v[62:65], v[2:9], v[202:209], v[62:65]
	v_mfma_f32_16x16x128_f8f6f4 v[54:57], v[2:9], v[210:217], v[54:57]
	v_mfma_f32_16x16x128_f8f6f4 v[50:53], v[10:17], v[210:217], v[50:53]
	v_mfma_f32_16x16x128_f8f6f4 v[82:85], v[26:33], v[210:217], v[82:85]
	v_mfma_f32_16x16x128_f8f6f4 v[86:89], v[18:25], v[210:217], v[86:89]
	s_setprio 0
	s_setprio 1
	v_mfma_f32_16x16x128_f8f6f4 v[78:81], v[18:25], v[218:225], v[78:81]
	v_mfma_f32_16x16x128_f8f6f4 v[74:77], v[26:33], v[218:225], v[74:77]
	v_mfma_f32_16x16x128_f8f6f4 v[42:45], v[10:17], v[218:225], v[42:45]
	v_mfma_f32_16x16x128_f8f6f4 v[46:49], v[2:9], v[218:225], v[46:49]
	v_mfma_f32_16x16x128_f8f6f4 v[38:41], v[2:9], v[226:233], v[38:41]
	v_mfma_f32_16x16x128_f8f6f4 v[34:37], v[10:17], v[226:233], v[34:37]
	v_mfma_f32_16x16x128_f8f6f4 v[66:69], v[26:33], v[226:233], v[66:69]
	v_mfma_f32_16x16x128_f8f6f4 v[70:73], v[18:25], v[226:233], v[70:73]
	s_barrier
	s_setprio 0
	s_add_u32 s80, s80, 0x20180
	s_addc_u32 s81, s81, 0
	s_add_u32 s8, s78, 0x200
	s_addc_u32 s9, s79, 0
	s_mov_b32 s62, 0
.LBB0_601:
	s_add_u32 s63, s80, 0xfffe0080
	s_addc_u32 s71, s81, -1
	s_cmp_eq_u32 s62, 4
	s_cselect_b32 s83, s4, s71
	s_cselect_b32 s82, s5, s63
	s_cselect_b32 s79, s53, s9
	s_cselect_b32 s78, s55, s8
	s_mov_b32 m0, s96
	v_lshl_add_u64 v[226:227], s[80:81], 0, v[170:171]
	global_load_lds_dwordx4 v[226:227], off
	v_lshl_add_u64 v[226:227], s[80:81], 0, v[172:173]
	s_mov_b32 m0, s61
	s_nop 0
	global_load_lds_dwordx4 v[226:227], off
	ds_read_b128 v[2:5], v200
	ds_read_b128 v[6:9], v200 offset:1024
	ds_read_b128 v[18:21], v200 offset:2048
	ds_read_b128 v[22:25], v200 offset:3072
	ds_read_b128 v[26:29], v200 offset:16384
	ds_read_b128 v[30:33], v200 offset:17408
	ds_read_b128 v[182:185], v200 offset:18432
	ds_read_b128 v[186:189], v200 offset:19456
	ds_read_b128 v[10:13], v201
	ds_read_b128 v[14:17], v201 offset:1024
	ds_read_b128 v[202:205], v201 offset:2048
	ds_read_b128 v[206:209], v201 offset:3072
	ds_read_b128 v[210:213], v201 offset:4096
	ds_read_b128 v[214:217], v201 offset:5120
	ds_read_b128 v[218:221], v201 offset:6144
	ds_read_b128 v[222:225], v201 offset:7168
	s_waitcnt vmcnt(8)
	s_waitcnt lgkmcnt(0)
	s_setprio 1
	s_barrier
	v_mfma_f32_16x16x128_f8f6f4 v[158:161], v[2:9], v[10:17], v[158:161]
	v_mfma_f32_16x16x128_f8f6f4 v[154:157], v[18:25], v[10:17], v[154:157]
	v_mfma_f32_16x16x128_f8f6f4 v[122:125], v[182:189], v[10:17], v[122:125]
	v_mfma_f32_16x16x128_f8f6f4 v[126:129], v[26:33], v[10:17], v[126:129]
	v_mfma_f32_16x16x128_f8f6f4 v[118:121], v[26:33], v[202:209], v[118:121]
	v_mfma_f32_16x16x128_f8f6f4 v[114:117], v[182:189], v[202:209], v[114:117]
	v_mfma_f32_16x16x128_f8f6f4 v[146:149], v[18:25], v[202:209], v[146:149]
	v_mfma_f32_16x16x128_f8f6f4 v[150:153], v[2:9], v[202:209], v[150:153]
	s_setprio 0
	s_setprio 1
	v_mfma_f32_16x16x128_f8f6f4 v[142:145], v[2:9], v[210:217], v[142:145]
	v_mfma_f32_16x16x128_f8f6f4 v[138:141], v[18:25], v[210:217], v[138:141]
	v_mfma_f32_16x16x128_f8f6f4 v[106:109], v[182:189], v[210:217], v[106:109]
	v_mfma_f32_16x16x128_f8f6f4 v[110:113], v[26:33], v[210:217], v[110:113]
	v_mfma_f32_16x16x128_f8f6f4 v[102:105], v[26:33], v[218:225], v[102:105]
	v_mfma_f32_16x16x128_f8f6f4 v[98:101], v[182:189], v[218:225], v[98:101]
	v_mfma_f32_16x16x128_f8f6f4 v[130:133], v[18:25], v[218:225], v[130:133]
	v_mfma_f32_16x16x128_f8f6f4 v[134:137], v[2:9], v[218:225], v[134:137]
	s_barrier
	s_setprio 0
	s_mov_b32 m0, s68
	v_lshl_add_u64 v[10:11], s[78:79], 0, v[164:165]
	s_add_u32 vcc_lo, s78, 0x20000
	global_load_lds_dwordx4 v[10:11], off
	v_lshl_add_u64 v[12:13], s[78:79], 0, v[168:169]
	s_mov_b32 m0, s69
	s_addc_u32 vcc_hi, s79, 0
	global_load_lds_dwordx4 v[12:13], off
	v_lshl_add_u64 v[14:15], vcc, 0, v[164:165]
	s_mov_b32 m0, s77
	v_lshl_add_u64 v[16:17], s[82:83], 0, v[166:167]
	global_load_lds_dwordx4 v[14:15], off
	v_lshl_add_u64 v[14:15], vcc, 0, v[168:169]
	s_mov_b32 m0, s84
	s_nop 0
	global_load_lds_dwordx4 v[14:15], off
	v_lshl_add_u64 v[14:15], s[82:83], 0, v[162:163]
	s_mov_b32 m0, s33
	s_nop 0
	global_load_lds_dwordx4 v[14:15], off
	s_mov_b32 m0, s85
	s_nop 0
	global_load_lds_dwordx4 v[16:17], off
	ds_read_b128 v[202:205], v201 offset:16384
	ds_read_b128 v[206:209], v201 offset:17408
	ds_read_b128 v[210:213], v201 offset:18432
	ds_read_b128 v[214:217], v201 offset:19456
	ds_read_b128 v[218:221], v201 offset:20480
	ds_read_b128 v[222:225], v201 offset:21504
	ds_read_b128 v[226:229], v201 offset:22528
	ds_read_b128 v[230:233], v201 offset:23552
	s_waitcnt vmcnt(8)
	s_waitcnt lgkmcnt(0)
	s_setprio 1
	s_barrier
	v_mfma_f32_16x16x128_f8f6f4 v[94:97], v[2:9], v[202:209], v[94:97]
	v_mfma_f32_16x16x128_f8f6f4 v[90:93], v[18:25], v[202:209], v[90:93]
	v_mfma_f32_16x16x128_f8f6f4 v[58:61], v[182:189], v[202:209], v[58:61]
	v_mfma_f32_16x16x128_f8f6f4 v[62:65], v[26:33], v[202:209], v[62:65]
	v_mfma_f32_16x16x128_f8f6f4 v[54:57], v[26:33], v[210:217], v[54:57]
	v_mfma_f32_16x16x128_f8f6f4 v[50:53], v[182:189], v[210:217], v[50:53]
	v_mfma_f32_16x16x128_f8f6f4 v[82:85], v[18:25], v[210:217], v[82:85]
	v_mfma_f32_16x16x128_f8f6f4 v[86:89], v[2:9], v[210:217], v[86:89]
	s_setprio 0
	s_setprio 1
	v_mfma_f32_16x16x128_f8f6f4 v[78:81], v[2:9], v[218:225], v[78:81]
	v_mfma_f32_16x16x128_f8f6f4 v[74:77], v[18:25], v[218:225], v[74:77]
	v_mfma_f32_16x16x128_f8f6f4 v[42:45], v[182:189], v[218:225], v[42:45]
	v_mfma_f32_16x16x128_f8f6f4 v[46:49], v[26:33], v[218:225], v[46:49]
	v_mfma_f32_16x16x128_f8f6f4 v[38:41], v[26:33], v[226:233], v[38:41]
	v_mfma_f32_16x16x128_f8f6f4 v[34:37], v[182:189], v[226:233], v[34:37]
	v_mfma_f32_16x16x128_f8f6f4 v[66:69], v[18:25], v[226:233], v[66:69]
	v_mfma_f32_16x16x128_f8f6f4 v[70:73], v[2:9], v[226:233], v[70:73]
	s_barrier
	s_setprio 0
	s_add_u32 s82, s82, 0x20000
	s_addc_u32 s83, s83, 0
	s_mov_b32 m0, s86
	v_lshl_add_u64 v[234:235], s[82:83], 0, v[162:163]
	global_load_lds_dwordx4 v[234:235], off
	v_lshl_add_u64 v[234:235], s[82:83], 0, v[166:167]
	s_mov_b32 m0, s87
	s_nop 0
	global_load_lds_dwordx4 v[234:235], off
	ds_read_b128 v[18:21], v200 offset:32768
	ds_read_b128 v[22:25], v200 offset:33792
	ds_read_b128 v[26:29], v200 offset:34816
	ds_read_b128 v[30:33], v200 offset:35840
	ds_read_b128 v[2:5], v200 offset:49152
	ds_read_b128 v[6:9], v200 offset:50176
	ds_read_b128 v[182:185], v200 offset:51200
	ds_read_b128 v[186:189], v200 offset:52224
	ds_read_b128 v[202:205], v201 offset:32768
	ds_read_b128 v[206:209], v201 offset:33792
	ds_read_b128 v[210:213], v201 offset:34816
	ds_read_b128 v[214:217], v201 offset:35840
	ds_read_b128 v[218:221], v201 offset:36864
	ds_read_b128 v[222:225], v201 offset:37888
	ds_read_b128 v[226:229], v201 offset:38912
	ds_read_b128 v[230:233], v201 offset:39936
	s_waitcnt vmcnt(8)
	s_waitcnt lgkmcnt(0)
	s_setprio 1
	s_barrier
	v_mfma_f32_16x16x128_f8f6f4 v[158:161], v[18:25], v[202:209], v[158:161]
	v_mfma_f32_16x16x128_f8f6f4 v[154:157], v[26:33], v[202:209], v[154:157]
	v_mfma_f32_16x16x128_f8f6f4 v[122:125], v[182:189], v[202:209], v[122:125]
	v_mfma_f32_16x16x128_f8f6f4 v[126:129], v[2:9], v[202:209], v[126:129]
	v_mfma_f32_16x16x128_f8f6f4 v[118:121], v[2:9], v[210:217], v[118:121]
	v_mfma_f32_16x16x128_f8f6f4 v[114:117], v[182:189], v[210:217], v[114:117]
	v_mfma_f32_16x16x128_f8f6f4 v[146:149], v[26:33], v[210:217], v[146:149]
	v_mfma_f32_16x16x128_f8f6f4 v[150:153], v[18:25], v[210:217], v[150:153]
	s_setprio 0
	s_setprio 1
	v_mfma_f32_16x16x128_f8f6f4 v[142:145], v[18:25], v[218:225], v[142:145]
	v_mfma_f32_16x16x128_f8f6f4 v[138:141], v[26:33], v[218:225], v[138:141]
	v_mfma_f32_16x16x128_f8f6f4 v[106:109], v[182:189], v[218:225], v[106:109]
	v_mfma_f32_16x16x128_f8f6f4 v[110:113], v[2:9], v[218:225], v[110:113]
	v_mfma_f32_16x16x128_f8f6f4 v[102:105], v[2:9], v[226:233], v[102:105]
	v_mfma_f32_16x16x128_f8f6f4 v[98:101], v[182:189], v[226:233], v[98:101]
	v_mfma_f32_16x16x128_f8f6f4 v[130:133], v[26:33], v[226:233], v[130:133]
	v_mfma_f32_16x16x128_f8f6f4 v[134:137], v[18:25], v[226:233], v[134:137]
	s_barrier
	s_setprio 0
	s_mov_b32 m0, s89
	v_lshl_add_u64 v[10:11], v[10:11], 0, s[42:43]
	s_add_u32 s78, s78, 0x20080
	global_load_lds_dwordx4 v[10:11], off
	v_lshl_add_u64 v[10:11], v[12:13], 0, s[42:43]
	s_mov_b32 m0, s90
	s_addc_u32 s79, s79, 0
	global_load_lds_dwordx4 v[10:11], off
	v_lshl_add_u64 v[10:11], s[78:79], 0, v[164:165]
	s_mov_b32 m0, s93
	s_nop 0
	global_load_lds_dwordx4 v[10:11], off
	v_lshl_add_u64 v[10:11], s[78:79], 0, v[168:169]
	s_mov_b32 m0, s95
	s_nop 0
	global_load_lds_dwordx4 v[10:11], off
	v_lshl_add_u64 v[10:11], v[14:15], 0, s[42:43]
	s_mov_b32 m0, s91
	s_nop 0
	global_load_lds_dwordx4 v[10:11], off
	v_lshl_add_u64 v[10:11], v[16:17], 0, s[42:43]
	s_mov_b32 m0, s92
	s_nop 0
	global_load_lds_dwordx4 v[10:11], off
	ds_read_b128 v[202:205], v201 offset:49152
	ds_read_b128 v[206:209], v201 offset:50176
	ds_read_b128 v[210:213], v201 offset:51200
	ds_read_b128 v[214:217], v201 offset:52224
	ds_read_b128 v[218:221], v201 offset:53248
	ds_read_b128 v[222:225], v201 offset:54272
	ds_read_b128 v[226:229], v201 offset:55296
	ds_read_b128 v[230:233], v201 offset:56320
	s_waitcnt vmcnt(8)
	s_waitcnt lgkmcnt(0)
	s_setprio 1
	s_barrier
	v_mfma_f32_16x16x128_f8f6f4 v[94:97], v[18:25], v[202:209], v[94:97]
	v_mfma_f32_16x16x128_f8f6f4 v[90:93], v[26:33], v[202:209], v[90:93]
	v_mfma_f32_16x16x128_f8f6f4 v[58:61], v[182:189], v[202:209], v[58:61]
	v_mfma_f32_16x16x128_f8f6f4 v[62:65], v[2:9], v[202:209], v[62:65]
	v_mfma_f32_16x16x128_f8f6f4 v[54:57], v[2:9], v[210:217], v[54:57]
	v_mfma_f32_16x16x128_f8f6f4 v[50:53], v[182:189], v[210:217], v[50:53]
	v_mfma_f32_16x16x128_f8f6f4 v[82:85], v[26:33], v[210:217], v[82:85]
	v_mfma_f32_16x16x128_f8f6f4 v[86:89], v[18:25], v[210:217], v[86:89]
	s_setprio 0
	s_setprio 1
	v_mfma_f32_16x16x128_f8f6f4 v[78:81], v[18:25], v[218:225], v[78:81]
	v_mfma_f32_16x16x128_f8f6f4 v[74:77], v[26:33], v[218:225], v[74:77]
	v_mfma_f32_16x16x128_f8f6f4 v[42:45], v[182:189], v[218:225], v[42:45]
	v_mfma_f32_16x16x128_f8f6f4 v[46:49], v[2:9], v[218:225], v[46:49]
	v_mfma_f32_16x16x128_f8f6f4 v[38:41], v[2:9], v[226:233], v[38:41]
	v_mfma_f32_16x16x128_f8f6f4 v[34:37], v[182:189], v[226:233], v[34:37]
	v_mfma_f32_16x16x128_f8f6f4 v[66:69], v[26:33], v[226:233], v[66:69]
	v_mfma_f32_16x16x128_f8f6f4 v[70:73], v[18:25], v[226:233], v[70:73]
	s_barrier
	s_setprio 0
	s_add_i32 s62, s62, 2
	s_add_u32 s80, s80, 0x100
	s_addc_u32 s81, s81, 0
	s_add_u32 s8, s8, 0x100
	s_addc_u32 s9, s9, 0
	s_cmp_gt_u32 s62, 5
	s_cbranch_scc0 .LBB0_601
	s_and_b64 vcc, exec, s[44:45]
	s_cbranch_vccz .LBB0_604
	s_barrier

.LBB0_616:
	ds_read_b128 v[18:21], v188
	ds_read_b128 v[22:25], v188 offset:1024
	ds_read_b128 v[26:29], v188 offset:2048
	ds_read_b128 v[30:33], v188 offset:3072
	ds_read_b128 v[2:5], v188 offset:16384
	ds_read_b128 v[6:9], v188 offset:17408
	ds_read_b128 v[10:13], v188 offset:18432
	ds_read_b128 v[14:17], v188 offset:19456
	s_ashr_i32 s55, s54, 31
	s_lshl_b64 s[62:63], s[54:55], 17
	s_add_u32 s72, s36, s62
	s_addc_u32 s73, s37, s63
	s_and_b64 s[62:63], s[2:3], exec
	s_cselect_b32 s85, s73, s79
	s_cselect_b32 s84, s72, s78
	s_ashr_i32 s53, s52, 31
	s_lshl_b64 s[62:63], s[52:53], 17
	s_add_u32 s74, s94, s62
	v_readlane_b32 s5, v254, 8
	s_addc_u32 s75, s5, s63
	s_and_b64 s[62:63], s[2:3], exec
	s_cselect_b32 s83, s75, s81
	s_cselect_b32 s82, s74, s80
	s_add_u32 s62, s78, 0x10080
	s_addc_u32 s63, s79, 0
	s_mov_b32 m0, s96
	v_lshl_add_u64 v[174:175], s[62:63], 0, v[166:167]
	ds_read_b128 v[196:199], v189
	ds_read_b128 v[200:203], v189 offset:1024
	ds_read_b128 v[204:207], v189 offset:2048
	ds_read_b128 v[208:211], v189 offset:3072
	ds_read_b128 v[212:215], v189 offset:4096
	ds_read_b128 v[216:219], v189 offset:5120
	ds_read_b128 v[220:223], v189 offset:6144
	ds_read_b128 v[224:227], v189 offset:7168
	global_load_lds_dwordx4 v[174:175], off
	v_lshl_add_u64 v[174:175], s[62:63], 0, v[168:169]
	s_mov_b32 m0, s97
	s_nop 0
	global_load_lds_dwordx4 v[174:175], off
	s_waitcnt vmcnt(8)
	s_waitcnt lgkmcnt(0)
	s_setprio 1
	s_barrier
	v_mfma_f32_16x16x128_f8f6f4 v[158:161], v[18:25], v[196:203], 0
	v_mfma_f32_16x16x128_f8f6f4 v[154:157], v[26:33], v[196:203], 0
	v_mfma_f32_16x16x128_f8f6f4 v[122:125], v[10:17], v[196:203], 0
	v_mfma_f32_16x16x128_f8f6f4 v[126:129], v[2:9], v[196:203], 0
	v_mfma_f32_16x16x128_f8f6f4 v[118:121], v[2:9], v[204:211], 0
	v_mfma_f32_16x16x128_f8f6f4 v[114:117], v[10:17], v[204:211], 0
	v_mfma_f32_16x16x128_f8f6f4 v[146:149], v[26:33], v[204:211], 0
	v_mfma_f32_16x16x128_f8f6f4 v[150:153], v[18:25], v[204:211], 0
	s_setprio 0
	s_setprio 1
	v_mfma_f32_16x16x128_f8f6f4 v[142:145], v[18:25], v[212:219], 0
	v_mfma_f32_16x16x128_f8f6f4 v[138:141], v[26:33], v[212:219], 0
	v_mfma_f32_16x16x128_f8f6f4 v[106:109], v[10:17], v[212:219], 0
	v_mfma_f32_16x16x128_f8f6f4 v[110:113], v[2:9], v[212:219], 0
	v_mfma_f32_16x16x128_f8f6f4 v[102:105], v[2:9], v[220:227], 0
	v_mfma_f32_16x16x128_f8f6f4 v[98:101], v[10:17], v[220:227], 0
	v_mfma_f32_16x16x128_f8f6f4 v[130:133], v[26:33], v[220:227], 0
	v_mfma_f32_16x16x128_f8f6f4 v[134:137], v[18:25], v[220:227], 0
	s_barrier
	s_setprio 0
	v_lshl_add_u64 v[174:175], s[80:81], 0, v[162:163]
	s_mov_b32 m0, s61
	v_lshl_add_u64 v[176:177], v[174:175], 0, s[46:47]
	global_load_lds_dwordx4 v[176:177], off
	v_lshl_add_u64 v[176:177], s[80:81], 0, v[164:165]
	s_add_u32 s62, s80, 0x10100
	v_lshl_add_u64 v[182:183], v[176:177], 0, s[46:47]
	s_mov_b32 m0, s68
	s_addc_u32 s63, s81, 0
	global_load_lds_dwordx4 v[182:183], off
	v_lshl_add_u64 v[182:183], s[62:63], 0, v[162:163]
	s_mov_b32 m0, s69
	s_nop 0
	global_load_lds_dwordx4 v[182:183], off
	v_lshl_add_u64 v[182:183], s[62:63], 0, v[164:165]
	s_mov_b32 m0, s77
	s_nop 0
	global_load_lds_dwordx4 v[182:183], off
	v_lshl_add_u64 v[182:183], s[78:79], 0, v[166:167]
	v_lshl_add_u64 v[184:185], v[182:183], 0, s[46:47]
	s_mov_b32 m0, s51
	s_nop 0
	global_load_lds_dwordx4 v[184:185], off
	v_lshl_add_u64 v[184:185], s[78:79], 0, v[168:169]
	v_lshl_add_u64 v[228:229], v[184:185], 0, s[46:47]
	s_mov_b32 m0, s86
	s_nop 0
	global_load_lds_dwordx4 v[228:229], off
	ds_read_b128 v[196:199], v189 offset:16384
	ds_read_b128 v[200:203], v189 offset:17408
	ds_read_b128 v[204:207], v189 offset:18432
	ds_read_b128 v[208:211], v189 offset:19456
	ds_read_b128 v[212:215], v189 offset:20480
	ds_read_b128 v[216:219], v189 offset:21504
	ds_read_b128 v[220:223], v189 offset:22528
	ds_read_b128 v[224:227], v189 offset:23552
	s_waitcnt vmcnt(8)
	s_waitcnt lgkmcnt(0)
	s_setprio 1
	s_barrier
	v_mfma_f32_16x16x128_f8f6f4 v[94:97], v[18:25], v[196:203], 0
	v_mfma_f32_16x16x128_f8f6f4 v[90:93], v[26:33], v[196:203], 0
	v_mfma_f32_16x16x128_f8f6f4 v[58:61], v[10:17], v[196:203], 0
	v_mfma_f32_16x16x128_f8f6f4 v[62:65], v[2:9], v[196:203], 0
	v_mfma_f32_16x16x128_f8f6f4 v[54:57], v[2:9], v[204:211], 0
	v_mfma_f32_16x16x128_f8f6f4 v[50:53], v[10:17], v[204:211], 0
	v_mfma_f32_16x16x128_f8f6f4 v[82:85], v[26:33], v[204:211], 0
	v_mfma_f32_16x16x128_f8f6f4 v[86:89], v[18:25], v[204:211], 0
	s_setprio 0
	s_setprio 1
	v_mfma_f32_16x16x128_f8f6f4 v[78:81], v[18:25], v[212:219], 0
	v_mfma_f32_16x16x128_f8f6f4 v[74:77], v[26:33], v[212:219], 0
	v_mfma_f32_16x16x128_f8f6f4 v[42:45], v[10:17], v[212:219], 0
	v_mfma_f32_16x16x128_f8f6f4 v[46:49], v[2:9], v[212:219], 0
	v_mfma_f32_16x16x128_f8f6f4 v[38:41], v[2:9], v[220:227], 0
	v_mfma_f32_16x16x128_f8f6f4 v[34:37], v[10:17], v[220:227], 0
	v_mfma_f32_16x16x128_f8f6f4 v[66:69], v[26:33], v[220:227], 0
	v_mfma_f32_16x16x128_f8f6f4 v[70:73], v[18:25], v[220:227], 0
	s_barrier
	s_setprio 0
	s_add_u32 s62, s78, 0x10100
	s_addc_u32 s63, s79, 0
	s_mov_b32 m0, s87
	v_lshl_add_u64 v[228:229], s[62:63], 0, v[166:167]
	global_load_lds_dwordx4 v[228:229], off
	v_lshl_add_u64 v[228:229], s[62:63], 0, v[168:169]
	s_mov_b32 m0, s88
	s_nop 0
	global_load_lds_dwordx4 v[228:229], off
	ds_read_b128 v[2:5], v188 offset:32768
	ds_read_b128 v[6:9], v188 offset:33792
	ds_read_b128 v[10:13], v188 offset:34816
	ds_read_b128 v[14:17], v188 offset:35840
	ds_read_b128 v[18:21], v188 offset:49152
	ds_read_b128 v[22:25], v188 offset:50176
	ds_read_b128 v[26:29], v188 offset:51200
	ds_read_b128 v[30:33], v188 offset:52224
	ds_read_b128 v[196:199], v189 offset:32768
	ds_read_b128 v[200:203], v189 offset:33792
	ds_read_b128 v[204:207], v189 offset:34816
	ds_read_b128 v[208:211], v189 offset:35840
	ds_read_b128 v[212:215], v189 offset:36864
	ds_read_b128 v[216:219], v189 offset:37888
	ds_read_b128 v[220:223], v189 offset:38912
	ds_read_b128 v[224:227], v189 offset:39936
	s_waitcnt vmcnt(8)
	s_waitcnt lgkmcnt(0)
	s_setprio 1
	s_barrier
	v_mfma_f32_16x16x128_f8f6f4 v[158:161], v[2:9], v[196:203], v[158:161]
	v_mfma_f32_16x16x128_f8f6f4 v[154:157], v[10:17], v[196:203], v[154:157]
	v_mfma_f32_16x16x128_f8f6f4 v[122:125], v[26:33], v[196:203], v[122:125]
	v_mfma_f32_16x16x128_f8f6f4 v[126:129], v[18:25], v[196:203], v[126:129]
	v_mfma_f32_16x16x128_f8f6f4 v[118:121], v[18:25], v[204:211], v[118:121]
	v_mfma_f32_16x16x128_f8f6f4 v[114:117], v[26:33], v[204:211], v[114:117]
	v_mfma_f32_16x16x128_f8f6f4 v[146:149], v[10:17], v[204:211], v[146:149]
	v_mfma_f32_16x16x128_f8f6f4 v[150:153], v[2:9], v[204:211], v[150:153]
	s_setprio 0
	s_setprio 1
	v_mfma_f32_16x16x128_f8f6f4 v[142:145], v[2:9], v[212:219], v[142:145]
	v_mfma_f32_16x16x128_f8f6f4 v[138:141], v[10:17], v[212:219], v[138:141]
	v_mfma_f32_16x16x128_f8f6f4 v[106:109], v[26:33], v[212:219], v[106:109]
	v_mfma_f32_16x16x128_f8f6f4 v[110:113], v[18:25], v[212:219], v[110:113]
	v_mfma_f32_16x16x128_f8f6f4 v[102:105], v[18:25], v[220:227], v[102:105]
	v_mfma_f32_16x16x128_f8f6f4 v[98:101], v[26:33], v[220:227], v[98:101]
	v_mfma_f32_16x16x128_f8f6f4 v[130:133], v[10:17], v[220:227], v[130:133]
	v_mfma_f32_16x16x128_f8f6f4 v[134:137], v[2:9], v[220:227], v[134:137]
	s_barrier
	s_setprio 0
	s_mov_b32 m0, s89
	v_lshl_add_u64 v[174:175], v[174:175], 0, s[48:49]
	s_add_u32 s62, s80, 0x10180
	global_load_lds_dwordx4 v[174:175], off
	v_lshl_add_u64 v[174:175], v[176:177], 0, s[48:49]
	s_mov_b32 m0, s90
	s_addc_u32 s63, s81, 0
	global_load_lds_dwordx4 v[174:175], off
	v_lshl_add_u64 v[174:175], s[62:63], 0, v[162:163]
	s_mov_b32 m0, s93
	s_nop 0
	global_load_lds_dwordx4 v[174:175], off
	v_lshl_add_u64 v[174:175], s[62:63], 0, v[164:165]
	s_mov_b32 m0, s95
	s_nop 0
	global_load_lds_dwordx4 v[174:175], off
	v_lshl_add_u64 v[174:175], v[182:183], 0, s[48:49]
	s_mov_b32 m0, s91
	s_nop 0
	global_load_lds_dwordx4 v[174:175], off
	v_lshl_add_u64 v[174:175], v[184:185], 0, s[48:49]
	s_mov_b32 m0, s92
	s_nop 0
	global_load_lds_dwordx4 v[174:175], off
	ds_read_b128 v[196:199], v189 offset:49152
	ds_read_b128 v[200:203], v189 offset:50176
	ds_read_b128 v[204:207], v189 offset:51200
	ds_read_b128 v[208:211], v189 offset:52224
	ds_read_b128 v[212:215], v189 offset:53248
	ds_read_b128 v[216:219], v189 offset:54272
	ds_read_b128 v[220:223], v189 offset:55296
	ds_read_b128 v[224:227], v189 offset:56320
	s_waitcnt vmcnt(8)
	s_waitcnt lgkmcnt(0)
	s_setprio 1
	s_barrier
	v_mfma_f32_16x16x128_f8f6f4 v[94:97], v[2:9], v[196:203], v[94:97]
	v_mfma_f32_16x16x128_f8f6f4 v[90:93], v[10:17], v[196:203], v[90:93]
	v_mfma_f32_16x16x128_f8f6f4 v[58:61], v[26:33], v[196:203], v[58:61]
	v_mfma_f32_16x16x128_f8f6f4 v[62:65], v[18:25], v[196:203], v[62:65]
	v_mfma_f32_16x16x128_f8f6f4 v[54:57], v[18:25], v[204:211], v[54:57]
	v_mfma_f32_16x16x128_f8f6f4 v[50:53], v[26:33], v[204:211], v[50:53]
	v_mfma_f32_16x16x128_f8f6f4 v[82:85], v[10:17], v[204:211], v[82:85]
	v_mfma_f32_16x16x128_f8f6f4 v[86:89], v[2:9], v[204:211], v[86:89]
	s_setprio 0
	s_setprio 1
	v_mfma_f32_16x16x128_f8f6f4 v[78:81], v[2:9], v[212:219], v[78:81]
	v_mfma_f32_16x16x128_f8f6f4 v[74:77], v[10:17], v[212:219], v[74:77]
	v_mfma_f32_16x16x128_f8f6f4 v[42:45], v[26:33], v[212:219], v[42:45]
	v_mfma_f32_16x16x128_f8f6f4 v[46:49], v[18:25], v[212:219], v[46:49]
	v_mfma_f32_16x16x128_f8f6f4 v[38:41], v[18:25], v[220:227], v[38:41]
	v_mfma_f32_16x16x128_f8f6f4 v[34:37], v[26:33], v[220:227], v[34:37]
	v_mfma_f32_16x16x128_f8f6f4 v[66:69], v[10:17], v[220:227], v[66:69]
	v_mfma_f32_16x16x128_f8f6f4 v[70:73], v[2:9], v[220:227], v[70:73]
	s_barrier
	s_setprio 0
	s_add_u32 s62, s78, 0x10180
	s_addc_u32 s63, s79, 0
	s_mov_b32 m0, s96
	v_lshl_add_u64 v[174:175], s[62:63], 0, v[166:167]
	global_load_lds_dwordx4 v[174:175], off
	v_lshl_add_u64 v[174:175], s[62:63], 0, v[168:169]
	s_mov_b32 m0, s97
	s_nop 0
	global_load_lds_dwordx4 v[174:175], off
	ds_read_b128 v[2:5], v188
	ds_read_b128 v[6:9], v188 offset:1024
	ds_read_b128 v[10:13], v188 offset:2048
	ds_read_b128 v[14:17], v188 offset:3072
	ds_read_b128 v[18:21], v188 offset:16384
	ds_read_b128 v[22:25], v188 offset:17408
	ds_read_b128 v[26:29], v188 offset:18432
	ds_read_b128 v[30:33], v188 offset:19456
	ds_read_b128 v[196:199], v189
	ds_read_b128 v[200:203], v189 offset:1024
	ds_read_b128 v[204:207], v189 offset:2048
	ds_read_b128 v[208:211], v189 offset:3072
	ds_read_b128 v[212:215], v189 offset:4096
	ds_read_b128 v[216:219], v189 offset:5120
	ds_read_b128 v[220:223], v189 offset:6144
	ds_read_b128 v[224:227], v189 offset:7168
	s_waitcnt vmcnt(8)
	s_waitcnt lgkmcnt(0)
	s_setprio 1
	s_barrier
	v_mfma_f32_16x16x128_f8f6f4 v[158:161], v[2:9], v[196:203], v[158:161]
	v_mfma_f32_16x16x128_f8f6f4 v[154:157], v[10:17], v[196:203], v[154:157]
	v_mfma_f32_16x16x128_f8f6f4 v[122:125], v[26:33], v[196:203], v[122:125]
	v_mfma_f32_16x16x128_f8f6f4 v[126:129], v[18:25], v[196:203], v[126:129]
	v_mfma_f32_16x16x128_f8f6f4 v[118:121], v[18:25], v[204:211], v[118:121]
	v_mfma_f32_16x16x128_f8f6f4 v[114:117], v[26:33], v[204:211], v[114:117]
	v_mfma_f32_16x16x128_f8f6f4 v[146:149], v[10:17], v[204:211], v[146:149]
	v_mfma_f32_16x16x128_f8f6f4 v[150:153], v[2:9], v[204:211], v[150:153]
	s_setprio 0
	s_setprio 1
	v_mfma_f32_16x16x128_f8f6f4 v[142:145], v[2:9], v[212:219], v[142:145]
	v_mfma_f32_16x16x128_f8f6f4 v[138:141], v[10:17], v[212:219], v[138:141]
	v_mfma_f32_16x16x128_f8f6f4 v[106:109], v[26:33], v[212:219], v[106:109]
	v_mfma_f32_16x16x128_f8f6f4 v[110:113], v[18:25], v[212:219], v[110:113]
	v_mfma_f32_16x16x128_f8f6f4 v[102:105], v[18:25], v[220:227], v[102:105]
	v_mfma_f32_16x16x128_f8f6f4 v[98:101], v[26:33], v[220:227], v[98:101]
	v_mfma_f32_16x16x128_f8f6f4 v[130:133], v[10:17], v[220:227], v[130:133]
	v_mfma_f32_16x16x128_f8f6f4 v[134:137], v[2:9], v[220:227], v[134:137]
	s_barrier
	s_setprio 0
	s_mov_b32 m0, s61
	v_lshl_add_u64 v[174:175], s[82:83], 0, v[162:163]
	s_add_u32 s62, s82, 0x10000
	global_load_lds_dwordx4 v[174:175], off
	v_lshl_add_u64 v[176:177], s[82:83], 0, v[164:165]
	s_mov_b32 m0, s68
	s_addc_u32 s63, s83, 0
	global_load_lds_dwordx4 v[176:177], off
	v_lshl_add_u64 v[182:183], s[62:63], 0, v[162:163]
	s_mov_b32 m0, s69
	v_lshl_add_u64 v[184:185], s[84:85], 0, v[168:169]
	global_load_lds_dwordx4 v[182:183], off
	v_lshl_add_u64 v[182:183], s[62:63], 0, v[164:165]
	s_mov_b32 m0, s77
	s_nop 0
	global_load_lds_dwordx4 v[182:183], off
	v_lshl_add_u64 v[182:183], s[84:85], 0, v[166:167]
	s_mov_b32 m0, s51
	s_nop 0
	global_load_lds_dwordx4 v[182:183], off
	s_mov_b32 m0, s86
	s_nop 0
	global_load_lds_dwordx4 v[184:185], off
	ds_read_b128 v[196:199], v189 offset:16384
	ds_read_b128 v[200:203], v189 offset:17408
	ds_read_b128 v[204:207], v189 offset:18432
	ds_read_b128 v[208:211], v189 offset:19456
	ds_read_b128 v[212:215], v189 offset:20480
	ds_read_b128 v[216:219], v189 offset:21504
	ds_read_b128 v[220:223], v189 offset:22528
	ds_read_b128 v[224:227], v189 offset:23552
	s_waitcnt vmcnt(8)
	s_waitcnt lgkmcnt(0)
	s_setprio 1
	s_barrier
	v_mfma_f32_16x16x128_f8f6f4 v[94:97], v[2:9], v[196:203], v[94:97]
	v_mfma_f32_16x16x128_f8f6f4 v[90:93], v[10:17], v[196:203], v[90:93]
	v_mfma_f32_16x16x128_f8f6f4 v[58:61], v[26:33], v[196:203], v[58:61]
	v_mfma_f32_16x16x128_f8f6f4 v[62:65], v[18:25], v[196:203], v[62:65]
	v_mfma_f32_16x16x128_f8f6f4 v[54:57], v[18:25], v[204:211], v[54:57]
	v_mfma_f32_16x16x128_f8f6f4 v[50:53], v[26:33], v[204:211], v[50:53]
	v_mfma_f32_16x16x128_f8f6f4 v[82:85], v[10:17], v[204:211], v[82:85]
	v_mfma_f32_16x16x128_f8f6f4 v[86:89], v[2:9], v[204:211], v[86:89]
	s_setprio 0
	s_setprio 1
	v_mfma_f32_16x16x128_f8f6f4 v[78:81], v[2:9], v[212:219], v[78:81]
	v_mfma_f32_16x16x128_f8f6f4 v[74:77], v[10:17], v[212:219], v[74:77]
	v_mfma_f32_16x16x128_f8f6f4 v[42:45], v[26:33], v[212:219], v[42:45]
	v_mfma_f32_16x16x128_f8f6f4 v[46:49], v[18:25], v[212:219], v[46:49]
	v_mfma_f32_16x16x128_f8f6f4 v[38:41], v[18:25], v[220:227], v[38:41]
	v_mfma_f32_16x16x128_f8f6f4 v[34:37], v[26:33], v[220:227], v[34:37]
	v_mfma_f32_16x16x128_f8f6f4 v[66:69], v[10:17], v[220:227], v[66:69]
	v_mfma_f32_16x16x128_f8f6f4 v[70:73], v[2:9], v[220:227], v[70:73]
	s_barrier
	s_setprio 0
	s_add_u32 s62, s84, 0x10000
	s_addc_u32 s63, s85, 0
	s_mov_b32 m0, s87
	v_lshl_add_u64 v[228:229], s[62:63], 0, v[166:167]
	global_load_lds_dwordx4 v[228:229], off
	v_lshl_add_u64 v[228:229], s[62:63], 0, v[168:169]
	s_mov_b32 m0, s88
	s_nop 0
	global_load_lds_dwordx4 v[228:229], off
	ds_read_b128 v[2:5], v188 offset:32768
	ds_read_b128 v[6:9], v188 offset:33792
	ds_read_b128 v[10:13], v188 offset:34816
	ds_read_b128 v[14:17], v188 offset:35840
	ds_read_b128 v[18:21], v188 offset:49152
	ds_read_b128 v[22:25], v188 offset:50176
	ds_read_b128 v[26:29], v188 offset:51200
	ds_read_b128 v[30:33], v188 offset:52224
	ds_read_b128 v[196:199], v189 offset:32768
	ds_read_b128 v[200:203], v189 offset:33792
	ds_read_b128 v[204:207], v189 offset:34816
	ds_read_b128 v[208:211], v189 offset:35840
	ds_read_b128 v[212:215], v189 offset:36864
	ds_read_b128 v[216:219], v189 offset:37888
	ds_read_b128 v[220:223], v189 offset:38912
	ds_read_b128 v[224:227], v189 offset:39936
	s_waitcnt vmcnt(8)
	s_waitcnt lgkmcnt(0)
	s_setprio 1
	s_barrier
	v_mfma_f32_16x16x128_f8f6f4 v[158:161], v[2:9], v[196:203], v[158:161]
	v_mfma_f32_16x16x128_f8f6f4 v[154:157], v[10:17], v[196:203], v[154:157]
	v_mfma_f32_16x16x128_f8f6f4 v[122:125], v[26:33], v[196:203], v[122:125]
	v_mfma_f32_16x16x128_f8f6f4 v[126:129], v[18:25], v[196:203], v[126:129]
	v_mfma_f32_16x16x128_f8f6f4 v[118:121], v[18:25], v[204:211], v[118:121]
	v_mfma_f32_16x16x128_f8f6f4 v[114:117], v[26:33], v[204:211], v[114:117]
	v_mfma_f32_16x16x128_f8f6f4 v[146:149], v[10:17], v[204:211], v[146:149]
	v_mfma_f32_16x16x128_f8f6f4 v[150:153], v[2:9], v[204:211], v[150:153]
	s_setprio 0
	s_setprio 1
	v_mfma_f32_16x16x128_f8f6f4 v[142:145], v[2:9], v[212:219], v[142:145]
	v_mfma_f32_16x16x128_f8f6f4 v[138:141], v[10:17], v[212:219], v[138:141]
	v_mfma_f32_16x16x128_f8f6f4 v[106:109], v[26:33], v[212:219], v[106:109]
	v_mfma_f32_16x16x128_f8f6f4 v[110:113], v[18:25], v[212:219], v[110:113]
	v_mfma_f32_16x16x128_f8f6f4 v[102:105], v[18:25], v[220:227], v[102:105]
	v_mfma_f32_16x16x128_f8f6f4 v[98:101], v[26:33], v[220:227], v[98:101]
	v_mfma_f32_16x16x128_f8f6f4 v[130:133], v[10:17], v[220:227], v[130:133]
	v_mfma_f32_16x16x128_f8f6f4 v[134:137], v[2:9], v[220:227], v[134:137]
	s_barrier
	s_setprio 0
	s_mov_b32 m0, s89
	v_lshl_add_u64 v[174:175], v[174:175], 0, s[40:41]
	s_add_u32 s62, s82, 0x10080
	global_load_lds_dwordx4 v[174:175], off
	v_lshl_add_u64 v[174:175], v[176:177], 0, s[40:41]
	s_mov_b32 m0, s90
	s_addc_u32 s63, s83, 0
	global_load_lds_dwordx4 v[174:175], off
	v_lshl_add_u64 v[174:175], s[62:63], 0, v[162:163]
	s_mov_b32 m0, s93
	s_nop 0
	global_load_lds_dwordx4 v[174:175], off
	v_lshl_add_u64 v[174:175], s[62:63], 0, v[164:165]
	s_mov_b32 m0, s95
	s_nop 0
	global_load_lds_dwordx4 v[174:175], off
	v_lshl_add_u64 v[174:175], v[182:183], 0, s[40:41]
	s_mov_b32 m0, s91
	s_nop 0
	global_load_lds_dwordx4 v[174:175], off
	v_lshl_add_u64 v[174:175], v[184:185], 0, s[40:41]
	s_mov_b32 m0, s92
	s_nop 0
	global_load_lds_dwordx4 v[174:175], off
	ds_read_b128 v[196:199], v189 offset:49152
	ds_read_b128 v[200:203], v189 offset:50176
	ds_read_b128 v[204:207], v189 offset:51200
	ds_read_b128 v[208:211], v189 offset:52224
	ds_read_b128 v[212:215], v189 offset:53248
	ds_read_b128 v[216:219], v189 offset:54272
	ds_read_b128 v[220:223], v189 offset:55296
	ds_read_b128 v[224:227], v189 offset:56320
	s_waitcnt vmcnt(8)
	s_waitcnt lgkmcnt(0)
	s_setprio 1
	s_barrier
	v_mfma_f32_16x16x128_f8f6f4 v[94:97], v[2:9], v[196:203], v[94:97]
	v_mfma_f32_16x16x128_f8f6f4 v[90:93], v[10:17], v[196:203], v[90:93]
	v_mfma_f32_16x16x128_f8f6f4 v[58:61], v[26:33], v[196:203], v[58:61]
	v_mfma_f32_16x16x128_f8f6f4 v[62:65], v[18:25], v[196:203], v[62:65]
	v_mfma_f32_16x16x128_f8f6f4 v[54:57], v[18:25], v[204:211], v[54:57]
	v_mfma_f32_16x16x128_f8f6f4 v[50:53], v[26:33], v[204:211], v[50:53]
	v_mfma_f32_16x16x128_f8f6f4 v[82:85], v[10:17], v[204:211], v[82:85]
	v_mfma_f32_16x16x128_f8f6f4 v[86:89], v[2:9], v[204:211], v[86:89]
	s_setprio 0
	s_setprio 1
	v_mfma_f32_16x16x128_f8f6f4 v[78:81], v[2:9], v[212:219], v[78:81]
	v_mfma_f32_16x16x128_f8f6f4 v[74:77], v[10:17], v[212:219], v[74:77]
	v_mfma_f32_16x16x128_f8f6f4 v[42:45], v[26:33], v[212:219], v[42:45]
	v_mfma_f32_16x16x128_f8f6f4 v[46:49], v[18:25], v[212:219], v[46:49]
	v_mfma_f32_16x16x128_f8f6f4 v[38:41], v[18:25], v[220:227], v[38:41]
	v_mfma_f32_16x16x128_f8f6f4 v[34:37], v[26:33], v[220:227], v[34:37]
	v_mfma_f32_16x16x128_f8f6f4 v[66:69], v[10:17], v[220:227], v[66:69]
	v_mfma_f32_16x16x128_f8f6f4 v[70:73], v[2:9], v[220:227], v[70:73]
	s_barrier
	s_setprio 0
	s_andn2_b64 vcc, exec, s[42:43]
	s_cbranch_vccnz .LBB0_618
	s_barrier

.LBB0_630:
	s_ashr_i32 s54, s48, 1
	s_ashr_i32 s51, s50, 31
	s_ashr_i32 s55, s54, 31
	s_lshl_b64 s[52:53], s[50:51], 19
	s_lshl_b64 s[54:55], s[54:55], 9
	s_waitcnt vmcnt(0)
	ds_read_b128 v[18:21], v181
	ds_read_b128 v[22:25], v181 offset:1024
	ds_read_b128 v[26:29], v181 offset:2048
	ds_read_b128 v[30:33], v181 offset:3072
	ds_read_b128 v[2:5], v181 offset:16384
	ds_read_b128 v[6:9], v181 offset:17408
	ds_read_b128 v[10:13], v181 offset:18432
	ds_read_b128 v[14:17], v181 offset:19456
	s_add_u32 s5, s26, s52
	s_addc_u32 s33, s27, s53
	s_add_u32 s52, s5, s54
	s_addc_u32 s53, s33, s55
	s_and_b64 s[54:55], s[2:3], exec
	s_cselect_b32 s81, s53, s75
	s_cselect_b32 s80, s52, s74
	s_ashr_i32 s49, s48, 31
	s_lshl_b64 s[54:55], s[48:49], 17
	v_readlane_b32 s5, v254, 9
	s_add_u32 s54, s5, s54
	v_readlane_b32 s5, v254, 10
	s_addc_u32 s55, s5, s55
	s_and_b64 s[62:63], s[2:3], exec
	s_cselect_b32 s79, s55, s77
	s_cselect_b32 s78, s54, s76
	s_add_u32 s62, s74, 0x40080
	s_addc_u32 s63, s75, 0
	s_add_i32 s33, s8, 0xc000
	v_lshl_add_u64 v[174:175], s[62:63], 0, v[166:167]
	s_mov_b32 m0, s33
	s_add_i32 s5, s8, 0xe000
	ds_read_b128 v[190:193], v187
	ds_read_b128 v[194:197], v187 offset:1024
	ds_read_b128 v[198:201], v187 offset:2048
	ds_read_b128 v[202:205], v187 offset:3072
	ds_read_b128 v[206:209], v187 offset:4096
	ds_read_b128 v[210:213], v187 offset:5120
	ds_read_b128 v[214:217], v187 offset:6144
	ds_read_b128 v[218:221], v187 offset:7168
	global_load_lds_dwordx4 v[174:175], off
	v_lshl_add_u64 v[174:175], s[62:63], 0, v[168:169]
	s_mov_b32 m0, s5
	s_nop 0
	global_load_lds_dwordx4 v[174:175], off
	s_waitcnt vmcnt(8)
	s_waitcnt lgkmcnt(0)
	s_setprio 1
	s_barrier
	v_mfma_f32_16x16x128_f8f6f4 v[158:161], v[18:25], v[190:197], 0
	v_mfma_f32_16x16x128_f8f6f4 v[154:157], v[26:33], v[190:197], 0
	v_mfma_f32_16x16x128_f8f6f4 v[122:125], v[10:17], v[190:197], 0
	v_mfma_f32_16x16x128_f8f6f4 v[126:129], v[2:9], v[190:197], 0
	v_mfma_f32_16x16x128_f8f6f4 v[118:121], v[2:9], v[198:205], 0
	v_mfma_f32_16x16x128_f8f6f4 v[114:117], v[10:17], v[198:205], 0
	v_mfma_f32_16x16x128_f8f6f4 v[146:149], v[26:33], v[198:205], 0
	v_mfma_f32_16x16x128_f8f6f4 v[150:153], v[18:25], v[198:205], 0
	s_setprio 0
	s_setprio 1
	v_mfma_f32_16x16x128_f8f6f4 v[142:145], v[18:25], v[206:213], 0
	v_mfma_f32_16x16x128_f8f6f4 v[138:141], v[26:33], v[206:213], 0
	v_mfma_f32_16x16x128_f8f6f4 v[106:109], v[10:17], v[206:213], 0
	v_mfma_f32_16x16x128_f8f6f4 v[110:113], v[2:9], v[206:213], 0
	v_mfma_f32_16x16x128_f8f6f4 v[102:105], v[2:9], v[214:221], 0
	v_mfma_f32_16x16x128_f8f6f4 v[98:101], v[10:17], v[214:221], 0
	v_mfma_f32_16x16x128_f8f6f4 v[130:133], v[26:33], v[214:221], 0
	v_mfma_f32_16x16x128_f8f6f4 v[134:137], v[18:25], v[214:221], 0
	s_barrier
	s_setprio 0
	v_lshl_add_u64 v[174:175], s[76:77], 0, v[162:163]
	s_mov_b32 m0, s9
	v_lshl_add_u64 v[176:177], v[174:175], 0, s[44:45]
	global_load_lds_dwordx4 v[176:177], off
	v_lshl_add_u64 v[176:177], s[76:77], 0, v[164:165]
	s_add_u32 s62, s76, 0x10100
	v_lshl_add_u64 v[182:183], v[176:177], 0, s[44:45]
	s_mov_b32 m0, s61
	s_addc_u32 s63, s77, 0
	global_load_lds_dwordx4 v[182:183], off
	v_lshl_add_u64 v[182:183], s[62:63], 0, v[162:163]
	s_mov_b32 m0, s68
	s_nop 0
	global_load_lds_dwordx4 v[182:183], off
	v_lshl_add_u64 v[182:183], s[62:63], 0, v[164:165]
	s_mov_b32 m0, s69
	s_nop 0
	global_load_lds_dwordx4 v[182:183], off
	v_lshl_add_u64 v[182:183], s[74:75], 0, v[166:167]
	v_lshl_add_u64 v[184:185], v[182:183], 0, s[44:45]
	s_mov_b32 m0, s8
	s_nop 0
	global_load_lds_dwordx4 v[184:185], off
	v_lshl_add_u64 v[184:185], s[74:75], 0, v[168:169]
	v_lshl_add_u64 v[222:223], v[184:185], 0, s[44:45]
	s_mov_b32 m0, s71
	s_nop 0
	global_load_lds_dwordx4 v[222:223], off
	ds_read_b128 v[190:193], v187 offset:16384
	ds_read_b128 v[194:197], v187 offset:17408
	ds_read_b128 v[198:201], v187 offset:18432
	ds_read_b128 v[202:205], v187 offset:19456
	ds_read_b128 v[206:209], v187 offset:20480
	ds_read_b128 v[210:213], v187 offset:21504
	ds_read_b128 v[214:217], v187 offset:22528
	ds_read_b128 v[218:221], v187 offset:23552
	s_waitcnt vmcnt(8)
	s_waitcnt lgkmcnt(0)
	s_setprio 1
	s_barrier
	v_mfma_f32_16x16x128_f8f6f4 v[94:97], v[18:25], v[190:197], 0
	v_mfma_f32_16x16x128_f8f6f4 v[90:93], v[26:33], v[190:197], 0
	v_mfma_f32_16x16x128_f8f6f4 v[58:61], v[10:17], v[190:197], 0
	v_mfma_f32_16x16x128_f8f6f4 v[62:65], v[2:9], v[190:197], 0
	v_mfma_f32_16x16x128_f8f6f4 v[54:57], v[2:9], v[198:205], 0
	v_mfma_f32_16x16x128_f8f6f4 v[50:53], v[10:17], v[198:205], 0
	v_mfma_f32_16x16x128_f8f6f4 v[82:85], v[26:33], v[198:205], 0
	v_mfma_f32_16x16x128_f8f6f4 v[86:89], v[18:25], v[198:205], 0
	s_setprio 0
	s_setprio 1
	v_mfma_f32_16x16x128_f8f6f4 v[78:81], v[18:25], v[206:213], 0
	v_mfma_f32_16x16x128_f8f6f4 v[74:77], v[26:33], v[206:213], 0
	v_mfma_f32_16x16x128_f8f6f4 v[42:45], v[10:17], v[206:213], 0
	v_mfma_f32_16x16x128_f8f6f4 v[46:49], v[2:9], v[206:213], 0
	v_mfma_f32_16x16x128_f8f6f4 v[38:41], v[2:9], v[214:221], 0
	v_mfma_f32_16x16x128_f8f6f4 v[34:37], v[10:17], v[214:221], 0
	v_mfma_f32_16x16x128_f8f6f4 v[66:69], v[26:33], v[214:221], 0
	v_mfma_f32_16x16x128_f8f6f4 v[70:73], v[18:25], v[214:221], 0
	s_barrier
	s_setprio 0
	s_add_u32 s62, s74, 0x40100
	s_addc_u32 s63, s75, 0
	s_mov_b32 m0, s73
	v_lshl_add_u64 v[222:223], s[62:63], 0, v[166:167]
	global_load_lds_dwordx4 v[222:223], off
	v_lshl_add_u64 v[222:223], s[62:63], 0, v[168:169]
	s_mov_b32 m0, s82
	s_nop 0
	global_load_lds_dwordx4 v[222:223], off
	ds_read_b128 v[2:5], v181 offset:32768
	ds_read_b128 v[6:9], v181 offset:33792
	ds_read_b128 v[10:13], v181 offset:34816
	ds_read_b128 v[14:17], v181 offset:35840
	ds_read_b128 v[18:21], v181 offset:49152
	ds_read_b128 v[22:25], v181 offset:50176
	ds_read_b128 v[26:29], v181 offset:51200
	ds_read_b128 v[30:33], v181 offset:52224
	ds_read_b128 v[190:193], v187 offset:32768
	ds_read_b128 v[194:197], v187 offset:33792
	ds_read_b128 v[198:201], v187 offset:34816
	ds_read_b128 v[202:205], v187 offset:35840
	ds_read_b128 v[206:209], v187 offset:36864
	ds_read_b128 v[210:213], v187 offset:37888
	ds_read_b128 v[214:217], v187 offset:38912
	ds_read_b128 v[218:221], v187 offset:39936
	s_waitcnt vmcnt(8)
	s_waitcnt lgkmcnt(0)
	s_setprio 1
	s_barrier
	v_mfma_f32_16x16x128_f8f6f4 v[158:161], v[2:9], v[190:197], v[158:161]
	v_mfma_f32_16x16x128_f8f6f4 v[154:157], v[10:17], v[190:197], v[154:157]
	v_mfma_f32_16x16x128_f8f6f4 v[122:125], v[26:33], v[190:197], v[122:125]
	v_mfma_f32_16x16x128_f8f6f4 v[126:129], v[18:25], v[190:197], v[126:129]
	v_mfma_f32_16x16x128_f8f6f4 v[118:121], v[18:25], v[198:205], v[118:121]
	v_mfma_f32_16x16x128_f8f6f4 v[114:117], v[26:33], v[198:205], v[114:117]
	v_mfma_f32_16x16x128_f8f6f4 v[146:149], v[10:17], v[198:205], v[146:149]
	v_mfma_f32_16x16x128_f8f6f4 v[150:153], v[2:9], v[198:205], v[150:153]
	s_setprio 0
	s_setprio 1
	v_mfma_f32_16x16x128_f8f6f4 v[142:145], v[2:9], v[206:213], v[142:145]
	v_mfma_f32_16x16x128_f8f6f4 v[138:141], v[10:17], v[206:213], v[138:141]
	v_mfma_f32_16x16x128_f8f6f4 v[106:109], v[26:33], v[206:213], v[106:109]
	v_mfma_f32_16x16x128_f8f6f4 v[110:113], v[18:25], v[206:213], v[110:113]
	v_mfma_f32_16x16x128_f8f6f4 v[102:105], v[18:25], v[214:221], v[102:105]
	v_mfma_f32_16x16x128_f8f6f4 v[98:101], v[26:33], v[214:221], v[98:101]
	v_mfma_f32_16x16x128_f8f6f4 v[130:133], v[10:17], v[214:221], v[130:133]
	v_mfma_f32_16x16x128_f8f6f4 v[134:137], v[2:9], v[214:221], v[134:137]
	s_barrier
	s_setprio 0
	s_mov_b32 m0, s83
	v_lshl_add_u64 v[174:175], v[174:175], 0, s[46:47]
	s_add_u32 s62, s76, 0x10180
	global_load_lds_dwordx4 v[174:175], off
	v_lshl_add_u64 v[174:175], v[176:177], 0, s[46:47]
	s_mov_b32 m0, s84
	s_addc_u32 s63, s77, 0
	global_load_lds_dwordx4 v[174:175], off
	v_lshl_add_u64 v[174:175], s[62:63], 0, v[162:163]
	s_mov_b32 m0, s87
	s_nop 0
	global_load_lds_dwordx4 v[174:175], off
	v_lshl_add_u64 v[174:175], s[62:63], 0, v[164:165]
	s_mov_b32 m0, s88
	s_nop 0
	global_load_lds_dwordx4 v[174:175], off
	v_lshl_add_u64 v[174:175], v[182:183], 0, s[46:47]
	s_mov_b32 m0, s85
	s_nop 0
	global_load_lds_dwordx4 v[174:175], off
	v_lshl_add_u64 v[174:175], v[184:185], 0, s[46:47]
	s_mov_b32 m0, s86
	s_nop 0
	global_load_lds_dwordx4 v[174:175], off
	ds_read_b128 v[190:193], v187 offset:49152
	ds_read_b128 v[194:197], v187 offset:50176
	ds_read_b128 v[198:201], v187 offset:51200
	ds_read_b128 v[202:205], v187 offset:52224
	ds_read_b128 v[206:209], v187 offset:53248
	ds_read_b128 v[210:213], v187 offset:54272
	ds_read_b128 v[214:217], v187 offset:55296
	ds_read_b128 v[218:221], v187 offset:56320
	s_waitcnt vmcnt(8)
	s_waitcnt lgkmcnt(0)
	s_setprio 1
	s_barrier
	v_mfma_f32_16x16x128_f8f6f4 v[94:97], v[2:9], v[190:197], v[94:97]
	v_mfma_f32_16x16x128_f8f6f4 v[90:93], v[10:17], v[190:197], v[90:93]
	v_mfma_f32_16x16x128_f8f6f4 v[58:61], v[26:33], v[190:197], v[58:61]
	v_mfma_f32_16x16x128_f8f6f4 v[62:65], v[18:25], v[190:197], v[62:65]
	v_mfma_f32_16x16x128_f8f6f4 v[54:57], v[18:25], v[198:205], v[54:57]
	v_mfma_f32_16x16x128_f8f6f4 v[50:53], v[26:33], v[198:205], v[50:53]
	v_mfma_f32_16x16x128_f8f6f4 v[82:85], v[10:17], v[198:205], v[82:85]
	v_mfma_f32_16x16x128_f8f6f4 v[86:89], v[2:9], v[198:205], v[86:89]
	s_setprio 0
	s_setprio 1
	v_mfma_f32_16x16x128_f8f6f4 v[78:81], v[2:9], v[206:213], v[78:81]
	v_mfma_f32_16x16x128_f8f6f4 v[74:77], v[10:17], v[206:213], v[74:77]
	v_mfma_f32_16x16x128_f8f6f4 v[42:45], v[26:33], v[206:213], v[42:45]
	v_mfma_f32_16x16x128_f8f6f4 v[46:49], v[18:25], v[206:213], v[46:49]
	v_mfma_f32_16x16x128_f8f6f4 v[38:41], v[18:25], v[214:221], v[38:41]
	v_mfma_f32_16x16x128_f8f6f4 v[34:37], v[26:33], v[214:221], v[34:37]
	v_mfma_f32_16x16x128_f8f6f4 v[66:69], v[10:17], v[214:221], v[66:69]
	v_mfma_f32_16x16x128_f8f6f4 v[70:73], v[2:9], v[214:221], v[70:73]
	s_barrier
	s_setprio 0
	s_add_u32 s62, s74, 0x40180
	s_addc_u32 s63, s75, 0
	s_mov_b32 m0, s33
	v_lshl_add_u64 v[174:175], s[62:63], 0, v[166:167]
	global_load_lds_dwordx4 v[174:175], off
	v_lshl_add_u64 v[174:175], s[62:63], 0, v[168:169]
	s_mov_b32 m0, s5
	s_nop 0
	global_load_lds_dwordx4 v[174:175], off
	ds_read_b128 v[2:5], v181
	ds_read_b128 v[6:9], v181 offset:1024
	ds_read_b128 v[10:13], v181 offset:2048
	ds_read_b128 v[14:17], v181 offset:3072
	ds_read_b128 v[18:21], v181 offset:16384
	ds_read_b128 v[22:25], v181 offset:17408
	ds_read_b128 v[26:29], v181 offset:18432
	ds_read_b128 v[30:33], v181 offset:19456
	ds_read_b128 v[190:193], v187
	ds_read_b128 v[194:197], v187 offset:1024
	ds_read_b128 v[198:201], v187 offset:2048
	ds_read_b128 v[202:205], v187 offset:3072
	ds_read_b128 v[206:209], v187 offset:4096
	ds_read_b128 v[210:213], v187 offset:5120
	ds_read_b128 v[214:217], v187 offset:6144
	ds_read_b128 v[218:221], v187 offset:7168
	s_waitcnt vmcnt(8)
	s_waitcnt lgkmcnt(0)
	s_setprio 1
	s_barrier
	v_mfma_f32_16x16x128_f8f6f4 v[158:161], v[2:9], v[190:197], v[158:161]
	v_mfma_f32_16x16x128_f8f6f4 v[154:157], v[10:17], v[190:197], v[154:157]
	v_mfma_f32_16x16x128_f8f6f4 v[122:125], v[26:33], v[190:197], v[122:125]
	v_mfma_f32_16x16x128_f8f6f4 v[126:129], v[18:25], v[190:197], v[126:129]
	v_mfma_f32_16x16x128_f8f6f4 v[118:121], v[18:25], v[198:205], v[118:121]
	v_mfma_f32_16x16x128_f8f6f4 v[114:117], v[26:33], v[198:205], v[114:117]
	v_mfma_f32_16x16x128_f8f6f4 v[146:149], v[10:17], v[198:205], v[146:149]
	v_mfma_f32_16x16x128_f8f6f4 v[150:153], v[2:9], v[198:205], v[150:153]
	s_setprio 0
	s_setprio 1
	v_mfma_f32_16x16x128_f8f6f4 v[142:145], v[2:9], v[206:213], v[142:145]
	v_mfma_f32_16x16x128_f8f6f4 v[138:141], v[10:17], v[206:213], v[138:141]
	v_mfma_f32_16x16x128_f8f6f4 v[106:109], v[26:33], v[206:213], v[106:109]
	v_mfma_f32_16x16x128_f8f6f4 v[110:113], v[18:25], v[206:213], v[110:113]
	v_mfma_f32_16x16x128_f8f6f4 v[102:105], v[18:25], v[214:221], v[102:105]
	v_mfma_f32_16x16x128_f8f6f4 v[98:101], v[26:33], v[214:221], v[98:101]
	v_mfma_f32_16x16x128_f8f6f4 v[130:133], v[10:17], v[214:221], v[130:133]
	v_mfma_f32_16x16x128_f8f6f4 v[134:137], v[2:9], v[214:221], v[134:137]
	s_barrier
	s_setprio 0
	s_mov_b32 m0, s9
	v_lshl_add_u64 v[174:175], s[78:79], 0, v[162:163]
	s_add_u32 s62, s78, 0x10000
	global_load_lds_dwordx4 v[174:175], off
	v_lshl_add_u64 v[176:177], s[78:79], 0, v[164:165]
	s_mov_b32 m0, s61
	s_addc_u32 s63, s79, 0
	global_load_lds_dwordx4 v[176:177], off
	v_lshl_add_u64 v[182:183], s[62:63], 0, v[162:163]
	s_mov_b32 m0, s68
	v_lshl_add_u64 v[184:185], s[80:81], 0, v[168:169]
	global_load_lds_dwordx4 v[182:183], off
	v_lshl_add_u64 v[182:183], s[62:63], 0, v[164:165]
	s_mov_b32 m0, s69
	s_nop 0
	global_load_lds_dwordx4 v[182:183], off
	v_lshl_add_u64 v[182:183], s[80:81], 0, v[166:167]
	s_mov_b32 m0, s8
	s_nop 0
	global_load_lds_dwordx4 v[182:183], off
	s_mov_b32 m0, s71
	s_nop 0
	global_load_lds_dwordx4 v[184:185], off
	ds_read_b128 v[190:193], v187 offset:16384
	ds_read_b128 v[194:197], v187 offset:17408
	ds_read_b128 v[198:201], v187 offset:18432
	ds_read_b128 v[202:205], v187 offset:19456
	ds_read_b128 v[206:209], v187 offset:20480
	ds_read_b128 v[210:213], v187 offset:21504
	ds_read_b128 v[214:217], v187 offset:22528
	ds_read_b128 v[218:221], v187 offset:23552
	s_waitcnt vmcnt(8)
	s_waitcnt lgkmcnt(0)
	s_setprio 1
	s_barrier
	v_mfma_f32_16x16x128_f8f6f4 v[94:97], v[2:9], v[190:197], v[94:97]
	v_mfma_f32_16x16x128_f8f6f4 v[90:93], v[10:17], v[190:197], v[90:93]
	v_mfma_f32_16x16x128_f8f6f4 v[58:61], v[26:33], v[190:197], v[58:61]
	v_mfma_f32_16x16x128_f8f6f4 v[62:65], v[18:25], v[190:197], v[62:65]
	v_mfma_f32_16x16x128_f8f6f4 v[54:57], v[18:25], v[198:205], v[54:57]
	v_mfma_f32_16x16x128_f8f6f4 v[50:53], v[26:33], v[198:205], v[50:53]
	v_mfma_f32_16x16x128_f8f6f4 v[82:85], v[10:17], v[198:205], v[82:85]
	v_mfma_f32_16x16x128_f8f6f4 v[86:89], v[2:9], v[198:205], v[86:89]
	s_setprio 0
	s_setprio 1
	v_mfma_f32_16x16x128_f8f6f4 v[78:81], v[2:9], v[206:213], v[78:81]
	v_mfma_f32_16x16x128_f8f6f4 v[74:77], v[10:17], v[206:213], v[74:77]
	v_mfma_f32_16x16x128_f8f6f4 v[42:45], v[26:33], v[206:213], v[42:45]
	v_mfma_f32_16x16x128_f8f6f4 v[46:49], v[18:25], v[206:213], v[46:49]
	v_mfma_f32_16x16x128_f8f6f4 v[38:41], v[18:25], v[214:221], v[38:41]
	v_mfma_f32_16x16x128_f8f6f4 v[34:37], v[26:33], v[214:221], v[34:37]
	v_mfma_f32_16x16x128_f8f6f4 v[66:69], v[10:17], v[214:221], v[66:69]
	v_mfma_f32_16x16x128_f8f6f4 v[70:73], v[2:9], v[214:221], v[70:73]
	s_barrier
	s_setprio 0
	s_add_u32 s62, s80, 0x40000
	s_addc_u32 s63, s81, 0
	s_mov_b32 m0, s73
	v_lshl_add_u64 v[222:223], s[62:63], 0, v[166:167]
	global_load_lds_dwordx4 v[222:223], off
	v_lshl_add_u64 v[222:223], s[62:63], 0, v[168:169]
	s_mov_b32 m0, s82
	s_nop 0
	global_load_lds_dwordx4 v[222:223], off
	ds_read_b128 v[2:5], v181 offset:32768
	ds_read_b128 v[6:9], v181 offset:33792
	ds_read_b128 v[10:13], v181 offset:34816
	ds_read_b128 v[14:17], v181 offset:35840
	ds_read_b128 v[18:21], v181 offset:49152
	ds_read_b128 v[22:25], v181 offset:50176
	ds_read_b128 v[26:29], v181 offset:51200
	ds_read_b128 v[30:33], v181 offset:52224
	ds_read_b128 v[190:193], v187 offset:32768
	ds_read_b128 v[194:197], v187 offset:33792
	ds_read_b128 v[198:201], v187 offset:34816
	ds_read_b128 v[202:205], v187 offset:35840
	ds_read_b128 v[206:209], v187 offset:36864
	ds_read_b128 v[210:213], v187 offset:37888
	ds_read_b128 v[214:217], v187 offset:38912
	ds_read_b128 v[218:221], v187 offset:39936
	s_waitcnt vmcnt(8)
	s_waitcnt lgkmcnt(0)
	s_setprio 1
	s_barrier
	v_mfma_f32_16x16x128_f8f6f4 v[158:161], v[2:9], v[190:197], v[158:161]
	v_mfma_f32_16x16x128_f8f6f4 v[154:157], v[10:17], v[190:197], v[154:157]
	v_mfma_f32_16x16x128_f8f6f4 v[122:125], v[26:33], v[190:197], v[122:125]
	v_mfma_f32_16x16x128_f8f6f4 v[126:129], v[18:25], v[190:197], v[126:129]
	v_mfma_f32_16x16x128_f8f6f4 v[118:121], v[18:25], v[198:205], v[118:121]
	v_mfma_f32_16x16x128_f8f6f4 v[114:117], v[26:33], v[198:205], v[114:117]
	v_mfma_f32_16x16x128_f8f6f4 v[146:149], v[10:17], v[198:205], v[146:149]
	v_mfma_f32_16x16x128_f8f6f4 v[150:153], v[2:9], v[198:205], v[150:153]
	s_setprio 0
	s_setprio 1
	v_mfma_f32_16x16x128_f8f6f4 v[142:145], v[2:9], v[206:213], v[142:145]
	v_mfma_f32_16x16x128_f8f6f4 v[138:141], v[10:17], v[206:213], v[138:141]
	v_mfma_f32_16x16x128_f8f6f4 v[106:109], v[26:33], v[206:213], v[106:109]
	v_mfma_f32_16x16x128_f8f6f4 v[110:113], v[18:25], v[206:213], v[110:113]
	v_mfma_f32_16x16x128_f8f6f4 v[102:105], v[18:25], v[214:221], v[102:105]
	v_mfma_f32_16x16x128_f8f6f4 v[98:101], v[26:33], v[214:221], v[98:101]
	v_mfma_f32_16x16x128_f8f6f4 v[130:133], v[10:17], v[214:221], v[130:133]
	v_mfma_f32_16x16x128_f8f6f4 v[134:137], v[2:9], v[214:221], v[134:137]
	s_barrier
	s_setprio 0
	s_mov_b32 m0, s83
	v_lshl_add_u64 v[174:175], v[174:175], 0, s[38:39]
	s_add_u32 s62, s78, 0x10080
	global_load_lds_dwordx4 v[174:175], off
	v_lshl_add_u64 v[174:175], v[176:177], 0, s[38:39]
	s_mov_b32 m0, s84
	s_addc_u32 s63, s79, 0
	global_load_lds_dwordx4 v[174:175], off
	v_lshl_add_u64 v[174:175], s[62:63], 0, v[162:163]
	s_mov_b32 m0, s87
	s_nop 0
	global_load_lds_dwordx4 v[174:175], off
	v_lshl_add_u64 v[174:175], s[62:63], 0, v[164:165]
	s_mov_b32 m0, s88
	s_nop 0
	global_load_lds_dwordx4 v[174:175], off
	v_lshl_add_u64 v[174:175], v[182:183], 0, s[38:39]
	s_mov_b32 m0, s85
	s_nop 0
	global_load_lds_dwordx4 v[174:175], off
	v_lshl_add_u64 v[174:175], v[184:185], 0, s[38:39]
	s_mov_b32 m0, s86
	s_nop 0
	global_load_lds_dwordx4 v[174:175], off
	ds_read_b128 v[190:193], v187 offset:49152
	ds_read_b128 v[194:197], v187 offset:50176
	ds_read_b128 v[198:201], v187 offset:51200
	ds_read_b128 v[202:205], v187 offset:52224
	ds_read_b128 v[206:209], v187 offset:53248
	ds_read_b128 v[210:213], v187 offset:54272
	ds_read_b128 v[214:217], v187 offset:55296
	ds_read_b128 v[218:221], v187 offset:56320
	s_waitcnt vmcnt(8)
	s_waitcnt lgkmcnt(0)
	s_setprio 1
	s_barrier
	v_mfma_f32_16x16x128_f8f6f4 v[94:97], v[2:9], v[190:197], v[94:97]
	v_mfma_f32_16x16x128_f8f6f4 v[90:93], v[10:17], v[190:197], v[90:93]
	v_mfma_f32_16x16x128_f8f6f4 v[58:61], v[26:33], v[190:197], v[58:61]
	v_mfma_f32_16x16x128_f8f6f4 v[62:65], v[18:25], v[190:197], v[62:65]
	v_mfma_f32_16x16x128_f8f6f4 v[54:57], v[18:25], v[198:205], v[54:57]
	v_mfma_f32_16x16x128_f8f6f4 v[50:53], v[26:33], v[198:205], v[50:53]
	v_mfma_f32_16x16x128_f8f6f4 v[82:85], v[10:17], v[198:205], v[82:85]
	v_mfma_f32_16x16x128_f8f6f4 v[86:89], v[2:9], v[198:205], v[86:89]
	s_setprio 0
	s_setprio 1
	v_mfma_f32_16x16x128_f8f6f4 v[78:81], v[2:9], v[206:213], v[78:81]
	v_mfma_f32_16x16x128_f8f6f4 v[74:77], v[10:17], v[206:213], v[74:77]
	v_mfma_f32_16x16x128_f8f6f4 v[42:45], v[26:33], v[206:213], v[42:45]
	v_mfma_f32_16x16x128_f8f6f4 v[46:49], v[18:25], v[206:213], v[46:49]
	v_mfma_f32_16x16x128_f8f6f4 v[38:41], v[18:25], v[214:221], v[38:41]
	v_mfma_f32_16x16x128_f8f6f4 v[34:37], v[26:33], v[214:221], v[34:37]
	v_mfma_f32_16x16x128_f8f6f4 v[66:69], v[10:17], v[214:221], v[66:69]
	v_mfma_f32_16x16x128_f8f6f4 v[70:73], v[2:9], v[214:221], v[70:73]
	s_barrier
	s_setprio 0
	s_andn2_b64 vcc, exec, s[40:41]
	s_cbranch_vccnz .LBB0_632
	s_barrier

.LBB0_791:
	s_add_u32 s37, s46, 0x100
	s_addc_u32 s39, s47, 0
	s_and_b64 s[50:51], s[48:49], exec
	s_cselect_b32 s51, s1, s39
	s_cselect_b32 s50, s0, s37
	s_add_u32 s37, s44, 0x100
	s_addc_u32 s39, s45, 0
	s_and_b64 s[48:49], s[48:49], exec
	s_cselect_b32 s49, s5, s39
	s_cselect_b32 s48, s4, s37
	s_add_u32 s88, s46, 0x80080
	s_addc_u32 s89, s47, 0
	s_add_i32 s37, s8, 0xc000
	v_lshl_add_u64 v[174:175], s[88:89], 0, v[154:155]
	s_mov_b32 m0, s37
	s_add_i32 s39, s8, 0xe000
	global_load_lds_dwordx4 v[174:175], off
	v_lshl_add_u64 v[174:175], s[88:89], 0, v[158:159]
	s_mov_b32 m0, s39
	s_nop 0
	global_load_lds_dwordx4 v[174:175], off
	ds_read_b128 v[2:5], v189
	ds_read_b128 v[6:9], v189 offset:1024
	ds_read_b128 v[192:195], v189 offset:2048
	ds_read_b128 v[196:199], v189 offset:3072
	ds_read_b128 v[200:203], v189 offset:16384
	ds_read_b128 v[204:207], v189 offset:17408
	ds_read_b128 v[208:211], v189 offset:18432
	ds_read_b128 v[212:215], v189 offset:19456
	ds_read_b128 v[216:219], v190
	ds_read_b128 v[220:223], v190 offset:1024
	ds_read_b128 v[224:227], v190 offset:2048
	ds_read_b128 v[228:231], v190 offset:3072
	ds_read_b128 v[242:245], v190 offset:4096
	ds_read_b128 v[246:249], v190 offset:5120
	ds_read_b128 v[232:235], v190 offset:6144
	ds_read_b128 v[236:239], v190 offset:7168
	s_waitcnt vmcnt(8)
	s_waitcnt lgkmcnt(0)
	s_setprio 1
	s_barrier
	v_mfma_f32_16x16x128_f8f6f4 v[134:137], v[2:9], v[216:223], 0
	v_mfma_f32_16x16x128_f8f6f4 v[130:133], v[192:199], v[216:223], 0
	v_mfma_f32_16x16x128_f8f6f4 v[98:101], v[208:215], v[216:223], 0
	v_mfma_f32_16x16x128_f8f6f4 v[102:105], v[200:207], v[216:223], 0
	v_mfma_f32_16x16x128_f8f6f4 v[94:97], v[200:207], v[224:231], 0
	v_mfma_f32_16x16x128_f8f6f4 v[90:93], v[208:215], v[224:231], 0
	v_mfma_f32_16x16x128_f8f6f4 v[122:125], v[192:199], v[224:231], 0
	v_mfma_f32_16x16x128_f8f6f4 v[126:129], v[2:9], v[224:231], 0
	s_setprio 0
	s_setprio 1
	v_mfma_f32_16x16x128_f8f6f4 v[118:121], v[2:9], v[242:249], 0
	v_mfma_f32_16x16x128_f8f6f4 v[114:117], v[192:199], v[242:249], 0
	v_mfma_f32_16x16x128_f8f6f4 v[82:85], v[208:215], v[242:249], 0
	v_mfma_f32_16x16x128_f8f6f4 v[86:89], v[200:207], v[242:249], 0
	v_mfma_f32_16x16x128_f8f6f4 v[78:81], v[200:207], v[232:239], 0
	v_mfma_f32_16x16x128_f8f6f4 v[74:77], v[208:215], v[232:239], 0
	v_mfma_f32_16x16x128_f8f6f4 v[106:109], v[192:199], v[232:239], 0
	v_mfma_f32_16x16x128_f8f6f4 v[110:113], v[2:9], v[232:239], 0
	s_barrier
	s_setprio 0
	s_mov_b32 m0, s9
	v_lshl_add_u64 v[174:175], s[48:49], 0, v[156:157]
	s_add_u32 s88, s48, 0x80000
	global_load_lds_dwordx4 v[174:175], off
	v_lshl_add_u64 v[176:177], s[48:49], 0, v[160:161]
	s_mov_b32 m0, s27
	s_addc_u32 s89, s49, 0
	global_load_lds_dwordx4 v[176:177], off
	v_lshl_add_u64 v[182:183], s[88:89], 0, v[156:157]
	s_mov_b32 m0, s33
	v_lshl_add_u64 v[184:185], s[50:51], 0, v[158:159]
	global_load_lds_dwordx4 v[182:183], off
	v_lshl_add_u64 v[182:183], s[88:89], 0, v[160:161]
	s_mov_b32 m0, s35
	s_nop 0
	global_load_lds_dwordx4 v[182:183], off
	v_lshl_add_u64 v[182:183], s[50:51], 0, v[154:155]
	s_mov_b32 m0, s8
	s_nop 0
	global_load_lds_dwordx4 v[182:183], off
	s_mov_b32 m0, s43
	s_nop 0
	global_load_lds_dwordx4 v[184:185], off
	ds_read_b128 v[216:219], v190 offset:16384
	ds_read_b128 v[220:223], v190 offset:17408
	ds_read_b128 v[224:227], v190 offset:18432
	ds_read_b128 v[228:231], v190 offset:19456
	ds_read_b128 v[232:235], v190 offset:20480
	ds_read_b128 v[236:239], v190 offset:21504
	ds_read_b128 v[242:245], v190 offset:22528
	ds_read_b128 v[246:249], v190 offset:23552
	s_waitcnt vmcnt(8)
	s_waitcnt lgkmcnt(0)
	s_setprio 1
	s_barrier
	v_mfma_f32_16x16x128_f8f6f4 v[70:73], v[2:9], v[216:223], 0
	v_mfma_f32_16x16x128_f8f6f4 v[66:69], v[192:199], v[216:223], 0
	v_mfma_f32_16x16x128_f8f6f4 v[34:37], v[208:215], v[216:223], 0
	v_mfma_f32_16x16x128_f8f6f4 v[38:41], v[200:207], v[216:223], 0
	v_mfma_f32_16x16x128_f8f6f4 v[30:33], v[200:207], v[224:231], 0
	v_mfma_f32_16x16x128_f8f6f4 v[26:29], v[208:215], v[224:231], 0
	v_mfma_f32_16x16x128_f8f6f4 v[58:61], v[192:199], v[224:231], 0
	v_mfma_f32_16x16x128_f8f6f4 v[62:65], v[2:9], v[224:231], 0
	s_setprio 0
	s_setprio 1
	v_mfma_f32_16x16x128_f8f6f4 v[54:57], v[2:9], v[232:239], 0
	v_mfma_f32_16x16x128_f8f6f4 v[50:53], v[192:199], v[232:239], 0
	v_mfma_f32_16x16x128_f8f6f4 v[18:21], v[208:215], v[232:239], 0
	v_mfma_f32_16x16x128_f8f6f4 v[22:25], v[200:207], v[232:239], 0
	v_mfma_f32_16x16x128_f8f6f4 v[14:17], v[200:207], v[242:249], 0
	v_mfma_f32_16x16x128_f8f6f4 v[10:13], v[208:215], v[242:249], 0
	v_mfma_f32_16x16x128_f8f6f4 v[42:45], v[192:199], v[242:249], 0
	v_mfma_f32_16x16x128_f8f6f4 v[46:49], v[2:9], v[242:249], 0
	s_barrier
	s_setprio 0
	s_add_u32 s50, s50, 0x80000
	s_addc_u32 s51, s51, 0
	s_mov_b32 m0, s52
	v_lshl_add_u64 v[186:187], s[50:51], 0, v[154:155]
	global_load_lds_dwordx4 v[186:187], off
	v_lshl_add_u64 v[186:187], s[50:51], 0, v[158:159]
	s_mov_b32 m0, s53
	s_nop 0
	global_load_lds_dwordx4 v[186:187], off
	ds_read_b128 v[2:5], v189 offset:32768
	ds_read_b128 v[6:9], v189 offset:33792
	ds_read_b128 v[192:195], v189 offset:34816
	ds_read_b128 v[196:199], v189 offset:35840
	ds_read_b128 v[200:203], v189 offset:49152
	ds_read_b128 v[204:207], v189 offset:50176
	ds_read_b128 v[208:211], v189 offset:51200
	ds_read_b128 v[212:215], v189 offset:52224
	ds_read_b128 v[216:219], v190 offset:32768
	ds_read_b128 v[220:223], v190 offset:33792
	ds_read_b128 v[224:227], v190 offset:34816
	ds_read_b128 v[228:231], v190 offset:35840
	ds_read_b128 v[232:235], v190 offset:36864
	ds_read_b128 v[236:239], v190 offset:37888
	ds_read_b128 v[242:245], v190 offset:38912
	ds_read_b128 v[246:249], v190 offset:39936
	s_waitcnt vmcnt(8)
	s_waitcnt lgkmcnt(0)
	s_setprio 1
	s_barrier
	v_mfma_f32_16x16x128_f8f6f4 v[134:137], v[2:9], v[216:223], v[134:137]
	v_mfma_f32_16x16x128_f8f6f4 v[130:133], v[192:199], v[216:223], v[130:133]
	v_mfma_f32_16x16x128_f8f6f4 v[98:101], v[208:215], v[216:223], v[98:101]
	v_mfma_f32_16x16x128_f8f6f4 v[102:105], v[200:207], v[216:223], v[102:105]
	v_mfma_f32_16x16x128_f8f6f4 v[94:97], v[200:207], v[224:231], v[94:97]
	v_mfma_f32_16x16x128_f8f6f4 v[90:93], v[208:215], v[224:231], v[90:93]
	v_mfma_f32_16x16x128_f8f6f4 v[122:125], v[192:199], v[224:231], v[122:125]
	v_mfma_f32_16x16x128_f8f6f4 v[126:129], v[2:9], v[224:231], v[126:129]
	s_setprio 0
	s_setprio 1
	v_mfma_f32_16x16x128_f8f6f4 v[118:121], v[2:9], v[232:239], v[118:121]
	v_mfma_f32_16x16x128_f8f6f4 v[114:117], v[192:199], v[232:239], v[114:117]
	v_mfma_f32_16x16x128_f8f6f4 v[82:85], v[208:215], v[232:239], v[82:85]
	v_mfma_f32_16x16x128_f8f6f4 v[86:89], v[200:207], v[232:239], v[86:89]
	v_mfma_f32_16x16x128_f8f6f4 v[78:81], v[200:207], v[242:249], v[78:81]
	v_mfma_f32_16x16x128_f8f6f4 v[74:77], v[208:215], v[242:249], v[74:77]
	v_mfma_f32_16x16x128_f8f6f4 v[106:109], v[192:199], v[242:249], v[106:109]
	v_mfma_f32_16x16x128_f8f6f4 v[110:113], v[2:9], v[242:249], v[110:113]
	s_barrier
	s_setprio 0
	s_mov_b32 m0, s70
	v_lshl_add_u64 v[174:175], v[174:175], 0, s[18:19]
	s_add_u32 s48, s48, 0x80080
	global_load_lds_dwordx4 v[174:175], off
	v_lshl_add_u64 v[174:175], v[176:177], 0, s[18:19]
	s_mov_b32 m0, s71
	s_addc_u32 s49, s49, 0
	global_load_lds_dwordx4 v[174:175], off
	v_lshl_add_u64 v[174:175], s[48:49], 0, v[156:157]
	s_mov_b32 m0, s74
	s_nop 0
	global_load_lds_dwordx4 v[174:175], off
	v_lshl_add_u64 v[174:175], s[48:49], 0, v[160:161]
	s_mov_b32 m0, s75
	s_nop 0
	global_load_lds_dwordx4 v[174:175], off
	v_lshl_add_u64 v[174:175], v[182:183], 0, s[18:19]
	s_mov_b32 m0, s72
	s_nop 0
	global_load_lds_dwordx4 v[174:175], off
	v_lshl_add_u64 v[174:175], v[184:185], 0, s[18:19]
	s_mov_b32 m0, s73
	s_nop 0
	global_load_lds_dwordx4 v[174:175], off
	ds_read_b128 v[216:219], v190 offset:49152
	ds_read_b128 v[220:223], v190 offset:50176
	ds_read_b128 v[224:227], v190 offset:51200
	ds_read_b128 v[228:231], v190 offset:52224
	ds_read_b128 v[232:235], v190 offset:53248
	ds_read_b128 v[236:239], v190 offset:54272
	ds_read_b128 v[242:245], v190 offset:55296
	ds_read_b128 v[246:249], v190 offset:56320
	s_waitcnt vmcnt(8)
	s_waitcnt lgkmcnt(0)
	s_setprio 1
	s_barrier
	v_mfma_f32_16x16x128_f8f6f4 v[70:73], v[2:9], v[216:223], v[70:73]
	v_mfma_f32_16x16x128_f8f6f4 v[66:69], v[192:199], v[216:223], v[66:69]
	v_mfma_f32_16x16x128_f8f6f4 v[34:37], v[208:215], v[216:223], v[34:37]
	v_mfma_f32_16x16x128_f8f6f4 v[38:41], v[200:207], v[216:223], v[38:41]
	v_mfma_f32_16x16x128_f8f6f4 v[30:33], v[200:207], v[224:231], v[30:33]
	v_mfma_f32_16x16x128_f8f6f4 v[26:29], v[208:215], v[224:231], v[26:29]
	v_mfma_f32_16x16x128_f8f6f4 v[58:61], v[192:199], v[224:231], v[58:61]
	v_mfma_f32_16x16x128_f8f6f4 v[62:65], v[2:9], v[224:231], v[62:65]
	s_setprio 0
	s_setprio 1
	v_mfma_f32_16x16x128_f8f6f4 v[54:57], v[2:9], v[232:239], v[54:57]
	v_mfma_f32_16x16x128_f8f6f4 v[50:53], v[192:199], v[232:239], v[50:53]
	v_mfma_f32_16x16x128_f8f6f4 v[18:21], v[208:215], v[232:239], v[18:21]
	v_mfma_f32_16x16x128_f8f6f4 v[22:25], v[200:207], v[232:239], v[22:25]
	v_mfma_f32_16x16x128_f8f6f4 v[14:17], v[200:207], v[242:249], v[14:17]
	v_mfma_f32_16x16x128_f8f6f4 v[10:13], v[208:215], v[242:249], v[10:13]
	v_mfma_f32_16x16x128_f8f6f4 v[42:45], v[192:199], v[242:249], v[42:45]
	v_mfma_f32_16x16x128_f8f6f4 v[46:49], v[2:9], v[242:249], v[46:49]
	s_barrier
	s_setprio 0
	s_cmp_lt_u32 s86, 3
	s_cbranch_scc1 .LBB0_796
	s_add_u32 s48, s55, s62
	s_addc_u32 s49, s61, s41
	s_add_u32 s46, s46, 0x80180
	s_addc_u32 s47, s47, 0
	s_add_u32 s41, s44, 0x200
	v_lshl_add_u64 v[174:175], v[172:173], 2, s[48:49]
	s_addc_u32 s50, s45, 0
	s_mov_b32 s51, 4
	s_cmp_eq_u32 s86, s51
	s_cselect_b64 s[44:45], -1, 0
	s_cmp_lg_u32 s86, s51
	s_cbranch_scc1 .LBB0_794

.LBB0_794:
	s_add_u32 s48, s46, 0xfff80080
	s_addc_u32 s49, s47, -1
	s_and_b64 s[44:45], s[44:45], exec
	s_cselect_b32 s44, s4, s41
	s_cselect_b32 s49, s1, s49
	s_cselect_b32 s48, s0, s48
	s_cselect_b32 s45, s5, s50
	s_mov_b32 m0, s37
	v_lshl_add_u64 v[176:177], s[46:47], 0, v[162:163]
	global_load_lds_dwordx4 v[176:177], off
	v_lshl_add_u64 v[176:177], s[46:47], 0, v[164:165]
	s_mov_b32 m0, s39
	s_nop 0
	global_load_lds_dwordx4 v[176:177], off
	ds_read_b128 v[2:5], v189
	ds_read_b128 v[6:9], v189 offset:1024
	ds_read_b128 v[192:195], v189 offset:2048
	ds_read_b128 v[196:199], v189 offset:3072
	ds_read_b128 v[200:203], v189 offset:16384
	ds_read_b128 v[204:207], v189 offset:17408
	ds_read_b128 v[208:211], v189 offset:18432
	ds_read_b128 v[212:215], v189 offset:19456
	ds_read_b128 v[216:219], v190
	ds_read_b128 v[220:223], v190 offset:1024
	ds_read_b128 v[224:227], v190 offset:2048
	ds_read_b128 v[228:231], v190 offset:3072
	ds_read_b128 v[232:235], v190 offset:4096
	ds_read_b128 v[236:239], v190 offset:5120
	ds_read_b128 v[242:245], v190 offset:6144
	ds_read_b128 v[246:249], v190 offset:7168
	s_waitcnt vmcnt(8)
	s_waitcnt lgkmcnt(0)
	s_setprio 1
	s_barrier
	v_mfma_f32_16x16x128_f8f6f4 v[134:137], v[2:9], v[216:223], v[134:137]
	v_mfma_f32_16x16x128_f8f6f4 v[130:133], v[192:199], v[216:223], v[130:133]
	v_mfma_f32_16x16x128_f8f6f4 v[98:101], v[208:215], v[216:223], v[98:101]
	v_mfma_f32_16x16x128_f8f6f4 v[102:105], v[200:207], v[216:223], v[102:105]
	v_mfma_f32_16x16x128_f8f6f4 v[94:97], v[200:207], v[224:231], v[94:97]
	v_mfma_f32_16x16x128_f8f6f4 v[90:93], v[208:215], v[224:231], v[90:93]
	v_mfma_f32_16x16x128_f8f6f4 v[122:125], v[192:199], v[224:231], v[122:125]
	v_mfma_f32_16x16x128_f8f6f4 v[126:129], v[2:9], v[224:231], v[126:129]
	s_setprio 0
	s_setprio 1
	v_mfma_f32_16x16x128_f8f6f4 v[118:121], v[2:9], v[232:239], v[118:121]
	v_mfma_f32_16x16x128_f8f6f4 v[114:117], v[192:199], v[232:239], v[114:117]
	v_mfma_f32_16x16x128_f8f6f4 v[82:85], v[208:215], v[232:239], v[82:85]
	v_mfma_f32_16x16x128_f8f6f4 v[86:89], v[200:207], v[232:239], v[86:89]
	v_mfma_f32_16x16x128_f8f6f4 v[78:81], v[200:207], v[242:249], v[78:81]
	v_mfma_f32_16x16x128_f8f6f4 v[74:77], v[208:215], v[242:249], v[74:77]
	v_mfma_f32_16x16x128_f8f6f4 v[106:109], v[192:199], v[242:249], v[106:109]
	v_mfma_f32_16x16x128_f8f6f4 v[110:113], v[2:9], v[242:249], v[110:113]
	s_barrier
	s_setprio 0
	s_mov_b32 m0, s9
	v_lshl_add_u64 v[176:177], s[44:45], 0, v[156:157]
	s_add_u32 s62, s44, 0x80000
	global_load_lds_dwordx4 v[176:177], off
	v_lshl_add_u64 v[182:183], s[44:45], 0, v[160:161]
	s_mov_b32 m0, s27
	s_addc_u32 s63, s45, 0
	global_load_lds_dwordx4 v[182:183], off
	v_lshl_add_u64 v[184:185], s[62:63], 0, v[156:157]
	s_mov_b32 m0, s33
	v_lshl_add_u64 v[186:187], s[48:49], 0, v[158:159]
	global_load_lds_dwordx4 v[184:185], off
	v_lshl_add_u64 v[184:185], s[62:63], 0, v[160:161]
	s_mov_b32 m0, s35
	s_nop 0
	global_load_lds_dwordx4 v[184:185], off
	v_lshl_add_u64 v[184:185], s[48:49], 0, v[154:155]
	s_mov_b32 m0, s8
	s_nop 0
	global_load_lds_dwordx4 v[184:185], off
	s_mov_b32 m0, s43
	s_nop 0
	global_load_lds_dwordx4 v[186:187], off
	ds_read_b128 v[216:219], v190 offset:16384
	ds_read_b128 v[220:223], v190 offset:17408
	ds_read_b128 v[224:227], v190 offset:18432
	ds_read_b128 v[228:231], v190 offset:19456
	ds_read_b128 v[232:235], v190 offset:20480
	ds_read_b128 v[236:239], v190 offset:21504
	ds_read_b128 v[242:245], v190 offset:22528
	ds_read_b128 v[246:249], v190 offset:23552
	s_waitcnt vmcnt(8)
	s_waitcnt lgkmcnt(0)
	s_setprio 1
	s_barrier
	v_mfma_f32_16x16x128_f8f6f4 v[70:73], v[2:9], v[216:223], v[70:73]
	v_mfma_f32_16x16x128_f8f6f4 v[66:69], v[192:199], v[216:223], v[66:69]
	v_mfma_f32_16x16x128_f8f6f4 v[34:37], v[208:215], v[216:223], v[34:37]
	v_mfma_f32_16x16x128_f8f6f4 v[38:41], v[200:207], v[216:223], v[38:41]
	v_mfma_f32_16x16x128_f8f6f4 v[30:33], v[200:207], v[224:231], v[30:33]
	v_mfma_f32_16x16x128_f8f6f4 v[26:29], v[208:215], v[224:231], v[26:29]
	v_mfma_f32_16x16x128_f8f6f4 v[58:61], v[192:199], v[224:231], v[58:61]
	v_mfma_f32_16x16x128_f8f6f4 v[62:65], v[2:9], v[224:231], v[62:65]
	s_setprio 0
	s_setprio 1
	v_mfma_f32_16x16x128_f8f6f4 v[54:57], v[2:9], v[232:239], v[54:57]
	v_mfma_f32_16x16x128_f8f6f4 v[50:53], v[192:199], v[232:239], v[50:53]
	v_mfma_f32_16x16x128_f8f6f4 v[18:21], v[208:215], v[232:239], v[18:21]
	v_mfma_f32_16x16x128_f8f6f4 v[22:25], v[200:207], v[232:239], v[22:25]
	v_mfma_f32_16x16x128_f8f6f4 v[14:17], v[200:207], v[242:249], v[14:17]
	v_mfma_f32_16x16x128_f8f6f4 v[10:13], v[208:215], v[242:249], v[10:13]
	v_mfma_f32_16x16x128_f8f6f4 v[42:45], v[192:199], v[242:249], v[42:45]
	v_mfma_f32_16x16x128_f8f6f4 v[46:49], v[2:9], v[242:249], v[46:49]
	s_barrier
	s_setprio 0
	s_add_u32 s48, s48, 0x80000
	s_addc_u32 s49, s49, 0
	s_mov_b32 m0, s52
	v_lshl_add_u64 v[252:253], s[48:49], 0, v[154:155]
	global_load_lds_dwordx4 v[252:253], off
	v_lshl_add_u64 v[252:253], s[48:49], 0, v[158:159]
	s_mov_b32 m0, s53
	s_nop 0
	global_load_lds_dwordx4 v[252:253], off
	ds_read_b128 v[192:195], v189 offset:32768
	ds_read_b128 v[196:199], v189 offset:33792
	ds_read_b128 v[200:203], v189 offset:34816
	ds_read_b128 v[204:207], v189 offset:35840
	ds_read_b128 v[2:5], v189 offset:49152
	ds_read_b128 v[6:9], v189 offset:50176
	ds_read_b128 v[208:211], v189 offset:51200
	ds_read_b128 v[212:215], v189 offset:52224
	ds_read_b128 v[216:219], v190 offset:32768
	ds_read_b128 v[220:223], v190 offset:33792
	ds_read_b128 v[224:227], v190 offset:34816
	ds_read_b128 v[228:231], v190 offset:35840
	ds_read_b128 v[232:235], v190 offset:36864
	ds_read_b128 v[236:239], v190 offset:37888
	ds_read_b128 v[242:245], v190 offset:38912
	ds_read_b128 v[246:249], v190 offset:39936
	s_waitcnt vmcnt(8)
	s_waitcnt lgkmcnt(0)
	s_setprio 1
	s_barrier
	v_mfma_f32_16x16x128_f8f6f4 v[134:137], v[192:199], v[216:223], v[134:137]
	v_mfma_f32_16x16x128_f8f6f4 v[130:133], v[200:207], v[216:223], v[130:133]
	v_mfma_f32_16x16x128_f8f6f4 v[98:101], v[208:215], v[216:223], v[98:101]
	v_mfma_f32_16x16x128_f8f6f4 v[102:105], v[2:9], v[216:223], v[102:105]
	v_mfma_f32_16x16x128_f8f6f4 v[94:97], v[2:9], v[224:231], v[94:97]
	v_mfma_f32_16x16x128_f8f6f4 v[90:93], v[208:215], v[224:231], v[90:93]
	v_mfma_f32_16x16x128_f8f6f4 v[122:125], v[200:207], v[224:231], v[122:125]
	v_mfma_f32_16x16x128_f8f6f4 v[126:129], v[192:199], v[224:231], v[126:129]
	s_setprio 0
	s_setprio 1
	v_mfma_f32_16x16x128_f8f6f4 v[118:121], v[192:199], v[232:239], v[118:121]
	v_mfma_f32_16x16x128_f8f6f4 v[114:117], v[200:207], v[232:239], v[114:117]
	v_mfma_f32_16x16x128_f8f6f4 v[82:85], v[208:215], v[232:239], v[82:85]
	v_mfma_f32_16x16x128_f8f6f4 v[86:89], v[2:9], v[232:239], v[86:89]
	v_mfma_f32_16x16x128_f8f6f4 v[78:81], v[2:9], v[242:249], v[78:81]
	v_mfma_f32_16x16x128_f8f6f4 v[74:77], v[208:215], v[242:249], v[74:77]
	v_mfma_f32_16x16x128_f8f6f4 v[106:109], v[200:207], v[242:249], v[106:109]
	v_mfma_f32_16x16x128_f8f6f4 v[110:113], v[192:199], v[242:249], v[110:113]
	s_barrier
	s_setprio 0
	s_mov_b32 m0, s70
	v_lshl_add_u64 v[176:177], v[176:177], 0, s[18:19]
	s_add_u32 s44, s44, 0x80080
	global_load_lds_dwordx4 v[176:177], off
	v_lshl_add_u64 v[176:177], v[182:183], 0, s[18:19]
	s_mov_b32 m0, s71
	s_addc_u32 s45, s45, 0
	global_load_lds_dwordx4 v[176:177], off
	v_lshl_add_u64 v[176:177], s[44:45], 0, v[156:157]
	s_mov_b32 m0, s74
	s_nop 0
	global_load_lds_dwordx4 v[176:177], off
	v_lshl_add_u64 v[176:177], s[44:45], 0, v[160:161]
	s_mov_b32 m0, s75
	s_nop 0
	global_load_lds_dwordx4 v[176:177], off
	v_lshl_add_u64 v[176:177], v[184:185], 0, s[18:19]
	s_mov_b32 m0, s72
	s_nop 0
	global_load_lds_dwordx4 v[176:177], off
	v_lshl_add_u64 v[176:177], v[186:187], 0, s[18:19]
	s_mov_b32 m0, s73
	s_nop 0
	global_load_lds_dwordx4 v[176:177], off
	ds_read_b128 v[216:219], v190 offset:49152
	ds_read_b128 v[220:223], v190 offset:50176
	ds_read_b128 v[224:227], v190 offset:51200
	ds_read_b128 v[228:231], v190 offset:52224
	ds_read_b128 v[232:235], v190 offset:53248
	ds_read_b128 v[236:239], v190 offset:54272
	ds_read_b128 v[242:245], v190 offset:55296
	ds_read_b128 v[246:249], v190 offset:56320
	s_waitcnt vmcnt(8)
	s_waitcnt lgkmcnt(0)
	s_setprio 1
	s_barrier
	v_mfma_f32_16x16x128_f8f6f4 v[70:73], v[192:199], v[216:223], v[70:73]
	v_mfma_f32_16x16x128_f8f6f4 v[66:69], v[200:207], v[216:223], v[66:69]
	v_mfma_f32_16x16x128_f8f6f4 v[34:37], v[208:215], v[216:223], v[34:37]
	v_mfma_f32_16x16x128_f8f6f4 v[38:41], v[2:9], v[216:223], v[38:41]
	v_mfma_f32_16x16x128_f8f6f4 v[30:33], v[2:9], v[224:231], v[30:33]
	v_mfma_f32_16x16x128_f8f6f4 v[26:29], v[208:215], v[224:231], v[26:29]
	v_mfma_f32_16x16x128_f8f6f4 v[58:61], v[200:207], v[224:231], v[58:61]
	v_mfma_f32_16x16x128_f8f6f4 v[62:65], v[192:199], v[224:231], v[62:65]
	s_setprio 0
	s_setprio 1
	v_mfma_f32_16x16x128_f8f6f4 v[54:57], v[192:199], v[232:239], v[54:57]
	v_mfma_f32_16x16x128_f8f6f4 v[50:53], v[200:207], v[232:239], v[50:53]
	v_mfma_f32_16x16x128_f8f6f4 v[18:21], v[208:215], v[232:239], v[18:21]
	v_mfma_f32_16x16x128_f8f6f4 v[22:25], v[2:9], v[232:239], v[22:25]
	v_mfma_f32_16x16x128_f8f6f4 v[14:17], v[2:9], v[242:249], v[14:17]
	v_mfma_f32_16x16x128_f8f6f4 v[10:13], v[208:215], v[242:249], v[10:13]
	v_mfma_f32_16x16x128_f8f6f4 v[42:45], v[200:207], v[242:249], v[42:45]
	v_mfma_f32_16x16x128_f8f6f4 v[46:49], v[192:199], v[242:249], v[46:49]
	s_barrier
	s_setprio 0
	s_add_i32 s44, s51, 2
	s_add_u32 s46, s46, 0x100
	s_addc_u32 s47, s47, 0
	s_add_u32 s41, s41, 0x100
	s_addc_u32 s50, s50, 0
	s_cmp_ge_i32 s51, s86
	s_cbranch_scc1 .LBB0_796
	s_mov_b32 s51, s44
	s_cmp_eq_u32 s86, s51
	s_cselect_b64 s[44:45], -1, 0
	s_cmp_lg_u32 s86, s51
	s_cbranch_scc0 .LBB0_793
	s_branch .LBB0_794

.LBB0_946:
	s_ashr_i32 s37, s36, 31
	s_lshl_b64 s[38:39], s[36:37], 20
	s_add_u32 s38, s22, s38
	s_addc_u32 s39, s23, s39
	s_and_b64 s[40:41], s[2:3], exec
	s_cselect_b32 s37, s39, s47
	s_cselect_b32 s84, s38, s46
	s_ashr_i32 s27, s26, 31
	s_lshl_b64 s[40:41], s[26:27], 20
	s_add_u32 s40, s25, s40
	s_addc_u32 s41, s35, s41
	s_and_b64 s[48:49], s[2:3], exec
	s_cselect_b32 s27, s41, s45
	s_cselect_b32 s85, s40, s44
	s_add_u32 s48, s46, 0x80080
	s_addc_u32 s49, s47, 0
	s_mov_b32 m0, s80
	v_lshl_add_u64 v[218:219], s[48:49], 0, v[164:165]
	global_load_lds_dwordx4 v[218:219], off
	v_lshl_add_u64 v[218:219], s[48:49], 0, v[168:169]
	s_mov_b32 m0, s81
	s_nop 0
	global_load_lds_dwordx4 v[218:219], off
	ds_read_b128 v[18:21], v192
	ds_read_b128 v[22:25], v192 offset:1024
	ds_read_b128 v[26:29], v192 offset:2048
	ds_read_b128 v[30:33], v192 offset:3072
	ds_read_b128 v[2:5], v192 offset:16384
	ds_read_b128 v[6:9], v192 offset:17408
	ds_read_b128 v[10:13], v192 offset:18432
	ds_read_b128 v[14:17], v192 offset:19456
	ds_read_b128 v[184:187], v193
	ds_read_b128 v[188:191], v193 offset:1024
	ds_read_b128 v[194:197], v193 offset:2048
	ds_read_b128 v[198:201], v193 offset:3072
	ds_read_b128 v[202:205], v193 offset:4096
	ds_read_b128 v[206:209], v193 offset:5120
	ds_read_b128 v[210:213], v193 offset:6144
	ds_read_b128 v[214:217], v193 offset:7168
	s_waitcnt vmcnt(8)
	s_waitcnt lgkmcnt(0)
	s_setprio 1
	s_barrier
	v_mfma_f32_16x16x128_f8f6f4 v[158:161], v[18:25], v[184:191], 0
	v_mfma_f32_16x16x128_f8f6f4 v[154:157], v[26:33], v[184:191], 0
	v_mfma_f32_16x16x128_f8f6f4 v[122:125], v[10:17], v[184:191], 0
	v_mfma_f32_16x16x128_f8f6f4 v[126:129], v[2:9], v[184:191], 0
	v_mfma_f32_16x16x128_f8f6f4 v[118:121], v[2:9], v[194:201], 0
	v_mfma_f32_16x16x128_f8f6f4 v[114:117], v[10:17], v[194:201], 0
	v_mfma_f32_16x16x128_f8f6f4 v[146:149], v[26:33], v[194:201], 0
	v_mfma_f32_16x16x128_f8f6f4 v[150:153], v[18:25], v[194:201], 0
	s_setprio 0
	s_setprio 1
	v_mfma_f32_16x16x128_f8f6f4 v[142:145], v[18:25], v[202:209], 0
	v_mfma_f32_16x16x128_f8f6f4 v[138:141], v[26:33], v[202:209], 0
	v_mfma_f32_16x16x128_f8f6f4 v[106:109], v[10:17], v[202:209], 0
	v_mfma_f32_16x16x128_f8f6f4 v[110:113], v[2:9], v[202:209], 0
	v_mfma_f32_16x16x128_f8f6f4 v[102:105], v[2:9], v[210:217], 0
	v_mfma_f32_16x16x128_f8f6f4 v[98:101], v[10:17], v[210:217], 0
	v_mfma_f32_16x16x128_f8f6f4 v[130:133], v[26:33], v[210:217], 0
	v_mfma_f32_16x16x128_f8f6f4 v[134:137], v[18:25], v[210:217], 0
	s_barrier
	s_setprio 0
	v_lshl_add_u64 v[184:185], s[44:45], 0, v[166:167]
	s_mov_b32 m0, s52
	v_lshl_add_u64 v[186:187], v[184:185], 0, s[14:15]
	global_load_lds_dwordx4 v[186:187], off
	v_lshl_add_u64 v[186:187], s[44:45], 0, v[170:171]
	s_add_u32 s48, s44, 0x80100
	v_lshl_add_u64 v[188:189], v[186:187], 0, s[14:15]
	s_mov_b32 m0, s53
	s_addc_u32 s49, s45, 0
	global_load_lds_dwordx4 v[188:189], off
	v_lshl_add_u64 v[188:189], s[48:49], 0, v[166:167]
	s_mov_b32 m0, s54
	s_nop 0
	global_load_lds_dwordx4 v[188:189], off
	v_lshl_add_u64 v[188:189], s[48:49], 0, v[170:171]
	s_mov_b32 m0, s55
	s_nop 0
	global_load_lds_dwordx4 v[188:189], off
	v_lshl_add_u64 v[188:189], s[46:47], 0, v[164:165]
	v_lshl_add_u64 v[190:191], v[188:189], 0, s[14:15]
	s_mov_b32 m0, s43
	s_nop 0
	global_load_lds_dwordx4 v[190:191], off
	v_lshl_add_u64 v[190:191], s[46:47], 0, v[168:169]
	v_lshl_add_u64 v[226:227], v[190:191], 0, s[14:15]
	s_mov_b32 m0, s61
	s_nop 0
	global_load_lds_dwordx4 v[226:227], off
	ds_read_b128 v[194:197], v193 offset:16384
	ds_read_b128 v[198:201], v193 offset:17408
	ds_read_b128 v[202:205], v193 offset:18432
	ds_read_b128 v[206:209], v193 offset:19456
	ds_read_b128 v[210:213], v193 offset:20480
	ds_read_b128 v[214:217], v193 offset:21504
	ds_read_b128 v[218:221], v193 offset:22528
	ds_read_b128 v[222:225], v193 offset:23552
	s_waitcnt vmcnt(8)
	s_waitcnt lgkmcnt(0)
	s_setprio 1
	s_barrier
	v_mfma_f32_16x16x128_f8f6f4 v[94:97], v[18:25], v[194:201], 0
	v_mfma_f32_16x16x128_f8f6f4 v[90:93], v[26:33], v[194:201], 0
	v_mfma_f32_16x16x128_f8f6f4 v[58:61], v[10:17], v[194:201], 0
	v_mfma_f32_16x16x128_f8f6f4 v[62:65], v[2:9], v[194:201], 0
	v_mfma_f32_16x16x128_f8f6f4 v[54:57], v[2:9], v[202:209], 0
	v_mfma_f32_16x16x128_f8f6f4 v[50:53], v[10:17], v[202:209], 0
	v_mfma_f32_16x16x128_f8f6f4 v[82:85], v[26:33], v[202:209], 0
	v_mfma_f32_16x16x128_f8f6f4 v[86:89], v[18:25], v[202:209], 0
	s_setprio 0
	s_setprio 1
	v_mfma_f32_16x16x128_f8f6f4 v[78:81], v[18:25], v[210:217], 0
	v_mfma_f32_16x16x128_f8f6f4 v[74:77], v[26:33], v[210:217], 0
	v_mfma_f32_16x16x128_f8f6f4 v[42:45], v[10:17], v[210:217], 0
	v_mfma_f32_16x16x128_f8f6f4 v[46:49], v[2:9], v[210:217], 0
	v_mfma_f32_16x16x128_f8f6f4 v[38:41], v[2:9], v[218:225], 0
	v_mfma_f32_16x16x128_f8f6f4 v[34:37], v[10:17], v[218:225], 0
	v_mfma_f32_16x16x128_f8f6f4 v[66:69], v[26:33], v[218:225], 0
	v_mfma_f32_16x16x128_f8f6f4 v[70:73], v[18:25], v[218:225], 0
	s_barrier
	s_setprio 0
	s_add_u32 s48, s46, 0x80100
	s_addc_u32 s49, s47, 0
	s_mov_b32 m0, s68
	v_lshl_add_u64 v[226:227], s[48:49], 0, v[164:165]
	global_load_lds_dwordx4 v[226:227], off
	v_lshl_add_u64 v[226:227], s[48:49], 0, v[168:169]
	s_mov_b32 m0, s69
	s_nop 0
	global_load_lds_dwordx4 v[226:227], off
	ds_read_b128 v[18:21], v192 offset:32768
	ds_read_b128 v[22:25], v192 offset:33792
	ds_read_b128 v[26:29], v192 offset:34816
	ds_read_b128 v[30:33], v192 offset:35840
	ds_read_b128 v[2:5], v192 offset:49152
	ds_read_b128 v[6:9], v192 offset:50176
	ds_read_b128 v[10:13], v192 offset:51200
	ds_read_b128 v[14:17], v192 offset:52224
	ds_read_b128 v[194:197], v193 offset:32768
	ds_read_b128 v[198:201], v193 offset:33792
	ds_read_b128 v[202:205], v193 offset:34816
	ds_read_b128 v[206:209], v193 offset:35840
	ds_read_b128 v[210:213], v193 offset:36864
	ds_read_b128 v[214:217], v193 offset:37888
	ds_read_b128 v[218:221], v193 offset:38912
	ds_read_b128 v[222:225], v193 offset:39936
	s_waitcnt vmcnt(8)
	s_waitcnt lgkmcnt(0)
	s_setprio 1
	s_barrier
	v_mfma_f32_16x16x128_f8f6f4 v[158:161], v[18:25], v[194:201], v[158:161]
	v_mfma_f32_16x16x128_f8f6f4 v[154:157], v[26:33], v[194:201], v[154:157]
	v_mfma_f32_16x16x128_f8f6f4 v[122:125], v[10:17], v[194:201], v[122:125]
	v_mfma_f32_16x16x128_f8f6f4 v[126:129], v[2:9], v[194:201], v[126:129]
	v_mfma_f32_16x16x128_f8f6f4 v[118:121], v[2:9], v[202:209], v[118:121]
	v_mfma_f32_16x16x128_f8f6f4 v[114:117], v[10:17], v[202:209], v[114:117]
	v_mfma_f32_16x16x128_f8f6f4 v[146:149], v[26:33], v[202:209], v[146:149]
	v_mfma_f32_16x16x128_f8f6f4 v[150:153], v[18:25], v[202:209], v[150:153]
	s_setprio 0
	s_setprio 1
	v_mfma_f32_16x16x128_f8f6f4 v[142:145], v[18:25], v[210:217], v[142:145]
	v_mfma_f32_16x16x128_f8f6f4 v[138:141], v[26:33], v[210:217], v[138:141]
	v_mfma_f32_16x16x128_f8f6f4 v[106:109], v[10:17], v[210:217], v[106:109]
	v_mfma_f32_16x16x128_f8f6f4 v[110:113], v[2:9], v[210:217], v[110:113]
	v_mfma_f32_16x16x128_f8f6f4 v[102:105], v[2:9], v[218:225], v[102:105]
	v_mfma_f32_16x16x128_f8f6f4 v[98:101], v[10:17], v[218:225], v[98:101]
	v_mfma_f32_16x16x128_f8f6f4 v[130:133], v[26:33], v[218:225], v[130:133]
	v_mfma_f32_16x16x128_f8f6f4 v[134:137], v[18:25], v[218:225], v[134:137]
	s_barrier
	s_setprio 0
	s_mov_b32 m0, s74
	v_lshl_add_u64 v[184:185], v[184:185], 0, s[18:19]
	s_add_u32 s48, s44, 0x80180
	global_load_lds_dwordx4 v[184:185], off
	v_lshl_add_u64 v[184:185], v[186:187], 0, s[18:19]
	s_mov_b32 m0, s75
	s_addc_u32 s49, s45, 0
	global_load_lds_dwordx4 v[184:185], off
	v_lshl_add_u64 v[184:185], s[48:49], 0, v[166:167]
	s_mov_b32 m0, s78
	s_nop 0
	global_load_lds_dwordx4 v[184:185], off
	v_lshl_add_u64 v[184:185], s[48:49], 0, v[170:171]
	s_mov_b32 m0, s79
	s_nop 0
	global_load_lds_dwordx4 v[184:185], off
	v_lshl_add_u64 v[184:185], v[188:189], 0, s[18:19]
	s_mov_b32 m0, s76
	s_nop 0
	global_load_lds_dwordx4 v[184:185], off
	v_lshl_add_u64 v[184:185], v[190:191], 0, s[18:19]
	s_mov_b32 m0, s77
	s_nop 0
	global_load_lds_dwordx4 v[184:185], off
	ds_read_b128 v[194:197], v193 offset:49152
	ds_read_b128 v[198:201], v193 offset:50176
	ds_read_b128 v[202:205], v193 offset:51200
	ds_read_b128 v[206:209], v193 offset:52224
	ds_read_b128 v[210:213], v193 offset:53248
	ds_read_b128 v[214:217], v193 offset:54272
	ds_read_b128 v[218:221], v193 offset:55296
	ds_read_b128 v[222:225], v193 offset:56320
	s_waitcnt vmcnt(8)
	s_waitcnt lgkmcnt(0)
	s_setprio 1
	s_barrier
	v_mfma_f32_16x16x128_f8f6f4 v[94:97], v[18:25], v[194:201], v[94:97]
	v_mfma_f32_16x16x128_f8f6f4 v[90:93], v[26:33], v[194:201], v[90:93]
	v_mfma_f32_16x16x128_f8f6f4 v[58:61], v[10:17], v[194:201], v[58:61]
	v_mfma_f32_16x16x128_f8f6f4 v[62:65], v[2:9], v[194:201], v[62:65]
	v_mfma_f32_16x16x128_f8f6f4 v[54:57], v[2:9], v[202:209], v[54:57]
	v_mfma_f32_16x16x128_f8f6f4 v[50:53], v[10:17], v[202:209], v[50:53]
	v_mfma_f32_16x16x128_f8f6f4 v[82:85], v[26:33], v[202:209], v[82:85]
	v_mfma_f32_16x16x128_f8f6f4 v[86:89], v[18:25], v[202:209], v[86:89]
	s_setprio 0
	s_setprio 1
	v_mfma_f32_16x16x128_f8f6f4 v[78:81], v[18:25], v[210:217], v[78:81]
	v_mfma_f32_16x16x128_f8f6f4 v[74:77], v[26:33], v[210:217], v[74:77]
	v_mfma_f32_16x16x128_f8f6f4 v[42:45], v[10:17], v[210:217], v[42:45]
	v_mfma_f32_16x16x128_f8f6f4 v[46:49], v[2:9], v[210:217], v[46:49]
	v_mfma_f32_16x16x128_f8f6f4 v[38:41], v[2:9], v[218:225], v[38:41]
	v_mfma_f32_16x16x128_f8f6f4 v[34:37], v[10:17], v[218:225], v[34:37]
	v_mfma_f32_16x16x128_f8f6f4 v[66:69], v[26:33], v[218:225], v[66:69]
	v_mfma_f32_16x16x128_f8f6f4 v[70:73], v[18:25], v[218:225], v[70:73]
	s_barrier
	s_setprio 0
	s_add_u32 s46, s46, 0x80180
	s_addc_u32 s47, s47, 0
	s_add_u32 s62, s44, 0x200
	s_addc_u32 s63, s45, 0
	s_mov_b32 s86, 0
.LBB0_947:
	s_add_u32 s44, s46, 0xfff80080
	s_addc_u32 s45, s47, -1
	s_cmp_eq_u32 s86, 28
	s_cselect_b32 s49, s37, s45
	s_cselect_b32 s48, s84, s44
	s_cselect_b32 s45, s27, s63
	s_cselect_b32 s44, s85, s62
	s_mov_b32 m0, s80
	v_lshl_add_u64 v[218:219], s[46:47], 0, v[172:173]
	global_load_lds_dwordx4 v[218:219], off
	v_lshl_add_u64 v[218:219], s[46:47], 0, v[174:175]
	s_mov_b32 m0, s81
	s_nop 0
	global_load_lds_dwordx4 v[218:219], off
	ds_read_b128 v[2:5], v192
	ds_read_b128 v[6:9], v192 offset:1024
	ds_read_b128 v[18:21], v192 offset:2048
	ds_read_b128 v[22:25], v192 offset:3072
	ds_read_b128 v[26:29], v192 offset:16384
	ds_read_b128 v[30:33], v192 offset:17408
	ds_read_b128 v[184:187], v192 offset:18432
	ds_read_b128 v[188:191], v192 offset:19456
	ds_read_b128 v[10:13], v193
	ds_read_b128 v[14:17], v193 offset:1024
	ds_read_b128 v[194:197], v193 offset:2048
	ds_read_b128 v[198:201], v193 offset:3072
	ds_read_b128 v[202:205], v193 offset:4096
	ds_read_b128 v[206:209], v193 offset:5120
	ds_read_b128 v[210:213], v193 offset:6144
	ds_read_b128 v[214:217], v193 offset:7168
	s_waitcnt vmcnt(8)
	s_waitcnt lgkmcnt(0)
	s_setprio 1
	s_barrier
	v_mfma_f32_16x16x128_f8f6f4 v[158:161], v[2:9], v[10:17], v[158:161]
	v_mfma_f32_16x16x128_f8f6f4 v[154:157], v[18:25], v[10:17], v[154:157]
	v_mfma_f32_16x16x128_f8f6f4 v[122:125], v[184:191], v[10:17], v[122:125]
	v_mfma_f32_16x16x128_f8f6f4 v[126:129], v[26:33], v[10:17], v[126:129]
	v_mfma_f32_16x16x128_f8f6f4 v[118:121], v[26:33], v[194:201], v[118:121]
	v_mfma_f32_16x16x128_f8f6f4 v[114:117], v[184:191], v[194:201], v[114:117]
	v_mfma_f32_16x16x128_f8f6f4 v[146:149], v[18:25], v[194:201], v[146:149]
	v_mfma_f32_16x16x128_f8f6f4 v[150:153], v[2:9], v[194:201], v[150:153]
	s_setprio 0
	s_setprio 1
	v_mfma_f32_16x16x128_f8f6f4 v[142:145], v[2:9], v[202:209], v[142:145]
	v_mfma_f32_16x16x128_f8f6f4 v[138:141], v[18:25], v[202:209], v[138:141]
	v_mfma_f32_16x16x128_f8f6f4 v[106:109], v[184:191], v[202:209], v[106:109]
	v_mfma_f32_16x16x128_f8f6f4 v[110:113], v[26:33], v[202:209], v[110:113]
	v_mfma_f32_16x16x128_f8f6f4 v[102:105], v[26:33], v[210:217], v[102:105]
	v_mfma_f32_16x16x128_f8f6f4 v[98:101], v[184:191], v[210:217], v[98:101]
	v_mfma_f32_16x16x128_f8f6f4 v[130:133], v[18:25], v[210:217], v[130:133]
	v_mfma_f32_16x16x128_f8f6f4 v[134:137], v[2:9], v[210:217], v[134:137]
	s_barrier
	s_setprio 0
	s_mov_b32 m0, s52
	v_lshl_add_u64 v[10:11], s[44:45], 0, v[166:167]
	s_add_u32 s88, s44, 0x80000
	global_load_lds_dwordx4 v[10:11], off
	v_lshl_add_u64 v[12:13], s[44:45], 0, v[170:171]
	s_mov_b32 m0, s53
	s_addc_u32 s89, s45, 0
	global_load_lds_dwordx4 v[12:13], off
	v_lshl_add_u64 v[14:15], s[88:89], 0, v[166:167]
	s_mov_b32 m0, s54
	v_lshl_add_u64 v[16:17], s[48:49], 0, v[168:169]
	global_load_lds_dwordx4 v[14:15], off
	v_lshl_add_u64 v[14:15], s[88:89], 0, v[170:171]
	s_mov_b32 m0, s55
	s_nop 0
	global_load_lds_dwordx4 v[14:15], off
	v_lshl_add_u64 v[14:15], s[48:49], 0, v[164:165]
	s_mov_b32 m0, s43
	s_nop 0
	global_load_lds_dwordx4 v[14:15], off
	s_mov_b32 m0, s61
	s_nop 0
	global_load_lds_dwordx4 v[16:17], off
	ds_read_b128 v[194:197], v193 offset:16384
	ds_read_b128 v[198:201], v193 offset:17408
	ds_read_b128 v[202:205], v193 offset:18432
	ds_read_b128 v[206:209], v193 offset:19456
	ds_read_b128 v[210:213], v193 offset:20480
	ds_read_b128 v[214:217], v193 offset:21504
	ds_read_b128 v[218:221], v193 offset:22528
	ds_read_b128 v[222:225], v193 offset:23552
	s_waitcnt vmcnt(8)
	s_waitcnt lgkmcnt(0)
	s_setprio 1
	s_barrier
	v_mfma_f32_16x16x128_f8f6f4 v[94:97], v[2:9], v[194:201], v[94:97]
	v_mfma_f32_16x16x128_f8f6f4 v[90:93], v[18:25], v[194:201], v[90:93]
	v_mfma_f32_16x16x128_f8f6f4 v[58:61], v[184:191], v[194:201], v[58:61]
	v_mfma_f32_16x16x128_f8f6f4 v[62:65], v[26:33], v[194:201], v[62:65]
	v_mfma_f32_16x16x128_f8f6f4 v[54:57], v[26:33], v[202:209], v[54:57]
	v_mfma_f32_16x16x128_f8f6f4 v[50:53], v[184:191], v[202:209], v[50:53]
	v_mfma_f32_16x16x128_f8f6f4 v[82:85], v[18:25], v[202:209], v[82:85]
	v_mfma_f32_16x16x128_f8f6f4 v[86:89], v[2:9], v[202:209], v[86:89]
	s_setprio 0
	s_setprio 1
	v_mfma_f32_16x16x128_f8f6f4 v[78:81], v[2:9], v[210:217], v[78:81]
	v_mfma_f32_16x16x128_f8f6f4 v[74:77], v[18:25], v[210:217], v[74:77]
	v_mfma_f32_16x16x128_f8f6f4 v[42:45], v[184:191], v[210:217], v[42:45]
	v_mfma_f32_16x16x128_f8f6f4 v[46:49], v[26:33], v[210:217], v[46:49]
	v_mfma_f32_16x16x128_f8f6f4 v[38:41], v[26:33], v[218:225], v[38:41]
	v_mfma_f32_16x16x128_f8f6f4 v[34:37], v[184:191], v[218:225], v[34:37]
	v_mfma_f32_16x16x128_f8f6f4 v[66:69], v[18:25], v[218:225], v[66:69]
	v_mfma_f32_16x16x128_f8f6f4 v[70:73], v[2:9], v[218:225], v[70:73]
	s_barrier
	s_setprio 0
	s_add_u32 s48, s48, 0x80000
	s_addc_u32 s49, s49, 0
	s_mov_b32 m0, s68
	v_lshl_add_u64 v[226:227], s[48:49], 0, v[164:165]
	global_load_lds_dwordx4 v[226:227], off
	v_lshl_add_u64 v[226:227], s[48:49], 0, v[168:169]
	s_mov_b32 m0, s69
	s_nop 0
	global_load_lds_dwordx4 v[226:227], off
	ds_read_b128 v[18:21], v192 offset:32768
	ds_read_b128 v[22:25], v192 offset:33792
	ds_read_b128 v[26:29], v192 offset:34816
	ds_read_b128 v[30:33], v192 offset:35840
	ds_read_b128 v[2:5], v192 offset:49152
	ds_read_b128 v[6:9], v192 offset:50176
	ds_read_b128 v[184:187], v192 offset:51200
	ds_read_b128 v[188:191], v192 offset:52224
	ds_read_b128 v[194:197], v193 offset:32768
	ds_read_b128 v[198:201], v193 offset:33792
	ds_read_b128 v[202:205], v193 offset:34816
	ds_read_b128 v[206:209], v193 offset:35840
	ds_read_b128 v[210:213], v193 offset:36864
	ds_read_b128 v[214:217], v193 offset:37888
	ds_read_b128 v[218:221], v193 offset:38912
	ds_read_b128 v[222:225], v193 offset:39936
	s_waitcnt vmcnt(8)
	s_waitcnt lgkmcnt(0)
	s_setprio 1
	s_barrier
	v_mfma_f32_16x16x128_f8f6f4 v[158:161], v[18:25], v[194:201], v[158:161]
	v_mfma_f32_16x16x128_f8f6f4 v[154:157], v[26:33], v[194:201], v[154:157]
	v_mfma_f32_16x16x128_f8f6f4 v[122:125], v[184:191], v[194:201], v[122:125]
	v_mfma_f32_16x16x128_f8f6f4 v[126:129], v[2:9], v[194:201], v[126:129]
	v_mfma_f32_16x16x128_f8f6f4 v[118:121], v[2:9], v[202:209], v[118:121]
	v_mfma_f32_16x16x128_f8f6f4 v[114:117], v[184:191], v[202:209], v[114:117]
	v_mfma_f32_16x16x128_f8f6f4 v[146:149], v[26:33], v[202:209], v[146:149]
	v_mfma_f32_16x16x128_f8f6f4 v[150:153], v[18:25], v[202:209], v[150:153]
	s_setprio 0
	s_setprio 1
	v_mfma_f32_16x16x128_f8f6f4 v[142:145], v[18:25], v[210:217], v[142:145]
	v_mfma_f32_16x16x128_f8f6f4 v[138:141], v[26:33], v[210:217], v[138:141]
	v_mfma_f32_16x16x128_f8f6f4 v[106:109], v[184:191], v[210:217], v[106:109]
	v_mfma_f32_16x16x128_f8f6f4 v[110:113], v[2:9], v[210:217], v[110:113]
	v_mfma_f32_16x16x128_f8f6f4 v[102:105], v[2:9], v[218:225], v[102:105]
	v_mfma_f32_16x16x128_f8f6f4 v[98:101], v[184:191], v[218:225], v[98:101]
	v_mfma_f32_16x16x128_f8f6f4 v[130:133], v[26:33], v[218:225], v[130:133]
	v_mfma_f32_16x16x128_f8f6f4 v[134:137], v[18:25], v[218:225], v[134:137]
	s_barrier
	s_setprio 0
	s_mov_b32 m0, s74
	v_lshl_add_u64 v[10:11], v[10:11], 0, s[4:5]
	s_add_u32 s44, s44, 0x80080
	global_load_lds_dwordx4 v[10:11], off
	v_lshl_add_u64 v[10:11], v[12:13], 0, s[4:5]
	s_mov_b32 m0, s75
	s_addc_u32 s45, s45, 0
	global_load_lds_dwordx4 v[10:11], off
	v_lshl_add_u64 v[10:11], s[44:45], 0, v[166:167]
	s_mov_b32 m0, s78
	s_nop 0
	global_load_lds_dwordx4 v[10:11], off
	v_lshl_add_u64 v[10:11], s[44:45], 0, v[170:171]
	s_mov_b32 m0, s79
	s_nop 0
	global_load_lds_dwordx4 v[10:11], off
	v_lshl_add_u64 v[10:11], v[14:15], 0, s[4:5]
	s_mov_b32 m0, s76
	s_nop 0
	global_load_lds_dwordx4 v[10:11], off
	v_lshl_add_u64 v[10:11], v[16:17], 0, s[4:5]
	s_mov_b32 m0, s77
	s_nop 0
	global_load_lds_dwordx4 v[10:11], off
	ds_read_b128 v[194:197], v193 offset:49152
	ds_read_b128 v[198:201], v193 offset:50176
	ds_read_b128 v[202:205], v193 offset:51200
	ds_read_b128 v[206:209], v193 offset:52224
	ds_read_b128 v[210:213], v193 offset:53248
	ds_read_b128 v[214:217], v193 offset:54272
	ds_read_b128 v[218:221], v193 offset:55296
	ds_read_b128 v[222:225], v193 offset:56320
	s_waitcnt vmcnt(8)
	s_waitcnt lgkmcnt(0)
	s_setprio 1
	s_barrier
	v_mfma_f32_16x16x128_f8f6f4 v[94:97], v[18:25], v[194:201], v[94:97]
	v_mfma_f32_16x16x128_f8f6f4 v[90:93], v[26:33], v[194:201], v[90:93]
	v_mfma_f32_16x16x128_f8f6f4 v[58:61], v[184:191], v[194:201], v[58:61]
	v_mfma_f32_16x16x128_f8f6f4 v[62:65], v[2:9], v[194:201], v[62:65]
	v_mfma_f32_16x16x128_f8f6f4 v[54:57], v[2:9], v[202:209], v[54:57]
	v_mfma_f32_16x16x128_f8f6f4 v[50:53], v[184:191], v[202:209], v[50:53]
	v_mfma_f32_16x16x128_f8f6f4 v[82:85], v[26:33], v[202:209], v[82:85]
	v_mfma_f32_16x16x128_f8f6f4 v[86:89], v[18:25], v[202:209], v[86:89]
	s_setprio 0
	s_setprio 1
	v_mfma_f32_16x16x128_f8f6f4 v[78:81], v[18:25], v[210:217], v[78:81]
	v_mfma_f32_16x16x128_f8f6f4 v[74:77], v[26:33], v[210:217], v[74:77]
	v_mfma_f32_16x16x128_f8f6f4 v[42:45], v[184:191], v[210:217], v[42:45]
	v_mfma_f32_16x16x128_f8f6f4 v[46:49], v[2:9], v[210:217], v[46:49]
	v_mfma_f32_16x16x128_f8f6f4 v[38:41], v[2:9], v[218:225], v[38:41]
	v_mfma_f32_16x16x128_f8f6f4 v[34:37], v[184:191], v[218:225], v[34:37]
	v_mfma_f32_16x16x128_f8f6f4 v[66:69], v[26:33], v[218:225], v[66:69]
	v_mfma_f32_16x16x128_f8f6f4 v[70:73], v[18:25], v[218:225], v[70:73]
	s_barrier
	s_setprio 0
	s_add_i32 s86, s86, 2
	s_add_u32 s46, s46, 0x100
	s_addc_u32 s47, s47, 0
	s_add_u32 s62, s62, 0x100
	s_addc_u32 s63, s63, 0
	s_cmp_gt_u32 s86, 29
	s_cbranch_scc0 .LBB0_947
	s_and_b64 vcc, exec, s[6:7]
	s_cbranch_vccz .LBB0_950
	s_barrier

.LBB0_1031:
	s_add_u32 s25, s36, 0x100
	s_addc_u32 s83, s37, 0
	s_and_b64 s[40:41], s[38:39], exec
	s_cselect_b32 s41, s1, s83
	s_cselect_b32 s40, s0, s25
	s_add_u32 s25, s26, 0x100
	s_addc_u32 s83, s27, 0
	s_and_b64 s[38:39], s[38:39], exec
	s_cselect_b32 s39, s5, s83
	s_cselect_b32 s38, s4, s25
	s_add_u32 s84, s36, 0x158080
	s_addc_u32 s85, s37, 0
	s_add_i32 s25, s23, 0xc000
	v_lshl_add_u64 v[174:175], s[84:85], 0, v[154:155]
	s_mov_b32 m0, s25
	s_add_i32 s83, s23, 0xe000
	global_load_lds_dwordx4 v[174:175], off
	v_lshl_add_u64 v[174:175], s[84:85], 0, v[158:159]
	s_mov_b32 m0, s83
	s_nop 0
	global_load_lds_dwordx4 v[174:175], off
	ds_read_b128 v[2:5], v189
	ds_read_b128 v[6:9], v189 offset:1024
	ds_read_b128 v[192:195], v189 offset:2048
	ds_read_b128 v[196:199], v189 offset:3072
	ds_read_b128 v[200:203], v189 offset:16384
	ds_read_b128 v[204:207], v189 offset:17408
	ds_read_b128 v[208:211], v189 offset:18432
	ds_read_b128 v[212:215], v189 offset:19456
	ds_read_b128 v[216:219], v190
	ds_read_b128 v[220:223], v190 offset:1024
	ds_read_b128 v[224:227], v190 offset:2048
	ds_read_b128 v[228:231], v190 offset:3072
	ds_read_b128 v[232:235], v190 offset:4096
	ds_read_b128 v[236:239], v190 offset:5120
	ds_read_b128 v[240:243], v190 offset:6144
	ds_read_b128 v[244:247], v190 offset:7168
	s_waitcnt vmcnt(8)
	s_waitcnt lgkmcnt(0)
	s_setprio 1
	s_barrier
	v_mfma_f32_16x16x128_f8f6f4 v[134:137], v[2:9], v[216:223], 0
	v_mfma_f32_16x16x128_f8f6f4 v[130:133], v[192:199], v[216:223], 0
	v_mfma_f32_16x16x128_f8f6f4 v[98:101], v[208:215], v[216:223], 0
	v_mfma_f32_16x16x128_f8f6f4 v[102:105], v[200:207], v[216:223], 0
	v_mfma_f32_16x16x128_f8f6f4 v[94:97], v[200:207], v[224:231], 0
	v_mfma_f32_16x16x128_f8f6f4 v[90:93], v[208:215], v[224:231], 0
	v_mfma_f32_16x16x128_f8f6f4 v[122:125], v[192:199], v[224:231], 0
	v_mfma_f32_16x16x128_f8f6f4 v[126:129], v[2:9], v[224:231], 0
	s_setprio 0
	s_setprio 1
	v_mfma_f32_16x16x128_f8f6f4 v[118:121], v[2:9], v[232:239], 0
	v_mfma_f32_16x16x128_f8f6f4 v[114:117], v[192:199], v[232:239], 0
	v_mfma_f32_16x16x128_f8f6f4 v[82:85], v[208:215], v[232:239], 0
	v_mfma_f32_16x16x128_f8f6f4 v[86:89], v[200:207], v[232:239], 0
	v_mfma_f32_16x16x128_f8f6f4 v[78:81], v[200:207], v[240:247], 0
	v_mfma_f32_16x16x128_f8f6f4 v[74:77], v[208:215], v[240:247], 0
	v_mfma_f32_16x16x128_f8f6f4 v[106:109], v[192:199], v[240:247], 0
	v_mfma_f32_16x16x128_f8f6f4 v[110:113], v[2:9], v[240:247], 0
	s_barrier
	s_setprio 0
	s_mov_b32 m0, s33
	v_lshl_add_u64 v[174:175], s[38:39], 0, v[156:157]
	s_add_u32 s84, s38, 0x158000
	global_load_lds_dwordx4 v[174:175], off
	v_lshl_add_u64 v[176:177], s[38:39], 0, v[160:161]
	s_mov_b32 m0, s35
	s_addc_u32 s85, s39, 0
	global_load_lds_dwordx4 v[176:177], off
	v_lshl_add_u64 v[182:183], s[84:85], 0, v[156:157]
	s_mov_b32 m0, s42
	v_lshl_add_u64 v[184:185], s[40:41], 0, v[158:159]
	global_load_lds_dwordx4 v[182:183], off
	v_lshl_add_u64 v[182:183], s[84:85], 0, v[160:161]
	s_mov_b32 m0, s43
	s_nop 0
	global_load_lds_dwordx4 v[182:183], off
	v_lshl_add_u64 v[182:183], s[40:41], 0, v[154:155]
	s_mov_b32 m0, s23
	s_nop 0
	global_load_lds_dwordx4 v[182:183], off
	s_mov_b32 m0, s44
	s_nop 0
	global_load_lds_dwordx4 v[184:185], off
	ds_read_b128 v[216:219], v190 offset:16384
	ds_read_b128 v[220:223], v190 offset:17408
	ds_read_b128 v[224:227], v190 offset:18432
	ds_read_b128 v[228:231], v190 offset:19456
	ds_read_b128 v[232:235], v190 offset:20480
	ds_read_b128 v[236:239], v190 offset:21504
	ds_read_b128 v[240:243], v190 offset:22528
	ds_read_b128 v[244:247], v190 offset:23552
	s_waitcnt vmcnt(8)
	s_waitcnt lgkmcnt(0)
	s_setprio 1
	s_barrier
	v_mfma_f32_16x16x128_f8f6f4 v[70:73], v[2:9], v[216:223], 0
	v_mfma_f32_16x16x128_f8f6f4 v[66:69], v[192:199], v[216:223], 0
	v_mfma_f32_16x16x128_f8f6f4 v[34:37], v[208:215], v[216:223], 0
	v_mfma_f32_16x16x128_f8f6f4 v[38:41], v[200:207], v[216:223], 0
	v_mfma_f32_16x16x128_f8f6f4 v[30:33], v[200:207], v[224:231], 0
	v_mfma_f32_16x16x128_f8f6f4 v[26:29], v[208:215], v[224:231], 0
	v_mfma_f32_16x16x128_f8f6f4 v[58:61], v[192:199], v[224:231], 0
	v_mfma_f32_16x16x128_f8f6f4 v[62:65], v[2:9], v[224:231], 0
	s_setprio 0
	s_setprio 1
	v_mfma_f32_16x16x128_f8f6f4 v[54:57], v[2:9], v[232:239], 0
	v_mfma_f32_16x16x128_f8f6f4 v[50:53], v[192:199], v[232:239], 0
	v_mfma_f32_16x16x128_f8f6f4 v[18:21], v[208:215], v[232:239], 0
	v_mfma_f32_16x16x128_f8f6f4 v[22:25], v[200:207], v[232:239], 0
	v_mfma_f32_16x16x128_f8f6f4 v[14:17], v[200:207], v[240:247], 0
	v_mfma_f32_16x16x128_f8f6f4 v[10:13], v[208:215], v[240:247], 0
	v_mfma_f32_16x16x128_f8f6f4 v[42:45], v[192:199], v[240:247], 0
	v_mfma_f32_16x16x128_f8f6f4 v[46:49], v[2:9], v[240:247], 0
	s_barrier
	s_setprio 0
	s_add_u32 s40, s40, 0x158000
	s_addc_u32 s41, s41, 0
	s_mov_b32 m0, s45
	v_lshl_add_u64 v[186:187], s[40:41], 0, v[154:155]
	global_load_lds_dwordx4 v[186:187], off
	v_lshl_add_u64 v[186:187], s[40:41], 0, v[158:159]
	s_mov_b32 m0, s46
	s_nop 0
	global_load_lds_dwordx4 v[186:187], off
	ds_read_b128 v[2:5], v189 offset:32768
	ds_read_b128 v[6:9], v189 offset:33792
	ds_read_b128 v[192:195], v189 offset:34816
	ds_read_b128 v[196:199], v189 offset:35840
	ds_read_b128 v[200:203], v189 offset:49152
	ds_read_b128 v[204:207], v189 offset:50176
	ds_read_b128 v[208:211], v189 offset:51200
	ds_read_b128 v[212:215], v189 offset:52224
	ds_read_b128 v[216:219], v190 offset:32768
	ds_read_b128 v[220:223], v190 offset:33792
	ds_read_b128 v[224:227], v190 offset:34816
	ds_read_b128 v[228:231], v190 offset:35840
	ds_read_b128 v[232:235], v190 offset:36864
	ds_read_b128 v[236:239], v190 offset:37888
	ds_read_b128 v[240:243], v190 offset:38912
	ds_read_b128 v[244:247], v190 offset:39936
	s_waitcnt vmcnt(8)
	s_waitcnt lgkmcnt(0)
	s_setprio 1
	s_barrier
	v_mfma_f32_16x16x128_f8f6f4 v[134:137], v[2:9], v[216:223], v[134:137]
	v_mfma_f32_16x16x128_f8f6f4 v[130:133], v[192:199], v[216:223], v[130:133]
	v_mfma_f32_16x16x128_f8f6f4 v[98:101], v[208:215], v[216:223], v[98:101]
	v_mfma_f32_16x16x128_f8f6f4 v[102:105], v[200:207], v[216:223], v[102:105]
	v_mfma_f32_16x16x128_f8f6f4 v[94:97], v[200:207], v[224:231], v[94:97]
	v_mfma_f32_16x16x128_f8f6f4 v[90:93], v[208:215], v[224:231], v[90:93]
	v_mfma_f32_16x16x128_f8f6f4 v[122:125], v[192:199], v[224:231], v[122:125]
	v_mfma_f32_16x16x128_f8f6f4 v[126:129], v[2:9], v[224:231], v[126:129]
	s_setprio 0
	s_setprio 1
	v_mfma_f32_16x16x128_f8f6f4 v[118:121], v[2:9], v[232:239], v[118:121]
	v_mfma_f32_16x16x128_f8f6f4 v[114:117], v[192:199], v[232:239], v[114:117]
	v_mfma_f32_16x16x128_f8f6f4 v[82:85], v[208:215], v[232:239], v[82:85]
	v_mfma_f32_16x16x128_f8f6f4 v[86:89], v[200:207], v[232:239], v[86:89]
	v_mfma_f32_16x16x128_f8f6f4 v[78:81], v[200:207], v[240:247], v[78:81]
	v_mfma_f32_16x16x128_f8f6f4 v[74:77], v[208:215], v[240:247], v[74:77]
	v_mfma_f32_16x16x128_f8f6f4 v[106:109], v[192:199], v[240:247], v[106:109]
	v_mfma_f32_16x16x128_f8f6f4 v[110:113], v[2:9], v[240:247], v[110:113]
	s_barrier
	s_setprio 0
	s_mov_b32 m0, s52
	v_lshl_add_u64 v[174:175], v[174:175], 0, s[14:15]
	s_add_u32 s38, s38, 0x158080
	global_load_lds_dwordx4 v[174:175], off
	v_lshl_add_u64 v[174:175], v[176:177], 0, s[14:15]
	s_mov_b32 m0, s53
	s_addc_u32 s39, s39, 0
	global_load_lds_dwordx4 v[174:175], off
	v_lshl_add_u64 v[174:175], s[38:39], 0, v[156:157]
	s_mov_b32 m0, s56
	s_nop 0
	global_load_lds_dwordx4 v[174:175], off
	v_lshl_add_u64 v[174:175], s[38:39], 0, v[160:161]
	s_mov_b32 m0, s57
	s_nop 0
	global_load_lds_dwordx4 v[174:175], off
	v_lshl_add_u64 v[174:175], v[182:183], 0, s[14:15]
	s_mov_b32 m0, s54
	s_nop 0
	global_load_lds_dwordx4 v[174:175], off
	v_lshl_add_u64 v[174:175], v[184:185], 0, s[14:15]
	s_mov_b32 m0, s55
	s_nop 0
	global_load_lds_dwordx4 v[174:175], off
	ds_read_b128 v[216:219], v190 offset:49152
	ds_read_b128 v[220:223], v190 offset:50176
	ds_read_b128 v[224:227], v190 offset:51200
	ds_read_b128 v[228:231], v190 offset:52224
	ds_read_b128 v[232:235], v190 offset:53248
	ds_read_b128 v[236:239], v190 offset:54272
	ds_read_b128 v[240:243], v190 offset:55296
	ds_read_b128 v[244:247], v190 offset:56320
	s_waitcnt vmcnt(8)
	s_waitcnt lgkmcnt(0)
	s_setprio 1
	s_barrier
	v_mfma_f32_16x16x128_f8f6f4 v[70:73], v[2:9], v[216:223], v[70:73]
	v_mfma_f32_16x16x128_f8f6f4 v[66:69], v[192:199], v[216:223], v[66:69]
	v_mfma_f32_16x16x128_f8f6f4 v[34:37], v[208:215], v[216:223], v[34:37]
	v_mfma_f32_16x16x128_f8f6f4 v[38:41], v[200:207], v[216:223], v[38:41]
	v_mfma_f32_16x16x128_f8f6f4 v[30:33], v[200:207], v[224:231], v[30:33]
	v_mfma_f32_16x16x128_f8f6f4 v[26:29], v[208:215], v[224:231], v[26:29]
	v_mfma_f32_16x16x128_f8f6f4 v[58:61], v[192:199], v[224:231], v[58:61]
	v_mfma_f32_16x16x128_f8f6f4 v[62:65], v[2:9], v[224:231], v[62:65]
	s_setprio 0
	s_setprio 1
	v_mfma_f32_16x16x128_f8f6f4 v[54:57], v[2:9], v[232:239], v[54:57]
	v_mfma_f32_16x16x128_f8f6f4 v[50:53], v[192:199], v[232:239], v[50:53]
	v_mfma_f32_16x16x128_f8f6f4 v[18:21], v[208:215], v[232:239], v[18:21]
	v_mfma_f32_16x16x128_f8f6f4 v[22:25], v[200:207], v[232:239], v[22:25]
	v_mfma_f32_16x16x128_f8f6f4 v[14:17], v[200:207], v[240:247], v[14:17]
	v_mfma_f32_16x16x128_f8f6f4 v[10:13], v[208:215], v[240:247], v[10:13]
	v_mfma_f32_16x16x128_f8f6f4 v[42:45], v[192:199], v[240:247], v[42:45]
	v_mfma_f32_16x16x128_f8f6f4 v[46:49], v[2:9], v[240:247], v[46:49]
	s_barrier
	s_setprio 0
	s_cmp_lt_u32 s82, 3
	s_cbranch_scc1 .LBB0_1036
	s_add_u32 s38, s48, s63
	s_addc_u32 s39, s49, s62
	s_add_u32 s36, s36, 0x158180
	s_addc_u32 s37, s37, 0
	s_add_u32 s40, s26, 0x200
	v_lshl_add_u64 v[174:175], v[172:173], 2, s[38:39]
	s_addc_u32 s41, s27, 0
	s_mov_b32 s84, 4
	s_cmp_eq_u32 s82, s84
	s_cselect_b64 s[26:27], -1, 0
	s_cmp_lg_u32 s82, s84
	s_cbranch_scc1 .LBB0_1034

.LBB0_1034:
	s_add_u32 s38, s36, 0xffea8080
	s_addc_u32 s39, s37, -1
	s_and_b64 s[26:27], s[26:27], exec
	s_cselect_b32 s26, s4, s40
	s_cselect_b32 s39, s1, s39
	s_cselect_b32 s38, s0, s38
	s_cselect_b32 s27, s5, s41
	s_mov_b32 m0, s25
	v_lshl_add_u64 v[176:177], s[36:37], 0, v[162:163]
	global_load_lds_dwordx4 v[176:177], off
	v_lshl_add_u64 v[176:177], s[36:37], 0, v[164:165]
	s_mov_b32 m0, s83
	s_nop 0
	global_load_lds_dwordx4 v[176:177], off
	ds_read_b128 v[2:5], v189
	ds_read_b128 v[6:9], v189 offset:1024
	ds_read_b128 v[192:195], v189 offset:2048
	ds_read_b128 v[196:199], v189 offset:3072
	ds_read_b128 v[200:203], v189 offset:16384
	ds_read_b128 v[204:207], v189 offset:17408
	ds_read_b128 v[208:211], v189 offset:18432
	ds_read_b128 v[212:215], v189 offset:19456
	ds_read_b128 v[216:219], v190
	ds_read_b128 v[220:223], v190 offset:1024
	ds_read_b128 v[224:227], v190 offset:2048
	ds_read_b128 v[228:231], v190 offset:3072
	ds_read_b128 v[232:235], v190 offset:4096
	ds_read_b128 v[236:239], v190 offset:5120
	ds_read_b128 v[240:243], v190 offset:6144
	ds_read_b128 v[244:247], v190 offset:7168
	s_waitcnt vmcnt(8)
	s_waitcnt lgkmcnt(0)
	s_setprio 1
	s_barrier
	v_mfma_f32_16x16x128_f8f6f4 v[134:137], v[2:9], v[216:223], v[134:137]
	v_mfma_f32_16x16x128_f8f6f4 v[130:133], v[192:199], v[216:223], v[130:133]
	v_mfma_f32_16x16x128_f8f6f4 v[98:101], v[208:215], v[216:223], v[98:101]
	v_mfma_f32_16x16x128_f8f6f4 v[102:105], v[200:207], v[216:223], v[102:105]
	v_mfma_f32_16x16x128_f8f6f4 v[94:97], v[200:207], v[224:231], v[94:97]
	v_mfma_f32_16x16x128_f8f6f4 v[90:93], v[208:215], v[224:231], v[90:93]
	v_mfma_f32_16x16x128_f8f6f4 v[122:125], v[192:199], v[224:231], v[122:125]
	v_mfma_f32_16x16x128_f8f6f4 v[126:129], v[2:9], v[224:231], v[126:129]
	s_setprio 0
	s_setprio 1
	v_mfma_f32_16x16x128_f8f6f4 v[118:121], v[2:9], v[232:239], v[118:121]
	v_mfma_f32_16x16x128_f8f6f4 v[114:117], v[192:199], v[232:239], v[114:117]
	v_mfma_f32_16x16x128_f8f6f4 v[82:85], v[208:215], v[232:239], v[82:85]
	v_mfma_f32_16x16x128_f8f6f4 v[86:89], v[200:207], v[232:239], v[86:89]
	v_mfma_f32_16x16x128_f8f6f4 v[78:81], v[200:207], v[240:247], v[78:81]
	v_mfma_f32_16x16x128_f8f6f4 v[74:77], v[208:215], v[240:247], v[74:77]
	v_mfma_f32_16x16x128_f8f6f4 v[106:109], v[192:199], v[240:247], v[106:109]
	v_mfma_f32_16x16x128_f8f6f4 v[110:113], v[2:9], v[240:247], v[110:113]
	s_barrier
	s_setprio 0
	s_mov_b32 m0, s33
	v_lshl_add_u64 v[176:177], s[26:27], 0, v[156:157]
	s_add_u32 s62, s26, 0x158000
	global_load_lds_dwordx4 v[176:177], off
	v_lshl_add_u64 v[182:183], s[26:27], 0, v[160:161]
	s_mov_b32 m0, s35
	s_addc_u32 s63, s27, 0
	global_load_lds_dwordx4 v[182:183], off
	v_lshl_add_u64 v[184:185], s[62:63], 0, v[156:157]
	s_mov_b32 m0, s42
	v_lshl_add_u64 v[186:187], s[38:39], 0, v[158:159]
	global_load_lds_dwordx4 v[184:185], off
	v_lshl_add_u64 v[184:185], s[62:63], 0, v[160:161]
	s_mov_b32 m0, s43
	s_nop 0
	global_load_lds_dwordx4 v[184:185], off
	v_lshl_add_u64 v[184:185], s[38:39], 0, v[154:155]
	s_mov_b32 m0, s23
	s_nop 0
	global_load_lds_dwordx4 v[184:185], off
	s_mov_b32 m0, s44
	s_nop 0
	global_load_lds_dwordx4 v[186:187], off
	ds_read_b128 v[216:219], v190 offset:16384
	ds_read_b128 v[220:223], v190 offset:17408
	ds_read_b128 v[224:227], v190 offset:18432
	ds_read_b128 v[228:231], v190 offset:19456
	ds_read_b128 v[232:235], v190 offset:20480
	ds_read_b128 v[236:239], v190 offset:21504
	ds_read_b128 v[240:243], v190 offset:22528
	ds_read_b128 v[244:247], v190 offset:23552
	s_waitcnt vmcnt(8)
	s_waitcnt lgkmcnt(0)
	s_setprio 1
	s_barrier
	v_mfma_f32_16x16x128_f8f6f4 v[70:73], v[2:9], v[216:223], v[70:73]
	v_mfma_f32_16x16x128_f8f6f4 v[66:69], v[192:199], v[216:223], v[66:69]
	v_mfma_f32_16x16x128_f8f6f4 v[34:37], v[208:215], v[216:223], v[34:37]
	v_mfma_f32_16x16x128_f8f6f4 v[38:41], v[200:207], v[216:223], v[38:41]
	v_mfma_f32_16x16x128_f8f6f4 v[30:33], v[200:207], v[224:231], v[30:33]
	v_mfma_f32_16x16x128_f8f6f4 v[26:29], v[208:215], v[224:231], v[26:29]
	v_mfma_f32_16x16x128_f8f6f4 v[58:61], v[192:199], v[224:231], v[58:61]
	v_mfma_f32_16x16x128_f8f6f4 v[62:65], v[2:9], v[224:231], v[62:65]
	s_setprio 0
	s_setprio 1
	v_mfma_f32_16x16x128_f8f6f4 v[54:57], v[2:9], v[232:239], v[54:57]
	v_mfma_f32_16x16x128_f8f6f4 v[50:53], v[192:199], v[232:239], v[50:53]
	v_mfma_f32_16x16x128_f8f6f4 v[18:21], v[208:215], v[232:239], v[18:21]
	v_mfma_f32_16x16x128_f8f6f4 v[22:25], v[200:207], v[232:239], v[22:25]
	v_mfma_f32_16x16x128_f8f6f4 v[14:17], v[200:207], v[240:247], v[14:17]
	v_mfma_f32_16x16x128_f8f6f4 v[10:13], v[208:215], v[240:247], v[10:13]
	v_mfma_f32_16x16x128_f8f6f4 v[42:45], v[192:199], v[240:247], v[42:45]
	v_mfma_f32_16x16x128_f8f6f4 v[46:49], v[2:9], v[240:247], v[46:49]
	s_barrier
	s_setprio 0
	s_add_u32 s38, s38, 0x158000
	s_addc_u32 s39, s39, 0
	s_mov_b32 m0, s45
	v_lshl_add_u64 v[248:249], s[38:39], 0, v[154:155]
	global_load_lds_dwordx4 v[248:249], off
	v_lshl_add_u64 v[248:249], s[38:39], 0, v[158:159]
	s_mov_b32 m0, s46
	s_nop 0
	global_load_lds_dwordx4 v[248:249], off
	ds_read_b128 v[192:195], v189 offset:32768
	ds_read_b128 v[196:199], v189 offset:33792
	ds_read_b128 v[200:203], v189 offset:34816
	ds_read_b128 v[204:207], v189 offset:35840
	ds_read_b128 v[2:5], v189 offset:49152
	ds_read_b128 v[6:9], v189 offset:50176
	ds_read_b128 v[208:211], v189 offset:51200
	ds_read_b128 v[212:215], v189 offset:52224
	ds_read_b128 v[216:219], v190 offset:32768
	ds_read_b128 v[220:223], v190 offset:33792
	ds_read_b128 v[224:227], v190 offset:34816
	ds_read_b128 v[228:231], v190 offset:35840
	ds_read_b128 v[232:235], v190 offset:36864
	ds_read_b128 v[236:239], v190 offset:37888
	ds_read_b128 v[240:243], v190 offset:38912
	ds_read_b128 v[244:247], v190 offset:39936
	s_waitcnt vmcnt(8)
	s_waitcnt lgkmcnt(0)
	s_setprio 1
	s_barrier
	v_mfma_f32_16x16x128_f8f6f4 v[134:137], v[192:199], v[216:223], v[134:137]
	v_mfma_f32_16x16x128_f8f6f4 v[130:133], v[200:207], v[216:223], v[130:133]
	v_mfma_f32_16x16x128_f8f6f4 v[98:101], v[208:215], v[216:223], v[98:101]
	v_mfma_f32_16x16x128_f8f6f4 v[102:105], v[2:9], v[216:223], v[102:105]
	v_mfma_f32_16x16x128_f8f6f4 v[94:97], v[2:9], v[224:231], v[94:97]
	v_mfma_f32_16x16x128_f8f6f4 v[90:93], v[208:215], v[224:231], v[90:93]
	v_mfma_f32_16x16x128_f8f6f4 v[122:125], v[200:207], v[224:231], v[122:125]
	v_mfma_f32_16x16x128_f8f6f4 v[126:129], v[192:199], v[224:231], v[126:129]
	s_setprio 0
	s_setprio 1
	v_mfma_f32_16x16x128_f8f6f4 v[118:121], v[192:199], v[232:239], v[118:121]
	v_mfma_f32_16x16x128_f8f6f4 v[114:117], v[200:207], v[232:239], v[114:117]
	v_mfma_f32_16x16x128_f8f6f4 v[82:85], v[208:215], v[232:239], v[82:85]
	v_mfma_f32_16x16x128_f8f6f4 v[86:89], v[2:9], v[232:239], v[86:89]
	v_mfma_f32_16x16x128_f8f6f4 v[78:81], v[2:9], v[240:247], v[78:81]
	v_mfma_f32_16x16x128_f8f6f4 v[74:77], v[208:215], v[240:247], v[74:77]
	v_mfma_f32_16x16x128_f8f6f4 v[106:109], v[200:207], v[240:247], v[106:109]
	v_mfma_f32_16x16x128_f8f6f4 v[110:113], v[192:199], v[240:247], v[110:113]
	s_barrier
	s_setprio 0
	s_mov_b32 m0, s52
	v_lshl_add_u64 v[176:177], v[176:177], 0, s[14:15]
	s_add_u32 s26, s26, 0x158080
	global_load_lds_dwordx4 v[176:177], off
	v_lshl_add_u64 v[176:177], v[182:183], 0, s[14:15]
	s_mov_b32 m0, s53
	s_addc_u32 s27, s27, 0
	global_load_lds_dwordx4 v[176:177], off
	v_lshl_add_u64 v[176:177], s[26:27], 0, v[156:157]
	s_mov_b32 m0, s56
	s_nop 0
	global_load_lds_dwordx4 v[176:177], off
	v_lshl_add_u64 v[176:177], s[26:27], 0, v[160:161]
	s_mov_b32 m0, s57
	s_nop 0
	global_load_lds_dwordx4 v[176:177], off
	v_lshl_add_u64 v[176:177], v[184:185], 0, s[14:15]
	s_mov_b32 m0, s54
	s_nop 0
	global_load_lds_dwordx4 v[176:177], off
	v_lshl_add_u64 v[176:177], v[186:187], 0, s[14:15]
	s_mov_b32 m0, s55
	s_nop 0
	global_load_lds_dwordx4 v[176:177], off
	ds_read_b128 v[216:219], v190 offset:49152
	ds_read_b128 v[220:223], v190 offset:50176
	ds_read_b128 v[224:227], v190 offset:51200
	ds_read_b128 v[228:231], v190 offset:52224
	ds_read_b128 v[232:235], v190 offset:53248
	ds_read_b128 v[236:239], v190 offset:54272
	ds_read_b128 v[240:243], v190 offset:55296
	ds_read_b128 v[244:247], v190 offset:56320
	s_waitcnt vmcnt(8)
	s_waitcnt lgkmcnt(0)
	s_setprio 1
	s_barrier
	v_mfma_f32_16x16x128_f8f6f4 v[70:73], v[192:199], v[216:223], v[70:73]
	v_mfma_f32_16x16x128_f8f6f4 v[66:69], v[200:207], v[216:223], v[66:69]
	v_mfma_f32_16x16x128_f8f6f4 v[34:37], v[208:215], v[216:223], v[34:37]
	v_mfma_f32_16x16x128_f8f6f4 v[38:41], v[2:9], v[216:223], v[38:41]
	v_mfma_f32_16x16x128_f8f6f4 v[30:33], v[2:9], v[224:231], v[30:33]
	v_mfma_f32_16x16x128_f8f6f4 v[26:29], v[208:215], v[224:231], v[26:29]
	v_mfma_f32_16x16x128_f8f6f4 v[58:61], v[200:207], v[224:231], v[58:61]
	v_mfma_f32_16x16x128_f8f6f4 v[62:65], v[192:199], v[224:231], v[62:65]
	s_setprio 0
	s_setprio 1
	v_mfma_f32_16x16x128_f8f6f4 v[54:57], v[192:199], v[232:239], v[54:57]
	v_mfma_f32_16x16x128_f8f6f4 v[50:53], v[200:207], v[232:239], v[50:53]
	v_mfma_f32_16x16x128_f8f6f4 v[18:21], v[208:215], v[232:239], v[18:21]
	v_mfma_f32_16x16x128_f8f6f4 v[22:25], v[2:9], v[232:239], v[22:25]
	v_mfma_f32_16x16x128_f8f6f4 v[14:17], v[2:9], v[240:247], v[14:17]
	v_mfma_f32_16x16x128_f8f6f4 v[10:13], v[208:215], v[240:247], v[10:13]
	v_mfma_f32_16x16x128_f8f6f4 v[42:45], v[200:207], v[240:247], v[42:45]
	v_mfma_f32_16x16x128_f8f6f4 v[46:49], v[192:199], v[240:247], v[46:49]
	s_barrier
	s_setprio 0
	s_add_i32 s26, s84, 2
	s_add_u32 s36, s36, 0x100
	s_addc_u32 s37, s37, 0
	s_add_u32 s40, s40, 0x100
	s_addc_u32 s41, s41, 0
	s_cmp_ge_i32 s84, s82
	s_cbranch_scc1 .LBB0_1036
	s_mov_b32 s84, s26
	s_cmp_eq_u32 s82, s84
	s_cselect_b64 s[26:27], -1, 0
	s_cmp_lg_u32 s82, s84
	s_cbranch_scc0 .LBB0_1033
	s_branch .LBB0_1034
